# on top of v18: the address-setup prefix of each load interval hoisted into the preceding compute interval MFMA run (24 sites, 114 instr)
# baseline (speedup 1.0000x reference)
; #define PG8_STAGE(bufoff, gbase) do { _Pragma("unroll") for (int _i = 0; _i < 2; ++_i) \
;         __builtin_amdgcn_global_load_lds((const unsigned*)((const char*)(gbase) + voff[_i]), (LAS unsigned*)(lds + (bufoff) + ldsw + _i * 8192), 16, 0, 0); } while (0)
; #define PG8_LDA(dst, b, h) do { _Pragma("unroll") for (int m = 0; m < 4; ++m) _Pragma("unroll") for (int k = 0; k < 2; ++k) dst[m][k] = *(const LAS bf16x8*)(lds + PG8_SA(b, h) + aoff + m * 2048 + k * 1024); } while (0)
; #define PG8_LDB(dst, b, h) do { _Pragma("unroll") for (int n = 0; n < 2; ++n) _Pragma("unroll") for (int k = 0; k < 2; ++k) dst[n][k] = *(const LAS bf16x8*)(lds + PG8_SB(b, h) + boff + n * 2048 + k * 1024); } while (0)
; #define PG8_MMA(ai, bj, At, Bt) do { __builtin_amdgcn_s_setprio(1); _Pragma("unroll") for (int m = 0; m < 4; ++m) _Pragma("unroll") for (int n = 0; n < 2; ++n) _Pragma("unroll") for (int k = 0; k < 2; ++k) \
;         acc[ai][bj][m][n] = __builtin_amdgcn_mfma_f32_16x16x32_bf16(Bt[n][k], At[m][k], acc[ai][bj][m][n], 0, 0, 0); __builtin_amdgcn_s_setprio(0); } while (0)
; #define PG8_WAIT_V(n) asm volatile("s_waitcnt vmcnt(" #n ")" ::: "memory")
; #define PG8_WAIT_L(n) asm volatile("s_waitcnt lgkmcnt(" #n ")" ::: "memory")
; #define PG8_BAR __builtin_amdgcn_s_barrier()
; #define PG8_SCHED __builtin_amdgcn_sched_barrier(0)
; template <class Epi>
; DI void gemm_phase(LAS unsigned char* lds, const Gemm g, const StaticOrder& S, const Epi& E) {
;     ...
;         for (int t = 0; t < nt; t += 2) {
;             const bool last = (t == nt - 2);
;             const char* a1 = cA + (size_t)(t + 1) * kstep;
;             const char* a2 = last ? nA : cA + (size_t)(t + 2) * kstep; const char* b2 = last ? nB : cB + (size_t)(t + 2) * kstep;
;             const char* a3 = a2 + kstep; const char* b3 = b2 + kstep;
;             PG8_LDB(B0, 0, 0); PG8_SCHED; PG8_LDA(At, 0, 0); PG8_STAGE(PG8_SA(1, 1), a1 + hstep);
;             PG8_WAIT_L(8); PG8_BAR; PG8_WAIT_L(0); PG8_MMA(0, 0, At, B0); PG8_BAR; PG8_SCHED;
;             PG8_LDB(B1, 0, 1); PG8_STAGE(PG8_SB(0, 0), b2);
;             PG8_BAR; PG8_WAIT_L(0); PG8_MMA(0, 1, At, B1); PG8_BAR;
;             PG8_LDA(At, 0, 1); PG8_STAGE(PG8_SA(0, 0), a2);
;             PG8_BAR; PG8_WAIT_L(0); PG8_MMA(1, 0, At, B0); PG8_BAR; PG8_SCHED;
;             PG8_STAGE(PG8_SB(0, 1), b2 + hstep);
;             PG8_WAIT_V(6); PG8_BAR; PG8_MMA(1, 1, At, B1); PG8_BAR;
.LBB0_37:
	s_add_u32 s20, s18, 0xfff80080
	s_addc_u32 s21, s19, -1
	s_add_i32 s39, 0, 0x10000
	v_add_u32_e32 v150, s39, v135
	ds_read_b128 v[138:141], v150
	ds_read_b128 v[142:145], v150 offset:1024
	ds_read_b128 v[146:149], v150 offset:2048
	ds_read_b128 v[150:153], v150 offset:3072
	s_cmp_eq_u32 s38, 28
	s_cselect_b32 s23, s4, s21
	s_cselect_b32 s22, s5, s20
	s_cselect_b32 s21, s9, s37
	s_cselect_b32 s20, s11, s33
	v_lshl_add_u64 v[154:155], s[18:19], 0, v[130:131]
	s_add_i32 m0, s28, 0xc000
	ds_read_b128 v[186:189], v137
	ds_read_b128 v[190:193], v137 offset:1024
	ds_read_b128 v[194:197], v137 offset:2048
	ds_read_b128 v[198:201], v137 offset:3072
	ds_read_b128 v[202:205], v137 offset:4096
	ds_read_b128 v[206:209], v137 offset:5120
	ds_read_b128 v[210:213], v137 offset:6144
	ds_read_b128 v[214:217], v137 offset:7168
	global_load_lds_dwordx4 v[154:155], off
	v_lshl_add_u64 v[154:155], s[18:19], 0, v[132:133]
	s_add_i32 m0, s28, 0xe000
	s_nop 0
	global_load_lds_dwordx4 v[154:155], off
	s_waitcnt lgkmcnt(8)
	s_setprio 1
	s_barrier
	s_waitcnt lgkmcnt(0)
	v_mfma_f32_16x16x32_bf16 v[124:127], v[138:141], v[186:189], v[124:127]
	v_mfma_f32_16x16x32_bf16 v[120:123], v[146:149], v[186:189], v[120:123]
	v_mfma_f32_16x16x32_bf16 v[108:111], v[138:141], v[194:197], v[108:111]
	v_mfma_f32_16x16x32_bf16 v[104:107], v[146:149], v[194:197], v[104:107]
	v_mfma_f32_16x16x32_bf16 v[92:95], v[138:141], v[202:205], v[92:95]
	v_mfma_f32_16x16x32_bf16 v[88:91], v[146:149], v[202:205], v[88:91]
	v_mfma_f32_16x16x32_bf16 v[76:79], v[138:141], v[210:213], v[76:79]
	v_mfma_f32_16x16x32_bf16 v[72:75], v[146:149], v[210:213], v[72:75]
	v_mfma_f32_16x16x32_bf16 v[124:127], v[142:145], v[190:193], v[124:127]
	v_mfma_f32_16x16x32_bf16 v[120:123], v[150:153], v[190:193], v[120:123]
	v_mfma_f32_16x16x32_bf16 v[108:111], v[142:145], v[198:201], v[108:111]
	v_mfma_f32_16x16x32_bf16 v[104:107], v[150:153], v[198:201], v[104:107]
	s_add_i32 s42, 0, 0x14000
	v_add_u32_e32 v154, s42, v135
	s_add_i32 s39, s39, s27
	v_mfma_f32_16x16x32_bf16 v[92:95], v[142:145], v[206:209], v[92:95]
	v_mfma_f32_16x16x32_bf16 v[88:91], v[150:153], v[206:209], v[88:91]
	v_mfma_f32_16x16x32_bf16 v[76:79], v[142:145], v[214:217], v[76:79]
	v_mfma_f32_16x16x32_bf16 v[72:75], v[150:153], v[214:217], v[72:75]
	s_setprio 0
	s_barrier
	ds_read_b128 v[226:229], v154
	ds_read_b128 v[230:233], v154 offset:1024
	ds_read_b128 v[234:237], v154 offset:2048
	ds_read_b128 v[238:241], v154 offset:3072
	v_lshl_add_u64 v[154:155], s[20:21], 0, v[158:159]
	s_mov_b32 m0, s39
	v_lshl_add_u64 v[218:219], s[20:21], 0, v[128:129]
	global_load_lds_dwordx4 v[154:155], off
	s_add_i32 m0, s39, 0x2000
	s_nop 0
	global_load_lds_dwordx4 v[218:219], off
	s_waitcnt lgkmcnt(0)
	s_setprio 1
	s_barrier
	v_mfma_f32_16x16x32_bf16 v[116:119], v[226:229], v[186:189], v[116:119]
	v_mfma_f32_16x16x32_bf16 v[112:115], v[234:237], v[186:189], v[112:115]
	v_mfma_f32_16x16x32_bf16 v[100:103], v[226:229], v[194:197], v[100:103]
	v_mfma_f32_16x16x32_bf16 v[96:99], v[234:237], v[194:197], v[96:99]
	v_mfma_f32_16x16x32_bf16 v[84:87], v[226:229], v[202:205], v[84:87]
	v_mfma_f32_16x16x32_bf16 v[80:83], v[234:237], v[202:205], v[80:83]
	v_mfma_f32_16x16x32_bf16 v[68:71], v[226:229], v[210:213], v[68:71]
	v_mfma_f32_16x16x32_bf16 v[64:67], v[234:237], v[210:213], v[64:67]
	v_mfma_f32_16x16x32_bf16 v[116:119], v[230:233], v[190:193], v[116:119]
	v_mfma_f32_16x16x32_bf16 v[112:115], v[238:241], v[190:193], v[112:115]
	v_mfma_f32_16x16x32_bf16 v[100:103], v[230:233], v[198:201], v[100:103]
	v_mfma_f32_16x16x32_bf16 v[96:99], v[238:241], v[198:201], v[96:99]
	s_mov_b32 m0, s28
	v_lshl_add_u64 v[220:221], s[22:23], 0, v[158:159]
	v_mfma_f32_16x16x32_bf16 v[84:87], v[230:233], v[206:209], v[84:87]
	v_mfma_f32_16x16x32_bf16 v[80:83], v[238:241], v[206:209], v[80:83]
	v_mfma_f32_16x16x32_bf16 v[68:71], v[230:233], v[214:217], v[68:71]
	v_mfma_f32_16x16x32_bf16 v[64:67], v[238:241], v[214:217], v[64:67]
	s_setprio 0
	s_barrier
	ds_read_b128 v[186:189], v137 offset:16384
	ds_read_b128 v[190:193], v137 offset:17408
	ds_read_b128 v[194:197], v137 offset:18432
	ds_read_b128 v[198:201], v137 offset:19456
	ds_read_b128 v[202:205], v137 offset:20480
	ds_read_b128 v[206:209], v137 offset:21504
	ds_read_b128 v[210:213], v137 offset:22528
	ds_read_b128 v[214:217], v137 offset:23552
	global_load_lds_dwordx4 v[220:221], off
	v_lshl_add_u64 v[242:243], s[22:23], 0, v[128:129]
	s_mov_b32 m0, s29
	s_nop 0
	global_load_lds_dwordx4 v[242:243], off
	s_waitcnt lgkmcnt(0)
	s_setprio 1
	s_barrier
	v_mfma_f32_16x16x32_bf16 v[60:63], v[138:141], v[186:189], v[60:63]
	v_mfma_f32_16x16x32_bf16 v[56:59], v[146:149], v[186:189], v[56:59]
	v_mfma_f32_16x16x32_bf16 v[44:47], v[138:141], v[194:197], v[44:47]
	v_mfma_f32_16x16x32_bf16 v[40:43], v[146:149], v[194:197], v[40:43]
	v_mfma_f32_16x16x32_bf16 v[28:31], v[138:141], v[202:205], v[28:31]
	v_mfma_f32_16x16x32_bf16 v[24:27], v[146:149], v[202:205], v[24:27]
	v_mfma_f32_16x16x32_bf16 v[12:15], v[138:141], v[210:213], v[12:15]
	v_mfma_f32_16x16x32_bf16 v[8:11], v[146:149], v[210:213], v[8:11]
	v_mfma_f32_16x16x32_bf16 v[60:63], v[142:145], v[190:193], v[60:63]
	v_mfma_f32_16x16x32_bf16 v[56:59], v[150:153], v[190:193], v[56:59]
	v_mfma_f32_16x16x32_bf16 v[44:47], v[142:145], v[198:201], v[44:47]
	v_mfma_f32_16x16x32_bf16 v[40:43], v[150:153], v[198:201], v[40:43]
	s_add_u32 s40, s20, 0x80000
	s_addc_u32 s41, s21, 0
	s_add_i32 s39, s42, s27
	v_lshl_add_u64 v[138:139], s[40:41], 0, v[158:159]
	s_mov_b32 m0, s39
	v_mfma_f32_16x16x32_bf16 v[28:31], v[142:145], v[206:209], v[28:31]
	v_mfma_f32_16x16x32_bf16 v[24:27], v[150:153], v[206:209], v[24:27]
	v_mfma_f32_16x16x32_bf16 v[12:15], v[142:145], v[214:217], v[12:15]
	v_mfma_f32_16x16x32_bf16 v[8:11], v[150:153], v[214:217], v[8:11]
	s_setprio 0
	s_barrier
; #define PG8_STAGE(bufoff, gbase) do { _Pragma("unroll") for (int _i = 0; _i < 2; ++_i) \
;         __builtin_amdgcn_global_load_lds((const unsigned*)((const char*)(gbase) + voff[_i]), (LAS unsigned*)(lds + (bufoff) + ldsw + _i * 8192), 16, 0, 0); } while (0)
; #define PG8_LDA(dst, b, h) do { _Pragma("unroll") for (int m = 0; m < 4; ++m) _Pragma("unroll") for (int k = 0; k < 2; ++k) dst[m][k] = *(const LAS bf16x8*)(lds + PG8_SA(b, h) + aoff + m * 2048 + k * 1024); } while (0)
; #define PG8_LDB(dst, b, h) do { _Pragma("unroll") for (int n = 0; n < 2; ++n) _Pragma("unroll") for (int k = 0; k < 2; ++k) dst[n][k] = *(const LAS bf16x8*)(lds + PG8_SB(b, h) + boff + n * 2048 + k * 1024); } while (0)
; #define PG8_MMA(ai, bj, At, Bt) do { __builtin_amdgcn_s_setprio(1); _Pragma("unroll") for (int m = 0; m < 4; ++m) _Pragma("unroll") for (int n = 0; n < 2; ++n) _Pragma("unroll") for (int k = 0; k < 2; ++k) \
;         acc[ai][bj][m][n] = __builtin_amdgcn_mfma_f32_16x16x32_bf16(Bt[n][k], At[m][k], acc[ai][bj][m][n], 0, 0, 0); __builtin_amdgcn_s_setprio(0); } while (0)
; #define PG8_WAIT_V(n) asm volatile("s_waitcnt vmcnt(" #n ")" ::: "memory")
; #define PG8_WAIT_L(n) asm volatile("s_waitcnt lgkmcnt(" #n ")" ::: "memory")
; #define PG8_BAR __builtin_amdgcn_s_barrier()
; #define PG8_SCHED __builtin_amdgcn_sched_barrier(0)
; template <class Epi>
; DI void gemm_phase(LAS unsigned char* lds, const Gemm g, const StaticOrder& S, const Epi& E) {
;     ...
;             PG8_STAGE(PG8_SB(0, 1), b2 + hstep);
;             PG8_WAIT_V(6); PG8_BAR; PG8_MMA(1, 1, At, B1); PG8_BAR;
;             PG8_LDB(B0, 1, 0); PG8_SCHED; PG8_LDA(At, 1, 0); PG8_STAGE(PG8_SA(0, 1), a2 + hstep);
;             PG8_WAIT_L(8); PG8_BAR; PG8_WAIT_L(0); PG8_MMA(0, 0, At, B0); PG8_BAR; PG8_SCHED;
;             PG8_LDB(B1, 1, 1); PG8_STAGE(PG8_SB(1, 0), b3);
;             PG8_BAR; PG8_WAIT_L(0); PG8_MMA(0, 1, At, B1); PG8_BAR;
;             PG8_LDA(At, 1, 1); PG8_STAGE(PG8_SA(1, 0), a3);
;             PG8_BAR; PG8_WAIT_L(0); PG8_MMA(1, 0, At, B0); PG8_BAR; PG8_SCHED;
	s_nop 0
	global_load_lds_dwordx4 v[138:139], off
	v_lshl_add_u64 v[138:139], s[40:41], 0, v[128:129]
	s_add_i32 m0, s39, 0x2000
	s_nop 0
	global_load_lds_dwordx4 v[138:139], off
	s_waitcnt vmcnt(6)
	s_setprio 1
	s_barrier
	v_mfma_f32_16x16x32_bf16 v[52:55], v[226:229], v[186:189], v[52:55]
	v_mfma_f32_16x16x32_bf16 v[48:51], v[234:237], v[186:189], v[48:51]
	v_mfma_f32_16x16x32_bf16 v[36:39], v[226:229], v[194:197], v[36:39]
	v_mfma_f32_16x16x32_bf16 v[32:35], v[234:237], v[194:197], v[32:35]
	v_mfma_f32_16x16x32_bf16 v[20:23], v[226:229], v[202:205], v[20:23]
	v_mfma_f32_16x16x32_bf16 v[16:19], v[234:237], v[202:205], v[16:19]
	v_mfma_f32_16x16x32_bf16 v[4:7], v[226:229], v[210:213], v[4:7]
	v_mfma_f32_16x16x32_bf16 v[0:3], v[234:237], v[210:213], v[0:3]
	v_mfma_f32_16x16x32_bf16 v[52:55], v[230:233], v[190:193], v[52:55]
	v_mfma_f32_16x16x32_bf16 v[48:51], v[238:241], v[190:193], v[48:51]
	v_mfma_f32_16x16x32_bf16 v[36:39], v[230:233], v[198:201], v[36:39]
	v_mfma_f32_16x16x32_bf16 v[32:35], v[238:241], v[198:201], v[32:35]
	s_add_i32 s39, 0, 0x18000
	v_add_u32_e32 v150, s39, v135
	v_mfma_f32_16x16x32_bf16 v[20:23], v[230:233], v[206:209], v[20:23]
	v_mfma_f32_16x16x32_bf16 v[16:19], v[238:241], v[206:209], v[16:19]
	v_mfma_f32_16x16x32_bf16 v[4:7], v[230:233], v[214:217], v[4:7]
	v_mfma_f32_16x16x32_bf16 v[0:3], v[238:241], v[214:217], v[0:3]
	s_setprio 0
	s_barrier
	ds_read_b128 v[138:141], v150
	ds_read_b128 v[142:145], v150 offset:1024
	ds_read_b128 v[146:149], v150 offset:2048
	ds_read_b128 v[150:153], v150 offset:3072
	s_add_u32 s22, s22, 0x80000
	s_addc_u32 s23, s23, 0
	s_mov_b32 m0, s30
	v_lshl_add_u64 v[226:227], s[22:23], 0, v[158:159]
	ds_read_b128 v[186:189], v137 offset:32768
	ds_read_b128 v[190:193], v137 offset:33792
	ds_read_b128 v[194:197], v137 offset:34816
	ds_read_b128 v[198:201], v137 offset:35840
	ds_read_b128 v[202:205], v137 offset:36864
	ds_read_b128 v[206:209], v137 offset:37888
	ds_read_b128 v[210:213], v137 offset:38912
	ds_read_b128 v[214:217], v137 offset:39936
	global_load_lds_dwordx4 v[226:227], off
	v_lshl_add_u64 v[226:227], s[22:23], 0, v[128:129]
	s_mov_b32 m0, s31
	s_nop 0
	global_load_lds_dwordx4 v[226:227], off
	s_waitcnt lgkmcnt(8)
	s_setprio 1
	s_barrier
	s_waitcnt lgkmcnt(0)
	v_mfma_f32_16x16x32_bf16 v[124:127], v[138:141], v[186:189], v[124:127]
	v_mfma_f32_16x16x32_bf16 v[120:123], v[146:149], v[186:189], v[120:123]
	v_mfma_f32_16x16x32_bf16 v[108:111], v[138:141], v[194:197], v[108:111]
	v_mfma_f32_16x16x32_bf16 v[104:107], v[146:149], v[194:197], v[104:107]
	v_mfma_f32_16x16x32_bf16 v[92:95], v[138:141], v[202:205], v[92:95]
	v_mfma_f32_16x16x32_bf16 v[88:91], v[146:149], v[202:205], v[88:91]
	v_mfma_f32_16x16x32_bf16 v[76:79], v[138:141], v[210:213], v[76:79]
	v_mfma_f32_16x16x32_bf16 v[72:75], v[146:149], v[210:213], v[72:75]
	v_mfma_f32_16x16x32_bf16 v[124:127], v[142:145], v[190:193], v[124:127]
	v_mfma_f32_16x16x32_bf16 v[120:123], v[150:153], v[190:193], v[120:123]
	v_mfma_f32_16x16x32_bf16 v[108:111], v[142:145], v[198:201], v[108:111]
	v_mfma_f32_16x16x32_bf16 v[104:107], v[150:153], v[198:201], v[104:107]
	s_add_i32 s22, 0, 0x1c000
	s_add_i32 s23, s39, s27
	v_add_u32_e32 v225, s22, v135
	v_lshl_add_u64 v[154:155], v[154:155], 0, s[94:95]
	s_mov_b32 m0, s23
	v_mfma_f32_16x16x32_bf16 v[92:95], v[142:145], v[206:209], v[92:95]
	v_mfma_f32_16x16x32_bf16 v[88:91], v[150:153], v[206:209], v[88:91]
	v_mfma_f32_16x16x32_bf16 v[76:79], v[142:145], v[214:217], v[76:79]
	v_mfma_f32_16x16x32_bf16 v[72:75], v[150:153], v[214:217], v[72:75]
	s_setprio 0
	s_barrier
	ds_read_b128 v[226:229], v225
	ds_read_b128 v[230:233], v225 offset:1024
	ds_read_b128 v[234:237], v225 offset:2048
	ds_read_b128 v[238:241], v225 offset:3072
	global_load_lds_dwordx4 v[154:155], off
	v_lshl_add_u64 v[154:155], v[218:219], 0, s[94:95]
	s_add_i32 m0, s23, 0x2000
	s_nop 0
	global_load_lds_dwordx4 v[154:155], off
	s_waitcnt lgkmcnt(0)
	s_setprio 1
	s_barrier
	v_mfma_f32_16x16x32_bf16 v[116:119], v[226:229], v[186:189], v[116:119]
	v_mfma_f32_16x16x32_bf16 v[112:115], v[234:237], v[186:189], v[112:115]
	v_mfma_f32_16x16x32_bf16 v[100:103], v[226:229], v[194:197], v[100:103]
	v_mfma_f32_16x16x32_bf16 v[96:99], v[234:237], v[194:197], v[96:99]
	v_mfma_f32_16x16x32_bf16 v[84:87], v[226:229], v[202:205], v[84:87]
	v_mfma_f32_16x16x32_bf16 v[80:83], v[234:237], v[202:205], v[80:83]
	v_mfma_f32_16x16x32_bf16 v[68:71], v[226:229], v[210:213], v[68:71]
	v_mfma_f32_16x16x32_bf16 v[64:67], v[234:237], v[210:213], v[64:67]
	v_mfma_f32_16x16x32_bf16 v[116:119], v[230:233], v[190:193], v[116:119]
	v_mfma_f32_16x16x32_bf16 v[112:115], v[238:241], v[190:193], v[112:115]
	v_mfma_f32_16x16x32_bf16 v[100:103], v[230:233], v[198:201], v[100:103]
	v_mfma_f32_16x16x32_bf16 v[96:99], v[238:241], v[198:201], v[96:99]
	s_mov_b32 m0, s34
	v_lshl_add_u64 v[154:155], v[220:221], 0, s[94:95]
	v_mfma_f32_16x16x32_bf16 v[84:87], v[230:233], v[206:209], v[84:87]
	v_mfma_f32_16x16x32_bf16 v[80:83], v[238:241], v[206:209], v[80:83]
	v_mfma_f32_16x16x32_bf16 v[68:71], v[230:233], v[214:217], v[68:71]
	v_mfma_f32_16x16x32_bf16 v[64:67], v[238:241], v[214:217], v[64:67]
	s_setprio 0
	s_barrier
	ds_read_b128 v[186:189], v137 offset:49152
	ds_read_b128 v[190:193], v137 offset:50176
	ds_read_b128 v[194:197], v137 offset:51200
	ds_read_b128 v[198:201], v137 offset:52224
	ds_read_b128 v[202:205], v137 offset:53248
	ds_read_b128 v[206:209], v137 offset:54272
	ds_read_b128 v[210:213], v137 offset:55296
	ds_read_b128 v[214:217], v137 offset:56320
	global_load_lds_dwordx4 v[154:155], off
	v_lshl_add_u64 v[154:155], v[242:243], 0, s[94:95]
	s_mov_b32 m0, s35
	s_nop 0
	global_load_lds_dwordx4 v[154:155], off
	s_waitcnt lgkmcnt(0)
	s_setprio 1
	s_barrier
; #define PG8_STAGE(bufoff, gbase) do { _Pragma("unroll") for (int _i = 0; _i < 2; ++_i) \
;         __builtin_amdgcn_global_load_lds((const unsigned*)((const char*)(gbase) + voff[_i]), (LAS unsigned*)(lds + (bufoff) + ldsw + _i * 8192), 16, 0, 0); } while (0)
; #define PG8_MMA(ai, bj, At, Bt) do { __builtin_amdgcn_s_setprio(1); _Pragma("unroll") for (int m = 0; m < 4; ++m) _Pragma("unroll") for (int n = 0; n < 2; ++n) _Pragma("unroll") for (int k = 0; k < 2; ++k) \
;         acc[ai][bj][m][n] = __builtin_amdgcn_mfma_f32_16x16x32_bf16(Bt[n][k], At[m][k], acc[ai][bj][m][n], 0, 0, 0); __builtin_amdgcn_s_setprio(0); } while (0)
; #define PG8_WAIT_V(n) asm volatile("s_waitcnt vmcnt(" #n ")" ::: "memory")
; #define PG8_WAIT_L(n) asm volatile("s_waitcnt lgkmcnt(" #n ")" ::: "memory")
; #define PG8_BAR __builtin_amdgcn_s_barrier()
; #define PG8_SCHED __builtin_amdgcn_sched_barrier(0)
; template <class Epi>
; DI void gemm_phase(LAS unsigned char* lds, const Gemm g, const StaticOrder& S, const Epi& E) {
;     ...
;             PG8_BAR; PG8_WAIT_L(0); PG8_MMA(1, 0, At, B0); PG8_BAR; PG8_SCHED;
;             PG8_STAGE(PG8_SB(1, 1), b3 + hstep);
;             PG8_WAIT_V(6); PG8_BAR; PG8_MMA(1, 1, At, B1); PG8_BAR;
;     DI void operator()(const f32x4 (&acc)[2][2][4][2], const Unit& u, int wr, int wc, int fr, int fq) const {
;         const int row0 = u.pm * BM + wr * 64 + fr, col0 = u.pn * HALF + wc * 32 + 8 * fq;
; #pragma unroll
;         for (int ai = 0; ai < 2; ++ai)
; #pragma unroll
;             for (int m = 0; m < 4; ++m) { float hv[8];
; #pragma unroll
;                 for (int n = 0; n < 2; ++n)
; #pragma unroll
;                     for (int e = 0; e < 4; ++e) { const float gt = acc[ai][0][m][n][e], up = acc[ai][1][m][n][e];
;                         hv[n * 4 + e] = gt * __builtin_amdgcn_rcpf(1.f + __builtin_amdgcn_exp2f(-1.4426950408889634f * gt)) * up; }
;                 *(u32x4*)(H + (size_t)(row0 + ai * HALF + m * 16) * DFF + col0) = (u32x4){pk(hv[0], hv[1]), pk(hv[2], hv[3]), pk(hv[4], hv[5]), pk(hv[6], hv[7])}; }
;     }
	v_mfma_f32_16x16x32_bf16 v[60:63], v[138:141], v[186:189], v[60:63]
	v_mfma_f32_16x16x32_bf16 v[56:59], v[146:149], v[186:189], v[56:59]
	v_mfma_f32_16x16x32_bf16 v[44:47], v[138:141], v[194:197], v[44:47]
	v_mfma_f32_16x16x32_bf16 v[40:43], v[146:149], v[194:197], v[40:43]
	v_mfma_f32_16x16x32_bf16 v[28:31], v[138:141], v[202:205], v[28:31]
	v_mfma_f32_16x16x32_bf16 v[24:27], v[146:149], v[202:205], v[24:27]
	v_mfma_f32_16x16x32_bf16 v[12:15], v[138:141], v[210:213], v[12:15]
	v_mfma_f32_16x16x32_bf16 v[8:11], v[146:149], v[210:213], v[8:11]
	v_mfma_f32_16x16x32_bf16 v[60:63], v[142:145], v[190:193], v[60:63]
	v_mfma_f32_16x16x32_bf16 v[56:59], v[150:153], v[190:193], v[56:59]
	v_mfma_f32_16x16x32_bf16 v[44:47], v[142:145], v[198:201], v[44:47]
	v_mfma_f32_16x16x32_bf16 v[40:43], v[150:153], v[198:201], v[40:43]
	s_add_u32 s20, s20, 0x80080
	s_addc_u32 s21, s21, 0
	s_add_i32 s22, s22, s27
	v_lshl_add_u64 v[138:139], s[20:21], 0, v[158:159]
	s_mov_b32 m0, s22
	v_mfma_f32_16x16x32_bf16 v[28:31], v[142:145], v[206:209], v[28:31]
	v_mfma_f32_16x16x32_bf16 v[24:27], v[150:153], v[206:209], v[24:27]
	v_mfma_f32_16x16x32_bf16 v[12:15], v[142:145], v[214:217], v[12:15]
	v_mfma_f32_16x16x32_bf16 v[8:11], v[150:153], v[214:217], v[8:11]
	s_setprio 0
	s_barrier
	s_nop 0
	global_load_lds_dwordx4 v[138:139], off
	v_lshl_add_u64 v[138:139], s[20:21], 0, v[128:129]
	s_add_i32 m0, s22, 0x2000
	s_nop 0
	global_load_lds_dwordx4 v[138:139], off
	s_waitcnt vmcnt(6)
	s_setprio 1
	s_barrier
	v_mfma_f32_16x16x32_bf16 v[52:55], v[226:229], v[186:189], v[52:55]
	v_mfma_f32_16x16x32_bf16 v[48:51], v[234:237], v[186:189], v[48:51]
	v_mfma_f32_16x16x32_bf16 v[36:39], v[226:229], v[194:197], v[36:39]
	v_mfma_f32_16x16x32_bf16 v[32:35], v[234:237], v[194:197], v[32:35]
	v_mfma_f32_16x16x32_bf16 v[20:23], v[226:229], v[202:205], v[20:23]
	v_mfma_f32_16x16x32_bf16 v[16:19], v[234:237], v[202:205], v[16:19]
	v_mfma_f32_16x16x32_bf16 v[4:7], v[226:229], v[210:213], v[4:7]
	v_mfma_f32_16x16x32_bf16 v[0:3], v[234:237], v[210:213], v[0:3]
	v_mfma_f32_16x16x32_bf16 v[52:55], v[230:233], v[190:193], v[52:55]
	v_mfma_f32_16x16x32_bf16 v[48:51], v[238:241], v[190:193], v[48:51]
	v_mfma_f32_16x16x32_bf16 v[36:39], v[230:233], v[198:201], v[36:39]
	v_mfma_f32_16x16x32_bf16 v[32:35], v[238:241], v[198:201], v[32:35]
	s_add_i32 s38, s38, 2
	s_add_u32 s18, s18, 0x100
	s_addc_u32 s19, s19, 0
	s_add_u32 s33, s33, 0x100
	s_addc_u32 s37, s37, 0
	s_cmp_gt_u32 s38, 29
	v_mfma_f32_16x16x32_bf16 v[20:23], v[230:233], v[206:209], v[20:23]
	v_mfma_f32_16x16x32_bf16 v[16:19], v[238:241], v[206:209], v[16:19]
	v_mfma_f32_16x16x32_bf16 v[4:7], v[230:233], v[214:217], v[4:7]
	v_mfma_f32_16x16x32_bf16 v[0:3], v[238:241], v[214:217], v[0:3]
	s_setprio 0
	s_barrier
	s_cbranch_scc0 .LBB0_37
	v_mul_f32_e32 v139, 0xbfb8aa3b, v124
	v_exp_f32_e32 v139, v139
	v_lshl_or_b32 v140, s2, 7, v136
	v_lshl_add_u32 v138, s3, 8, v134
	v_ashrrev_i32_e32 v141, 31, v140
	v_add_f32_e32 v139, 1.0, v139
	v_rcp_f32_e32 v142, v139
	v_mul_f32_e32 v139, 0xbfb8aa3b, v125
	v_exp_f32_e32 v139, v139
	s_movk_i32 s4, 0x2c00
	s_and_b64 vcc, exec, s[6:7]
	s_mov_b64 s[20:21], s[16:17]
	v_add_f32_e32 v139, 1.0, v139
	v_rcp_f32_e32 v143, v139
	v_mul_f32_e32 v139, 0xbfb8aa3b, v126
	v_exp_f32_e32 v139, v139
	s_mov_b64 s[18:19], s[14:15]
	v_pk_mul_f32 v[124:125], v[124:125], v[142:143]
	v_add_f32_e32 v139, 1.0, v139
	v_rcp_f32_e32 v144, v139
	v_mul_f32_e32 v139, 0xbfb8aa3b, v127
	v_exp_f32_e32 v139, v139
	v_pk_mul_f32 v[116:117], v[124:125], v[116:117]
	v_add_f32_e32 v139, 1.0, v139
	v_rcp_f32_e32 v145, v139
	v_mul_f32_e32 v139, 0xbfb8aa3b, v120
	v_exp_f32_e32 v139, v139
	v_cvt_pk_bf16_f32 v116, v116, v117
	v_pk_mul_f32 v[124:125], v[126:127], v[144:145]
	v_add_f32_e32 v139, 1.0, v139
	v_rcp_f32_e32 v146, v139
	v_mul_f32_e32 v139, 0xbfb8aa3b, v121
	v_exp_f32_e32 v139, v139
	v_pk_mul_f32 v[118:119], v[124:125], v[118:119]
	v_add_f32_e32 v139, 1.0, v139
	v_rcp_f32_e32 v147, v139
	v_mul_f32_e32 v139, 0xbfb8aa3b, v122
	v_exp_f32_e32 v139, v139
	v_cvt_pk_bf16_f32 v117, v118, v119
	v_pk_mul_f32 v[118:119], v[120:121], v[146:147]
	v_add_f32_e32 v139, 1.0, v139
	v_rcp_f32_e32 v148, v139
	v_mul_f32_e32 v139, 0xbfb8aa3b, v123
	v_exp_f32_e32 v139, v139
	v_pk_mul_f32 v[112:113], v[118:119], v[112:113]
	v_add_f32_e32 v139, 1.0, v139
	v_rcp_f32_e32 v149, v139
	v_cvt_pk_bf16_f32 v118, v112, v113
	v_pk_mul_f32 v[112:113], v[122:123], v[148:149]
	s_nop 0
	v_pk_mul_f32 v[112:113], v[112:113], v[114:115]
	v_lshlrev_b64 v[114:115], 1, v[140:141]
	v_cvt_pk_bf16_f32 v119, v112, v113
	v_mov_b64_e32 v[112:113], s[54:55]
	v_mad_i64_i32 v[120:121], s[2:3], v138, s4, v[112:113]
	v_lshl_add_u64 v[120:121], v[120:121], 0, v[114:115]
	global_store_dwordx4 v[120:121], v[116:119], off
	v_mul_f32_e32 v120, 0xbfb8aa3b, v104
	v_mul_f32_e32 v121, 0xbfb8aa3b, v105
	v_mul_f32_e32 v116, 0xbfb8aa3b, v108
	v_mul_f32_e32 v117, 0xbfb8aa3b, v109
	v_exp_f32_e32 v116, v116
	v_exp_f32_e32 v117, v117
	v_mul_f32_e32 v118, 0xbfb8aa3b, v110
	v_mul_f32_e32 v119, 0xbfb8aa3b, v111
	v_exp_f32_e32 v118, v118
	v_exp_f32_e32 v119, v119
	v_exp_f32_e32 v120, v120
	v_exp_f32_e32 v121, v121
	v_add_f32_e32 v116, 1.0, v116
	v_add_f32_e32 v117, 1.0, v117
	v_mul_f32_e32 v122, 0xbfb8aa3b, v106
	v_mul_f32_e32 v123, 0xbfb8aa3b, v107
	v_rcp_f32_e32 v116, v116
	v_rcp_f32_e32 v117, v117
	v_add_f32_e32 v118, 1.0, v118
	v_add_f32_e32 v119, 1.0, v119
	v_exp_f32_e32 v122, v122
	v_exp_f32_e32 v123, v123
	v_rcp_f32_e32 v118, v118
	v_rcp_f32_e32 v119, v119
	v_add_f32_e32 v120, 1.0, v120
	v_add_f32_e32 v121, 1.0, v121
	v_rcp_f32_e32 v120, v120
	v_rcp_f32_e32 v121, v121
	v_add_f32_e32 v122, 1.0, v122
;     DI void operator()(const f32x4 (&acc)[2][2][4][2], const Unit& u, int wr, int wc, int fr, int fq) const {
;     ...
;             for (int m = 0; m < 4; ++m) { float hv[8];
; #pragma unroll
;                 for (int n = 0; n < 2; ++n)
; #pragma unroll
;                     for (int e = 0; e < 4; ++e) { const float gt = acc[ai][0][m][n][e], up = acc[ai][1][m][n][e];
;                         hv[n * 4 + e] = gt * __builtin_amdgcn_rcpf(1.f + __builtin_amdgcn_exp2f(-1.4426950408889634f * gt)) * up; }
;                 *(u32x4*)(H + (size_t)(row0 + ai * HALF + m * 16) * DFF + col0) = (u32x4){pk(hv[0], hv[1]), pk(hv[2], hv[3]), pk(hv[4], hv[5]), pk(hv[6], hv[7])}; }
	v_add_f32_e32 v123, 1.0, v123
	v_pk_mul_f32 v[108:109], v[108:109], v[116:117]
	v_rcp_f32_e32 v122, v122
	v_rcp_f32_e32 v123, v123
	v_pk_mul_f32 v[100:101], v[108:109], v[100:101]
	v_pk_mul_f32 v[108:109], v[110:111], v[118:119]
	v_cvt_pk_bf16_f32 v100, v100, v101
	v_pk_mul_f32 v[102:103], v[108:109], v[102:103]
	s_nop 0
	v_cvt_pk_bf16_f32 v101, v102, v103
	v_pk_mul_f32 v[102:103], v[104:105], v[120:121]
	s_nop 0
	v_pk_mul_f32 v[96:97], v[102:103], v[96:97]
	s_nop 0
	v_cvt_pk_bf16_f32 v102, v96, v97
	v_pk_mul_f32 v[96:97], v[106:107], v[122:123]
	s_nop 0
	v_pk_mul_f32 v[96:97], v[96:97], v[98:99]
	v_mul_f32_e32 v98, 0xbfb8aa3b, v94
	v_cvt_pk_bf16_f32 v103, v96, v97
	v_or_b32_e32 v96, 16, v138
	v_mad_i64_i32 v[96:97], s[2:3], v96, s4, v[112:113]
	v_lshl_add_u64 v[96:97], v[96:97], 0, v[114:115]
	global_store_dwordx4 v[96:97], v[100:103], off
	v_mul_f32_e32 v96, 0xbfb8aa3b, v92
	v_mul_f32_e32 v97, 0xbfb8aa3b, v93
	v_exp_f32_e32 v96, v96
	v_exp_f32_e32 v97, v97
	v_mul_f32_e32 v99, 0xbfb8aa3b, v95
	v_exp_f32_e32 v98, v98
	v_exp_f32_e32 v99, v99
	v_mul_f32_e32 v100, 0xbfb8aa3b, v88
	v_mul_f32_e32 v101, 0xbfb8aa3b, v89
	v_exp_f32_e32 v100, v100
	v_exp_f32_e32 v101, v101
	v_add_f32_e32 v96, 1.0, v96
	v_add_f32_e32 v97, 1.0, v97
	v_mul_f32_e32 v102, 0xbfb8aa3b, v90
	v_mul_f32_e32 v103, 0xbfb8aa3b, v91
	v_rcp_f32_e32 v96, v96
	v_rcp_f32_e32 v97, v97
	v_add_f32_e32 v98, 1.0, v98
	v_add_f32_e32 v99, 1.0, v99
	v_exp_f32_e32 v102, v102
	v_exp_f32_e32 v103, v103
	v_rcp_f32_e32 v98, v98
	v_rcp_f32_e32 v99, v99
	v_add_f32_e32 v100, 1.0, v100
	v_add_f32_e32 v101, 1.0, v101
	v_rcp_f32_e32 v100, v100
	v_rcp_f32_e32 v101, v101
	v_add_f32_e32 v102, 1.0, v102
	v_add_f32_e32 v103, 1.0, v103
	v_pk_mul_f32 v[92:93], v[92:93], v[96:97]
	v_rcp_f32_e32 v102, v102
	v_rcp_f32_e32 v103, v103
	v_pk_mul_f32 v[84:85], v[92:93], v[84:85]
	v_pk_mul_f32 v[92:93], v[94:95], v[98:99]
	v_cvt_pk_bf16_f32 v84, v84, v85
	v_pk_mul_f32 v[86:87], v[92:93], v[86:87]
	s_nop 0
	v_cvt_pk_bf16_f32 v85, v86, v87
	v_pk_mul_f32 v[86:87], v[88:89], v[100:101]
	s_nop 0
	v_pk_mul_f32 v[80:81], v[86:87], v[80:81]
	s_nop 0
	v_cvt_pk_bf16_f32 v86, v80, v81
	v_pk_mul_f32 v[80:81], v[90:91], v[102:103]
	s_nop 0
	v_pk_mul_f32 v[80:81], v[80:81], v[82:83]
	v_mul_f32_e32 v82, 0xbfb8aa3b, v78
	v_cvt_pk_bf16_f32 v87, v80, v81
	v_or_b32_e32 v80, 32, v138
	v_mad_i64_i32 v[80:81], s[2:3], v80, s4, v[112:113]
	v_lshl_add_u64 v[80:81], v[80:81], 0, v[114:115]
	global_store_dwordx4 v[80:81], v[84:87], off
	v_mul_f32_e32 v80, 0xbfb8aa3b, v76
	v_mul_f32_e32 v81, 0xbfb8aa3b, v77
	v_exp_f32_e32 v80, v80
	v_exp_f32_e32 v81, v81
	v_mul_f32_e32 v83, 0xbfb8aa3b, v79
	v_exp_f32_e32 v82, v82
	v_exp_f32_e32 v83, v83
	v_mul_f32_e32 v84, 0xbfb8aa3b, v72
	v_mul_f32_e32 v85, 0xbfb8aa3b, v73
	v_exp_f32_e32 v84, v84
	v_exp_f32_e32 v85, v85
	v_add_f32_e32 v80, 1.0, v80
	v_add_f32_e32 v81, 1.0, v81
	v_mul_f32_e32 v86, 0xbfb8aa3b, v74
	v_mul_f32_e32 v87, 0xbfb8aa3b, v75
	v_rcp_f32_e32 v80, v80
	v_rcp_f32_e32 v81, v81
	v_add_f32_e32 v82, 1.0, v82
	v_add_f32_e32 v83, 1.0, v83
	v_exp_f32_e32 v86, v86
	v_exp_f32_e32 v87, v87
	v_rcp_f32_e32 v82, v82
	v_rcp_f32_e32 v83, v83
	v_add_f32_e32 v84, 1.0, v84
	v_add_f32_e32 v85, 1.0, v85
	v_rcp_f32_e32 v84, v84
	v_rcp_f32_e32 v85, v85
	v_add_f32_e32 v86, 1.0, v86
	v_add_f32_e32 v87, 1.0, v87
	v_pk_mul_f32 v[76:77], v[76:77], v[80:81]
	v_rcp_f32_e32 v86, v86
	v_rcp_f32_e32 v87, v87
	v_pk_mul_f32 v[68:69], v[76:77], v[68:69]
	v_pk_mul_f32 v[76:77], v[78:79], v[82:83]
	v_cvt_pk_bf16_f32 v68, v68, v69
	v_pk_mul_f32 v[70:71], v[76:77], v[70:71]
	s_nop 0
	v_cvt_pk_bf16_f32 v69, v70, v71
	v_pk_mul_f32 v[70:71], v[72:73], v[84:85]
	v_add_u32_e32 v72, 0x80, v138
	v_pk_mul_f32 v[64:65], v[70:71], v[64:65]
	s_nop 0
	v_cvt_pk_bf16_f32 v70, v64, v65
	v_pk_mul_f32 v[64:65], v[74:75], v[86:87]
	s_nop 0
	v_pk_mul_f32 v[64:65], v[64:65], v[66:67]
	v_mul_f32_e32 v66, 0xbfb8aa3b, v62
	v_cvt_pk_bf16_f32 v71, v64, v65
	v_or_b32_e32 v64, 48, v138
	v_mad_i64_i32 v[64:65], s[2:3], v64, s4, v[112:113]
	v_lshl_add_u64 v[64:65], v[64:65], 0, v[114:115]
	global_store_dwordx4 v[64:65], v[68:71], off
	v_mul_f32_e32 v64, 0xbfb8aa3b, v60
	v_mul_f32_e32 v65, 0xbfb8aa3b, v61
	v_exp_f32_e32 v64, v64
	v_exp_f32_e32 v65, v65
	v_mul_f32_e32 v67, 0xbfb8aa3b, v63
	v_exp_f32_e32 v66, v66
	v_exp_f32_e32 v67, v67
	v_mul_f32_e32 v68, 0xbfb8aa3b, v56
	v_mul_f32_e32 v69, 0xbfb8aa3b, v57
	v_exp_f32_e32 v68, v68
	v_exp_f32_e32 v69, v69
	v_add_f32_e32 v64, 1.0, v64
	v_add_f32_e32 v65, 1.0, v65
	v_mul_f32_e32 v70, 0xbfb8aa3b, v58
	v_mul_f32_e32 v71, 0xbfb8aa3b, v59
	v_rcp_f32_e32 v64, v64
	v_rcp_f32_e32 v65, v65
	v_add_f32_e32 v66, 1.0, v66
	v_add_f32_e32 v67, 1.0, v67
	v_exp_f32_e32 v70, v70
	v_exp_f32_e32 v71, v71
	v_rcp_f32_e32 v66, v66
	v_rcp_f32_e32 v67, v67
	v_add_f32_e32 v68, 1.0, v68
	v_add_f32_e32 v69, 1.0, v69
	v_rcp_f32_e32 v68, v68
	v_rcp_f32_e32 v69, v69
	v_add_f32_e32 v70, 1.0, v70
	v_add_f32_e32 v71, 1.0, v71
	v_pk_mul_f32 v[60:61], v[60:61], v[64:65]
	v_rcp_f32_e32 v70, v70
	v_rcp_f32_e32 v71, v71
	v_pk_mul_f32 v[52:53], v[60:61], v[52:53]
	v_pk_mul_f32 v[60:61], v[62:63], v[66:67]
	v_cvt_pk_bf16_f32 v52, v52, v53
	v_pk_mul_f32 v[54:55], v[60:61], v[54:55]
	s_nop 0
	v_cvt_pk_bf16_f32 v53, v54, v55
	v_pk_mul_f32 v[54:55], v[56:57], v[68:69]
; #define PG8_WAIT_V(n) asm volatile("s_waitcnt vmcnt(" #n ")" ::: "memory")
; #define PG8_BAR __builtin_amdgcn_s_barrier()
; template <class Epi>
; DI void gemm_phase(LAS unsigned char* lds, const Gemm g, const StaticOrder& S, const Epi& E) {
;     ...
;         E(acc, cur, wr, wc, fr, fq);
;         if (!has_next) break;
; #pragma unroll
;         for (int a = 0; a < 2; ++a)
; #pragma unroll
;             for (int b = 0; b < 2; ++b)
; #pragma unroll
;                 for (int m = 0; m < 4; ++m)
; #pragma unroll
;                     for (int n = 0; n < 2; ++n) acc[a][b][m][n] = (f32x4){0.f, 0.f, 0.f, 0.f};
;         cur = nxt; cA = nA; cB = nB; ++ui;
;     }
;     PG8_WAIT_V(0);
;     if (wr == 0) PG8_BAR;
;     DI void operator()(const f32x4 (&acc)[2][2][4][2], const Unit& u, int wr, int wc, int fr, int fq) const {
;     ...
;             for (int m = 0; m < 4; ++m) { float hv[8];
; #pragma unroll
;                 for (int n = 0; n < 2; ++n)
; #pragma unroll
;                     for (int e = 0; e < 4; ++e) { const float gt = acc[ai][0][m][n][e], up = acc[ai][1][m][n][e];
;                         hv[n * 4 + e] = gt * __builtin_amdgcn_rcpf(1.f + __builtin_amdgcn_exp2f(-1.4426950408889634f * gt)) * up; }
;                 *(u32x4*)(H + (size_t)(row0 + ai * HALF + m * 16) * DFF + col0) = (u32x4){pk(hv[0], hv[1]), pk(hv[2], hv[3]), pk(hv[4], hv[5]), pk(hv[6], hv[7])}; }
	s_nop 0
	v_pk_mul_f32 v[48:49], v[54:55], v[48:49]
	s_nop 0
	v_cvt_pk_bf16_f32 v54, v48, v49
	v_pk_mul_f32 v[48:49], v[58:59], v[70:71]
	s_nop 0
	v_pk_mul_f32 v[48:49], v[48:49], v[50:51]
	v_mul_f32_e32 v50, 0xbfb8aa3b, v46
	v_cvt_pk_bf16_f32 v55, v48, v49
	v_mad_i64_i32 v[48:49], s[2:3], v72, s4, v[112:113]
	v_lshl_add_u64 v[48:49], v[48:49], 0, v[114:115]
	global_store_dwordx4 v[48:49], v[52:55], off
	v_mul_f32_e32 v48, 0xbfb8aa3b, v44
	v_mul_f32_e32 v49, 0xbfb8aa3b, v45
	v_exp_f32_e32 v48, v48
	v_exp_f32_e32 v49, v49
	v_mul_f32_e32 v51, 0xbfb8aa3b, v47
	v_exp_f32_e32 v50, v50
	v_exp_f32_e32 v51, v51
	v_mul_f32_e32 v52, 0xbfb8aa3b, v40
	v_mul_f32_e32 v53, 0xbfb8aa3b, v41
	v_exp_f32_e32 v52, v52
	v_exp_f32_e32 v53, v53
	v_add_f32_e32 v48, 1.0, v48
	v_add_f32_e32 v49, 1.0, v49
	v_mul_f32_e32 v54, 0xbfb8aa3b, v42
	v_mul_f32_e32 v55, 0xbfb8aa3b, v43
	v_rcp_f32_e32 v48, v48
	v_rcp_f32_e32 v49, v49
	v_add_f32_e32 v50, 1.0, v50
	v_add_f32_e32 v51, 1.0, v51
	v_exp_f32_e32 v54, v54
	v_exp_f32_e32 v55, v55
	v_rcp_f32_e32 v50, v50
	v_rcp_f32_e32 v51, v51
	v_add_f32_e32 v52, 1.0, v52
	v_add_f32_e32 v53, 1.0, v53
	v_rcp_f32_e32 v52, v52
	v_rcp_f32_e32 v53, v53
	v_add_f32_e32 v54, 1.0, v54
	v_add_f32_e32 v55, 1.0, v55
	v_pk_mul_f32 v[44:45], v[44:45], v[48:49]
	v_rcp_f32_e32 v54, v54
	v_rcp_f32_e32 v55, v55
	v_pk_mul_f32 v[36:37], v[44:45], v[36:37]
	v_pk_mul_f32 v[44:45], v[46:47], v[50:51]
	v_cvt_pk_bf16_f32 v36, v36, v37
	v_pk_mul_f32 v[38:39], v[44:45], v[38:39]
	s_nop 0
	v_cvt_pk_bf16_f32 v37, v38, v39
	v_pk_mul_f32 v[38:39], v[40:41], v[52:53]
	s_nop 0
	v_pk_mul_f32 v[32:33], v[38:39], v[32:33]
	s_nop 0
	v_cvt_pk_bf16_f32 v38, v32, v33
	v_pk_mul_f32 v[32:33], v[42:43], v[54:55]
	s_nop 0
	v_pk_mul_f32 v[32:33], v[32:33], v[34:35]
	v_mul_f32_e32 v34, 0xbfb8aa3b, v30
	v_cvt_pk_bf16_f32 v39, v32, v33
	v_add_u32_e32 v32, 0x90, v138
	v_mad_i64_i32 v[32:33], s[2:3], v32, s4, v[112:113]
	v_lshl_add_u64 v[32:33], v[32:33], 0, v[114:115]
	global_store_dwordx4 v[32:33], v[36:39], off
	v_mul_f32_e32 v32, 0xbfb8aa3b, v28
	v_mul_f32_e32 v33, 0xbfb8aa3b, v29
	v_exp_f32_e32 v32, v32
	v_exp_f32_e32 v33, v33
	v_mul_f32_e32 v35, 0xbfb8aa3b, v31
	v_exp_f32_e32 v34, v34
	v_exp_f32_e32 v35, v35
	v_mul_f32_e32 v36, 0xbfb8aa3b, v24
	v_mul_f32_e32 v37, 0xbfb8aa3b, v25
	v_exp_f32_e32 v36, v36
	v_exp_f32_e32 v37, v37
	v_add_f32_e32 v32, 1.0, v32
	v_add_f32_e32 v33, 1.0, v33
	v_mul_f32_e32 v38, 0xbfb8aa3b, v26
	v_mul_f32_e32 v39, 0xbfb8aa3b, v27
	v_rcp_f32_e32 v32, v32
	v_rcp_f32_e32 v33, v33
	v_add_f32_e32 v34, 1.0, v34
	v_add_f32_e32 v35, 1.0, v35
	v_exp_f32_e32 v38, v38
	v_exp_f32_e32 v39, v39
	v_rcp_f32_e32 v34, v34
	v_rcp_f32_e32 v35, v35
	v_add_f32_e32 v36, 1.0, v36
	v_add_f32_e32 v37, 1.0, v37
	v_rcp_f32_e32 v36, v36
	v_rcp_f32_e32 v37, v37
	v_add_f32_e32 v38, 1.0, v38
	v_add_f32_e32 v39, 1.0, v39
	v_pk_mul_f32 v[28:29], v[28:29], v[32:33]
	v_rcp_f32_e32 v38, v38
	v_rcp_f32_e32 v39, v39
	v_pk_mul_f32 v[20:21], v[28:29], v[20:21]
	v_pk_mul_f32 v[28:29], v[30:31], v[34:35]
	v_cvt_pk_bf16_f32 v20, v20, v21
	v_pk_mul_f32 v[22:23], v[28:29], v[22:23]
	s_nop 0
	v_cvt_pk_bf16_f32 v21, v22, v23
	v_pk_mul_f32 v[22:23], v[24:25], v[36:37]
	s_nop 0
	v_pk_mul_f32 v[16:17], v[22:23], v[16:17]
	s_nop 0
	v_cvt_pk_bf16_f32 v22, v16, v17
	v_pk_mul_f32 v[16:17], v[26:27], v[38:39]
	s_nop 0
	v_pk_mul_f32 v[16:17], v[16:17], v[18:19]
	v_mul_f32_e32 v18, 0xbfb8aa3b, v14
	v_cvt_pk_bf16_f32 v23, v16, v17
	v_add_u32_e32 v16, 0xa0, v138
	v_mad_i64_i32 v[16:17], s[2:3], v16, s4, v[112:113]
	v_lshl_add_u64 v[16:17], v[16:17], 0, v[114:115]
	global_store_dwordx4 v[16:17], v[20:23], off
	v_mul_f32_e32 v16, 0xbfb8aa3b, v12
	v_mul_f32_e32 v17, 0xbfb8aa3b, v13
	v_exp_f32_e32 v16, v16
	v_exp_f32_e32 v17, v17
	v_mul_f32_e32 v19, 0xbfb8aa3b, v15
	v_exp_f32_e32 v18, v18
	v_exp_f32_e32 v19, v19
	v_mul_f32_e32 v20, 0xbfb8aa3b, v8
	v_mul_f32_e32 v21, 0xbfb8aa3b, v9
	v_exp_f32_e32 v20, v20
	v_exp_f32_e32 v21, v21
	v_add_f32_e32 v16, 1.0, v16
	v_add_f32_e32 v17, 1.0, v17
	v_mul_f32_e32 v22, 0xbfb8aa3b, v10
	v_mul_f32_e32 v23, 0xbfb8aa3b, v11
	v_rcp_f32_e32 v16, v16
	v_rcp_f32_e32 v17, v17
	v_add_f32_e32 v18, 1.0, v18
	v_add_f32_e32 v19, 1.0, v19
	v_exp_f32_e32 v22, v22
	v_exp_f32_e32 v23, v23
	v_rcp_f32_e32 v18, v18
	v_rcp_f32_e32 v19, v19
	v_add_f32_e32 v20, 1.0, v20
	v_add_f32_e32 v21, 1.0, v21
	v_rcp_f32_e32 v20, v20
	v_rcp_f32_e32 v21, v21
	v_add_f32_e32 v22, 1.0, v22
	v_add_f32_e32 v23, 1.0, v23
	v_pk_mul_f32 v[12:13], v[12:13], v[16:17]
	v_rcp_f32_e32 v22, v22
	v_rcp_f32_e32 v23, v23
	v_pk_mul_f32 v[4:5], v[12:13], v[4:5]
	v_pk_mul_f32 v[12:13], v[14:15], v[18:19]
	v_cvt_pk_bf16_f32 v4, v4, v5
	v_pk_mul_f32 v[6:7], v[12:13], v[6:7]
	s_nop 0
	v_cvt_pk_bf16_f32 v5, v6, v7
	v_pk_mul_f32 v[6:7], v[8:9], v[20:21]
	s_nop 0
	v_pk_mul_f32 v[0:1], v[6:7], v[0:1]
	s_nop 0
	v_cvt_pk_bf16_f32 v6, v0, v1
	v_pk_mul_f32 v[0:1], v[10:11], v[22:23]
	s_nop 0
	v_pk_mul_f32 v[0:1], v[0:1], v[2:3]
	s_nop 0
	v_cvt_pk_bf16_f32 v7, v0, v1
	v_add_u32_e32 v0, 0xb0, v138
	v_mad_i64_i32 v[0:1], s[2:3], v0, s4, v[112:113]
	v_lshl_add_u64 v[0:1], v[0:1], 0, v[114:115]
	s_mov_b32 s2, s8
	s_mov_b32 s3, s10
	global_store_dwordx4 v[0:1], v[4:7], off
	s_cbranch_vccz .LBB0_34
	s_waitcnt vmcnt(0)
	s_cmpk_gt_u32 s24, 0xff
	s_cbranch_scc1 .LBB0_41
	s_barrier

; #define PG8_STAGE(bufoff, gbase) do { _Pragma("unroll") for (int _i = 0; _i < 2; ++_i) \
;         __builtin_amdgcn_global_load_lds((const unsigned*)((const char*)(gbase) + voff[_i]), (LAS unsigned*)(lds + (bufoff) + ldsw + _i * 8192), 16, 0, 0); } while (0)
; #define PG8_LDA(dst, b, h) do { _Pragma("unroll") for (int m = 0; m < 4; ++m) _Pragma("unroll") for (int k = 0; k < 2; ++k) dst[m][k] = *(const LAS bf16x8*)(lds + PG8_SA(b, h) + aoff + m * 2048 + k * 1024); } while (0)
; #define PG8_LDB(dst, b, h) do { _Pragma("unroll") for (int n = 0; n < 2; ++n) _Pragma("unroll") for (int k = 0; k < 2; ++k) dst[n][k] = *(const LAS bf16x8*)(lds + PG8_SB(b, h) + boff + n * 2048 + k * 1024); } while (0)
; #define PG8_MMA(ai, bj, At, Bt) do { __builtin_amdgcn_s_setprio(1); _Pragma("unroll") for (int m = 0; m < 4; ++m) _Pragma("unroll") for (int n = 0; n < 2; ++n) _Pragma("unroll") for (int k = 0; k < 2; ++k) \
;         acc[ai][bj][m][n] = __builtin_amdgcn_mfma_f32_16x16x32_bf16(Bt[n][k], At[m][k], acc[ai][bj][m][n], 0, 0, 0); __builtin_amdgcn_s_setprio(0); } while (0)
; template <class Epi>
; DI void gemm_phase(LAS unsigned char* lds, const Gemm g, const StaticOrder& S, const Epi& E) {
;     ...
;     for (;;) {
;         const bool has_next = S.next(ui + 1, nxt);
;         const char* nA = has_next ? (const char*)g.A + (size_t)nxt.pm * tstep : cA; const char* nB = has_next ? (const char*)g.Bt + (size_t)nxt.pn * tstep : cB;
;         for (int t = 0; t < nt; t += 2) {
;             const bool last = (t == nt - 2);
;             const char* a1 = cA + (size_t)(t + 1) * kstep;
;             const char* a2 = last ? nA : cA + (size_t)(t + 2) * kstep; const char* b2 = last ? nB : cB + (size_t)(t + 2) * kstep;
;             const char* a3 = a2 + kstep; const char* b3 = b2 + kstep;
;             PG8_LDB(B0, 0, 0); PG8_SCHED; PG8_LDA(At, 0, 0); PG8_STAGE(PG8_SA(1, 1), a1 + hstep);
;             PG8_WAIT_L(8); PG8_BAR; PG8_WAIT_L(0); PG8_MMA(0, 0, At, B0); PG8_BAR; PG8_SCHED;
;             PG8_LDB(B1, 0, 1); PG8_STAGE(PG8_SB(0, 0), b2);
;             PG8_BAR; PG8_WAIT_L(0); PG8_MMA(0, 1, At, B1); PG8_BAR;
;             PG8_LDA(At, 0, 1); PG8_STAGE(PG8_SA(0, 0), a2);
;             PG8_BAR; PG8_WAIT_L(0); PG8_MMA(1, 0, At, B0); PG8_BAR; PG8_SCHED;
;             PG8_STAGE(PG8_SB(0, 1), b2 + hstep);
;             PG8_WAIT_V(6); PG8_BAR; PG8_MMA(1, 1, At, B1); PG8_BAR;
.LBB0_77:
	s_add_u32 s22, s20, 0x100
	s_addc_u32 s23, s21, 0
	s_add_i32 s43, 0, 0x10000
	v_add_u32_e32 v140, s43, v226
	ds_read_b128 v[128:131], v140
	ds_read_b128 v[132:135], v140 offset:1024
	ds_read_b128 v[136:139], v140 offset:2048
	ds_read_b128 v[140:143], v140 offset:3072
	s_cmp_eq_u32 s33, 32
	s_cselect_b32 s27, s9, s23
	s_cselect_b32 s26, s8, s22
	s_cselect_b32 s25, s11, s5
	s_cselect_b32 s24, s10, s4
	v_lshl_add_u64 v[214:215], s[20:21], 0, v[190:191]
	s_add_i32 m0, s34, 0xc000
	ds_read_b128 v[144:147], v228
	ds_read_b128 v[148:151], v228 offset:1024
	ds_read_b128 v[152:155], v228 offset:2048
	ds_read_b128 v[194:197], v228 offset:3072
	ds_read_b128 v[198:201], v228 offset:4096
	ds_read_b128 v[202:205], v228 offset:5120
	ds_read_b128 v[206:209], v228 offset:6144
	ds_read_b128 v[210:213], v228 offset:7168
	global_load_lds_dwordx4 v[214:215], off
	v_lshl_add_u64 v[214:215], s[20:21], 0, v[192:193]
	s_add_i32 m0, s34, 0xe000
	s_nop 0
	global_load_lds_dwordx4 v[214:215], off
	s_waitcnt lgkmcnt(8)
	s_setprio 1
	s_barrier
	s_waitcnt lgkmcnt(0)
	v_mfma_f32_16x16x32_bf16 v[124:127], v[128:131], v[144:147], v[124:127]
	v_mfma_f32_16x16x32_bf16 v[120:123], v[136:139], v[144:147], v[120:123]
	v_mfma_f32_16x16x32_bf16 v[116:119], v[128:131], v[152:155], v[116:119]
	v_mfma_f32_16x16x32_bf16 v[112:115], v[136:139], v[152:155], v[112:115]
	v_mfma_f32_16x16x32_bf16 v[108:111], v[128:131], v[198:201], v[108:111]
	v_mfma_f32_16x16x32_bf16 v[104:107], v[136:139], v[198:201], v[104:107]
	v_mfma_f32_16x16x32_bf16 v[100:103], v[128:131], v[206:209], v[100:103]
	v_mfma_f32_16x16x32_bf16 v[96:99], v[136:139], v[206:209], v[96:99]
	v_mfma_f32_16x16x32_bf16 v[124:127], v[132:135], v[148:151], v[124:127]
	v_mfma_f32_16x16x32_bf16 v[120:123], v[140:143], v[148:151], v[120:123]
	v_mfma_f32_16x16x32_bf16 v[116:119], v[132:135], v[194:197], v[116:119]
	v_mfma_f32_16x16x32_bf16 v[112:115], v[140:143], v[194:197], v[112:115]
	s_add_i32 s44, 0, 0x14000
	s_add_i32 s20, s43, s31
	v_add_u32_e32 v158, s44, v226
	v_lshl_add_u64 v[218:219], s[24:25], 0, v[188:189]
	s_mov_b32 m0, s20
	v_mfma_f32_16x16x32_bf16 v[108:111], v[132:135], v[202:205], v[108:111]
	v_mfma_f32_16x16x32_bf16 v[104:107], v[140:143], v[202:205], v[104:107]
	v_mfma_f32_16x16x32_bf16 v[100:103], v[132:135], v[210:213], v[100:103]
	v_mfma_f32_16x16x32_bf16 v[96:99], v[140:143], v[210:213], v[96:99]
	s_setprio 0
	s_barrier
	ds_read_b128 v[214:217], v158
	ds_read_b128 v[230:233], v158 offset:1024
	ds_read_b128 v[234:237], v158 offset:2048
	ds_read_b128 v[238:241], v158 offset:3072
	global_load_lds_dwordx4 v[218:219], off
	v_lshl_add_u64 v[220:221], s[24:25], 0, v[186:187]
	s_add_i32 m0, s20, 0x2000
	s_nop 0
	global_load_lds_dwordx4 v[220:221], off
	s_waitcnt lgkmcnt(0)
	s_setprio 1
	s_barrier
	v_mfma_f32_16x16x32_bf16 v[60:63], v[214:217], v[144:147], v[60:63]
	v_mfma_f32_16x16x32_bf16 v[56:59], v[234:237], v[144:147], v[56:59]
	v_mfma_f32_16x16x32_bf16 v[52:55], v[214:217], v[152:155], v[52:55]
	v_mfma_f32_16x16x32_bf16 v[48:51], v[234:237], v[152:155], v[48:51]
	v_mfma_f32_16x16x32_bf16 v[44:47], v[214:217], v[198:201], v[44:47]
	v_mfma_f32_16x16x32_bf16 v[40:43], v[234:237], v[198:201], v[40:43]
	v_mfma_f32_16x16x32_bf16 v[36:39], v[214:217], v[206:209], v[36:39]
	v_mfma_f32_16x16x32_bf16 v[32:35], v[234:237], v[206:209], v[32:35]
	v_mfma_f32_16x16x32_bf16 v[60:63], v[230:233], v[148:151], v[60:63]
	v_mfma_f32_16x16x32_bf16 v[56:59], v[238:241], v[148:151], v[56:59]
	v_mfma_f32_16x16x32_bf16 v[52:55], v[230:233], v[194:197], v[52:55]
	v_mfma_f32_16x16x32_bf16 v[48:51], v[238:241], v[194:197], v[48:51]
	s_mov_b32 m0, s34
	v_lshl_add_u64 v[242:243], s[26:27], 0, v[188:189]
	v_mfma_f32_16x16x32_bf16 v[44:47], v[230:233], v[202:205], v[44:47]
	v_mfma_f32_16x16x32_bf16 v[40:43], v[238:241], v[202:205], v[40:43]
	v_mfma_f32_16x16x32_bf16 v[36:39], v[230:233], v[210:213], v[36:39]
	v_mfma_f32_16x16x32_bf16 v[32:35], v[238:241], v[210:213], v[32:35]
	s_setprio 0
	s_barrier
	ds_read_b128 v[144:147], v228 offset:16384
	ds_read_b128 v[148:151], v228 offset:17408
	ds_read_b128 v[152:155], v228 offset:18432
	ds_read_b128 v[194:197], v228 offset:19456
	ds_read_b128 v[198:201], v228 offset:20480
	ds_read_b128 v[202:205], v228 offset:21504
	ds_read_b128 v[206:209], v228 offset:22528
	ds_read_b128 v[210:213], v228 offset:23552
	global_load_lds_dwordx4 v[242:243], off
	v_lshl_add_u64 v[244:245], s[26:27], 0, v[186:187]
	s_mov_b32 m0, s35
	s_nop 0
	global_load_lds_dwordx4 v[244:245], off
	s_waitcnt lgkmcnt(0)
	s_setprio 1
	s_barrier
	v_mfma_f32_16x16x32_bf16 v[92:95], v[128:131], v[144:147], v[92:95]
	v_mfma_f32_16x16x32_bf16 v[88:91], v[136:139], v[144:147], v[88:91]
	v_mfma_f32_16x16x32_bf16 v[84:87], v[128:131], v[152:155], v[84:87]
	v_mfma_f32_16x16x32_bf16 v[80:83], v[136:139], v[152:155], v[80:83]
	v_mfma_f32_16x16x32_bf16 v[76:79], v[128:131], v[198:201], v[76:79]
	v_mfma_f32_16x16x32_bf16 v[72:75], v[136:139], v[198:201], v[72:75]
	v_mfma_f32_16x16x32_bf16 v[68:71], v[128:131], v[206:209], v[68:71]
	v_mfma_f32_16x16x32_bf16 v[64:67], v[136:139], v[206:209], v[64:67]
	v_mfma_f32_16x16x32_bf16 v[92:95], v[132:135], v[148:151], v[92:95]
	v_mfma_f32_16x16x32_bf16 v[88:91], v[140:143], v[148:151], v[88:91]
	v_mfma_f32_16x16x32_bf16 v[84:87], v[132:135], v[194:197], v[84:87]
	v_mfma_f32_16x16x32_bf16 v[80:83], v[140:143], v[194:197], v[80:83]
	s_add_u32 s20, s24, 0x90000
	s_addc_u32 s21, s25, 0
	s_add_i32 s43, s44, s31
	v_lshl_add_u64 v[128:129], s[20:21], 0, v[188:189]
	s_mov_b32 m0, s43
	v_mfma_f32_16x16x32_bf16 v[76:79], v[132:135], v[202:205], v[76:79]
	v_mfma_f32_16x16x32_bf16 v[72:75], v[140:143], v[202:205], v[72:75]
	v_mfma_f32_16x16x32_bf16 v[68:71], v[132:135], v[210:213], v[68:71]
	v_mfma_f32_16x16x32_bf16 v[64:67], v[140:143], v[210:213], v[64:67]
	s_setprio 0
	s_barrier
; #define PG8_STAGE(bufoff, gbase) do { _Pragma("unroll") for (int _i = 0; _i < 2; ++_i) \
;         __builtin_amdgcn_global_load_lds((const unsigned*)((const char*)(gbase) + voff[_i]), (LAS unsigned*)(lds + (bufoff) + ldsw + _i * 8192), 16, 0, 0); } while (0)
; #define PG8_LDA(dst, b, h) do { _Pragma("unroll") for (int m = 0; m < 4; ++m) _Pragma("unroll") for (int k = 0; k < 2; ++k) dst[m][k] = *(const LAS bf16x8*)(lds + PG8_SA(b, h) + aoff + m * 2048 + k * 1024); } while (0)
; #define PG8_LDB(dst, b, h) do { _Pragma("unroll") for (int n = 0; n < 2; ++n) _Pragma("unroll") for (int k = 0; k < 2; ++k) dst[n][k] = *(const LAS bf16x8*)(lds + PG8_SB(b, h) + boff + n * 2048 + k * 1024); } while (0)
; #define PG8_MMA(ai, bj, At, Bt) do { __builtin_amdgcn_s_setprio(1); _Pragma("unroll") for (int m = 0; m < 4; ++m) _Pragma("unroll") for (int n = 0; n < 2; ++n) _Pragma("unroll") for (int k = 0; k < 2; ++k) \
;         acc[ai][bj][m][n] = __builtin_amdgcn_mfma_f32_16x16x32_bf16(Bt[n][k], At[m][k], acc[ai][bj][m][n], 0, 0, 0); __builtin_amdgcn_s_setprio(0); } while (0)
; #define PG8_WAIT_V(n) asm volatile("s_waitcnt vmcnt(" #n ")" ::: "memory")
; #define PG8_WAIT_L(n) asm volatile("s_waitcnt lgkmcnt(" #n ")" ::: "memory")
; #define PG8_BAR __builtin_amdgcn_s_barrier()
; #define PG8_SCHED __builtin_amdgcn_sched_barrier(0)
; template <class Epi>
; DI void gemm_phase(LAS unsigned char* lds, const Gemm g, const StaticOrder& S, const Epi& E) {
;     ...
;             PG8_STAGE(PG8_SB(0, 1), b2 + hstep);
;             PG8_WAIT_V(6); PG8_BAR; PG8_MMA(1, 1, At, B1); PG8_BAR;
;             PG8_LDB(B0, 1, 0); PG8_SCHED; PG8_LDA(At, 1, 0); PG8_STAGE(PG8_SA(0, 1), a2 + hstep);
;             PG8_WAIT_L(8); PG8_BAR; PG8_WAIT_L(0); PG8_MMA(0, 0, At, B0); PG8_BAR; PG8_SCHED;
;             PG8_LDB(B1, 1, 1); PG8_STAGE(PG8_SB(1, 0), b3);
;             PG8_BAR; PG8_WAIT_L(0); PG8_MMA(0, 1, At, B1); PG8_BAR;
;             PG8_LDA(At, 1, 1); PG8_STAGE(PG8_SA(1, 0), a3);
;             PG8_BAR; PG8_WAIT_L(0); PG8_MMA(1, 0, At, B0); PG8_BAR; PG8_SCHED;
	s_nop 0
	global_load_lds_dwordx4 v[128:129], off
	v_lshl_add_u64 v[128:129], s[20:21], 0, v[186:187]
	s_add_i32 m0, s43, 0x2000
	s_nop 0
	global_load_lds_dwordx4 v[128:129], off
	s_waitcnt vmcnt(6)
	s_setprio 1
	s_barrier
	v_mfma_f32_16x16x32_bf16 v[28:31], v[214:217], v[144:147], v[28:31]
	v_mfma_f32_16x16x32_bf16 v[24:27], v[234:237], v[144:147], v[24:27]
	v_mfma_f32_16x16x32_bf16 v[20:23], v[214:217], v[152:155], v[20:23]
	v_mfma_f32_16x16x32_bf16 v[16:19], v[234:237], v[152:155], v[16:19]
	v_mfma_f32_16x16x32_bf16 v[12:15], v[214:217], v[198:201], v[12:15]
	v_mfma_f32_16x16x32_bf16 v[8:11], v[234:237], v[198:201], v[8:11]
	v_mfma_f32_16x16x32_bf16 v[4:7], v[214:217], v[206:209], v[4:7]
	v_mfma_f32_16x16x32_bf16 v[0:3], v[234:237], v[206:209], v[0:3]
	v_mfma_f32_16x16x32_bf16 v[28:31], v[230:233], v[148:151], v[28:31]
	v_mfma_f32_16x16x32_bf16 v[24:27], v[238:241], v[148:151], v[24:27]
	v_mfma_f32_16x16x32_bf16 v[20:23], v[230:233], v[194:197], v[20:23]
	v_mfma_f32_16x16x32_bf16 v[16:19], v[238:241], v[194:197], v[16:19]
	s_add_i32 s43, 0, 0x18000
	v_add_u32_e32 v140, s43, v226
	v_mfma_f32_16x16x32_bf16 v[12:15], v[230:233], v[202:205], v[12:15]
	v_mfma_f32_16x16x32_bf16 v[8:11], v[238:241], v[202:205], v[8:11]
	v_mfma_f32_16x16x32_bf16 v[4:7], v[230:233], v[210:213], v[4:7]
	v_mfma_f32_16x16x32_bf16 v[0:3], v[238:241], v[210:213], v[0:3]
	s_setprio 0
	s_barrier
	ds_read_b128 v[128:131], v140
	ds_read_b128 v[132:135], v140 offset:1024
	ds_read_b128 v[136:139], v140 offset:2048
	ds_read_b128 v[140:143], v140 offset:3072
	s_add_u32 s20, s26, 0x90000
	s_addc_u32 s21, s27, 0
	s_mov_b32 m0, s36
	v_lshl_add_u64 v[214:215], s[20:21], 0, v[188:189]
	ds_read_b128 v[144:147], v228 offset:32768
	ds_read_b128 v[148:151], v228 offset:33792
	ds_read_b128 v[152:155], v228 offset:34816
	ds_read_b128 v[194:197], v228 offset:35840
	ds_read_b128 v[198:201], v228 offset:36864
	ds_read_b128 v[202:205], v228 offset:37888
	ds_read_b128 v[206:209], v228 offset:38912
	ds_read_b128 v[210:213], v228 offset:39936
	global_load_lds_dwordx4 v[214:215], off
	v_lshl_add_u64 v[214:215], s[20:21], 0, v[186:187]
	s_mov_b32 m0, s37
	s_nop 0
	global_load_lds_dwordx4 v[214:215], off
	s_waitcnt lgkmcnt(8)
	s_setprio 1
	s_barrier
	s_waitcnt lgkmcnt(0)
	v_mfma_f32_16x16x32_bf16 v[124:127], v[128:131], v[144:147], v[124:127]
	v_mfma_f32_16x16x32_bf16 v[120:123], v[136:139], v[144:147], v[120:123]
	v_mfma_f32_16x16x32_bf16 v[116:119], v[128:131], v[152:155], v[116:119]
	v_mfma_f32_16x16x32_bf16 v[112:115], v[136:139], v[152:155], v[112:115]
	v_mfma_f32_16x16x32_bf16 v[108:111], v[128:131], v[198:201], v[108:111]
	v_mfma_f32_16x16x32_bf16 v[104:107], v[136:139], v[198:201], v[104:107]
	v_mfma_f32_16x16x32_bf16 v[100:103], v[128:131], v[206:209], v[100:103]
	v_mfma_f32_16x16x32_bf16 v[96:99], v[136:139], v[206:209], v[96:99]
	v_mfma_f32_16x16x32_bf16 v[124:127], v[132:135], v[148:151], v[124:127]
	v_mfma_f32_16x16x32_bf16 v[120:123], v[140:143], v[148:151], v[120:123]
	v_mfma_f32_16x16x32_bf16 v[116:119], v[132:135], v[194:197], v[116:119]
	v_mfma_f32_16x16x32_bf16 v[112:115], v[140:143], v[194:197], v[112:115]
	s_add_i32 s26, 0, 0x1c000
	s_add_i32 s20, s43, s31
	v_add_u32_e32 v158, s26, v226
	v_lshl_add_u64 v[218:219], v[218:219], 0, s[94:95]
	s_mov_b32 m0, s20
	v_mfma_f32_16x16x32_bf16 v[108:111], v[132:135], v[202:205], v[108:111]
	v_mfma_f32_16x16x32_bf16 v[104:107], v[140:143], v[202:205], v[104:107]
	v_mfma_f32_16x16x32_bf16 v[100:103], v[132:135], v[210:213], v[100:103]
	v_mfma_f32_16x16x32_bf16 v[96:99], v[140:143], v[210:213], v[96:99]
	s_setprio 0
	s_barrier
	ds_read_b128 v[214:217], v158
	ds_read_b128 v[230:233], v158 offset:1024
	ds_read_b128 v[234:237], v158 offset:2048
	ds_read_b128 v[238:241], v158 offset:3072
	global_load_lds_dwordx4 v[218:219], off
	v_lshl_add_u64 v[218:219], v[220:221], 0, s[94:95]
	s_add_i32 m0, s20, 0x2000
	s_nop 0
	global_load_lds_dwordx4 v[218:219], off
	s_waitcnt lgkmcnt(0)
	s_setprio 1
	s_barrier
	v_mfma_f32_16x16x32_bf16 v[60:63], v[214:217], v[144:147], v[60:63]
	v_mfma_f32_16x16x32_bf16 v[56:59], v[234:237], v[144:147], v[56:59]
	v_mfma_f32_16x16x32_bf16 v[52:55], v[214:217], v[152:155], v[52:55]
	v_mfma_f32_16x16x32_bf16 v[48:51], v[234:237], v[152:155], v[48:51]
	v_mfma_f32_16x16x32_bf16 v[44:47], v[214:217], v[198:201], v[44:47]
	v_mfma_f32_16x16x32_bf16 v[40:43], v[234:237], v[198:201], v[40:43]
	v_mfma_f32_16x16x32_bf16 v[36:39], v[214:217], v[206:209], v[36:39]
	v_mfma_f32_16x16x32_bf16 v[32:35], v[234:237], v[206:209], v[32:35]
	v_mfma_f32_16x16x32_bf16 v[60:63], v[230:233], v[148:151], v[60:63]
	v_mfma_f32_16x16x32_bf16 v[56:59], v[238:241], v[148:151], v[56:59]
	v_mfma_f32_16x16x32_bf16 v[52:55], v[230:233], v[194:197], v[52:55]
	v_mfma_f32_16x16x32_bf16 v[48:51], v[238:241], v[194:197], v[48:51]
	s_mov_b32 m0, s38
	v_lshl_add_u64 v[218:219], v[242:243], 0, s[94:95]
	v_mfma_f32_16x16x32_bf16 v[44:47], v[230:233], v[202:205], v[44:47]
	v_mfma_f32_16x16x32_bf16 v[40:43], v[238:241], v[202:205], v[40:43]
	v_mfma_f32_16x16x32_bf16 v[36:39], v[230:233], v[210:213], v[36:39]
	v_mfma_f32_16x16x32_bf16 v[32:35], v[238:241], v[210:213], v[32:35]
	s_setprio 0
	s_barrier
	ds_read_b128 v[144:147], v228 offset:49152
	ds_read_b128 v[148:151], v228 offset:50176
	ds_read_b128 v[152:155], v228 offset:51200
	ds_read_b128 v[194:197], v228 offset:52224
	ds_read_b128 v[198:201], v228 offset:53248
	ds_read_b128 v[202:205], v228 offset:54272
	ds_read_b128 v[206:209], v228 offset:55296
	ds_read_b128 v[210:213], v228 offset:56320
	global_load_lds_dwordx4 v[218:219], off
	v_lshl_add_u64 v[218:219], v[244:245], 0, s[94:95]
	s_mov_b32 m0, s39
	s_nop 0
	global_load_lds_dwordx4 v[218:219], off
	s_waitcnt lgkmcnt(0)
	s_setprio 1
	s_barrier
; #define PG8_WAIT_V(n) asm volatile("s_waitcnt vmcnt(" #n ")" ::: "memory")
; template <class Epi>
; DI void gemm_phase(LAS unsigned char* lds, const Gemm g, const StaticOrder& S, const Epi& E) {
;     ...
;             PG8_BAR; PG8_WAIT_L(0); PG8_MMA(1, 0, At, B0); PG8_BAR; PG8_SCHED;
;             PG8_STAGE(PG8_SB(1, 1), b3 + hstep);
;             PG8_WAIT_V(6); PG8_BAR; PG8_MMA(1, 1, At, B1); PG8_BAR;
;     template <bool LN, int BJ, int LO, int HI> DI void batch(const f32x4 (&acc)[2][2][4][2], unsigned row0, unsigned col0, const f32x4 (&gv)[2], const f32x4 (&bv)[2]) const {
;         f32x4 r[HI - LO]; float mean[(HI - LO) / 2], rstd[(HI - LO) / 2];
; #pragma unroll
;         for (int i = LO; i < HI; ++i) { const int ai = i >> 3, m = (i >> 1) & 3, n = i & 1; const unsigned row = row0 + ai * HALF + m * 16;
;             if (n == 0) { mean[(i - LO) >> 1] = 0.f; rstd[(i - LO) >> 1] = 1.f;
;                 if (LN) { const float2 st = *(const float2*)(stats + row * 2u); mean[(i - LO) >> 1] = st.x; rstd[(i - LO) >> 1] = st.y; } }
;             r[i - LO] = *(const f32x4*)(src + (row * (unsigned)DM + col0 + BJ * HALF + n * 16)); }
; #pragma unroll
;         for (int i = LO; i < HI; ++i) { const int ai = i >> 3, m = (i >> 1) & 3, n = i & 1; const unsigned row = row0 + ai * HALF + m * 16;
;             *(f32x4*)(Y + (row * (unsigned)DM + col0 + BJ * HALF + n * 16)) = acc[ai][BJ][m][n] + ((r[i - LO] - mean[(i - LO) >> 1]) * rstd[(i - LO) >> 1]) * gv[n] + bv[n]; }
;         __builtin_amdgcn_sched_barrier(0);
;     }
;     template <bool LN, int BJ> DI void load_gb(unsigned col0, f32x4 (&gv)[2], f32x4 (&bv)[2]) const {
; #pragma unroll
;         for (int n = 0; n < 2; ++n) {
;             if (LN) { gv[n] = *(const f32x4*)(gam + col0 + BJ * HALF + n * 16) * ALPHA; bv[n] = *(const f32x4*)(bet + col0 + BJ * HALF + n * 16) * ALPHA; }
;             else { gv[n] = (f32x4){ALPHA, ALPHA, ALPHA, ALPHA}; bv[n] = (f32x4){0.f, 0.f, 0.f, 0.f}; }
;         }
;     }
;     template <bool LN> DI void run(const f32x4 (&acc)[2][2][4][2], const Unit& u, int wr, int wc, int fr, int fq) const {
;         const unsigned row0 = u.pm * BM + wr * 64 + fr, col0 = u.pn * BM + wc * 32 + 4 * fq;
;         f32x4 gv[2], bv[2];
;         load_gb<LN, 0>(col0, gv, bv);
;         batch<LN, 0, 0, 4>(acc, row0, col0, gv, bv);
;         batch<LN, 0, 4, 8>(acc, row0, col0, gv, bv);
	v_mfma_f32_16x16x32_bf16 v[92:95], v[128:131], v[144:147], v[92:95]
	v_mfma_f32_16x16x32_bf16 v[88:91], v[136:139], v[144:147], v[88:91]
	v_mfma_f32_16x16x32_bf16 v[84:87], v[128:131], v[152:155], v[84:87]
	v_mfma_f32_16x16x32_bf16 v[80:83], v[136:139], v[152:155], v[80:83]
	v_mfma_f32_16x16x32_bf16 v[76:79], v[128:131], v[198:201], v[76:79]
	v_mfma_f32_16x16x32_bf16 v[72:75], v[136:139], v[198:201], v[72:75]
	v_mfma_f32_16x16x32_bf16 v[68:71], v[128:131], v[206:209], v[68:71]
	v_mfma_f32_16x16x32_bf16 v[64:67], v[136:139], v[206:209], v[64:67]
	v_mfma_f32_16x16x32_bf16 v[92:95], v[132:135], v[148:151], v[92:95]
	v_mfma_f32_16x16x32_bf16 v[88:91], v[140:143], v[148:151], v[88:91]
	v_mfma_f32_16x16x32_bf16 v[84:87], v[132:135], v[194:197], v[84:87]
	v_mfma_f32_16x16x32_bf16 v[80:83], v[140:143], v[194:197], v[80:83]
	s_add_u32 s20, s24, 0x90080
	s_addc_u32 s21, s25, 0
	s_add_i32 s24, s26, s31
	v_lshl_add_u64 v[128:129], s[20:21], 0, v[188:189]
	s_mov_b32 m0, s24
	v_mfma_f32_16x16x32_bf16 v[76:79], v[132:135], v[202:205], v[76:79]
	v_mfma_f32_16x16x32_bf16 v[72:75], v[140:143], v[202:205], v[72:75]
	v_mfma_f32_16x16x32_bf16 v[68:71], v[132:135], v[210:213], v[68:71]
	v_mfma_f32_16x16x32_bf16 v[64:67], v[140:143], v[210:213], v[64:67]
	s_setprio 0
	s_barrier
	s_nop 0
	global_load_lds_dwordx4 v[128:129], off
	v_lshl_add_u64 v[128:129], s[20:21], 0, v[186:187]
	s_add_i32 m0, s24, 0x2000
	s_nop 0
	global_load_lds_dwordx4 v[128:129], off
	s_waitcnt vmcnt(6)
	s_setprio 1
	s_barrier
	v_mfma_f32_16x16x32_bf16 v[28:31], v[214:217], v[144:147], v[28:31]
	v_mfma_f32_16x16x32_bf16 v[24:27], v[234:237], v[144:147], v[24:27]
	v_mfma_f32_16x16x32_bf16 v[20:23], v[214:217], v[152:155], v[20:23]
	v_mfma_f32_16x16x32_bf16 v[16:19], v[234:237], v[152:155], v[16:19]
	v_mfma_f32_16x16x32_bf16 v[12:15], v[214:217], v[198:201], v[12:15]
	v_mfma_f32_16x16x32_bf16 v[8:11], v[234:237], v[198:201], v[8:11]
	v_mfma_f32_16x16x32_bf16 v[4:7], v[214:217], v[206:209], v[4:7]
	v_mfma_f32_16x16x32_bf16 v[0:3], v[234:237], v[206:209], v[0:3]
	v_mfma_f32_16x16x32_bf16 v[28:31], v[230:233], v[148:151], v[28:31]
	v_mfma_f32_16x16x32_bf16 v[24:27], v[238:241], v[148:151], v[24:27]
	v_mfma_f32_16x16x32_bf16 v[20:23], v[230:233], v[194:197], v[20:23]
	v_mfma_f32_16x16x32_bf16 v[16:19], v[238:241], v[194:197], v[16:19]
	s_add_i32 s33, s33, 2
	s_add_u32 s4, s4, 0x100
	s_addc_u32 s5, s5, 0
	s_cmp_gt_u32 s33, 33
	s_mov_b64 s[20:21], s[22:23]
	v_mfma_f32_16x16x32_bf16 v[12:15], v[230:233], v[202:205], v[12:15]
	v_mfma_f32_16x16x32_bf16 v[8:11], v[238:241], v[202:205], v[8:11]
	v_mfma_f32_16x16x32_bf16 v[4:7], v[230:233], v[210:213], v[4:7]
	v_mfma_f32_16x16x32_bf16 v[0:3], v[238:241], v[210:213], v[0:3]
	s_setprio 0
	s_barrier
	s_cbranch_scc0 .LBB0_77
	v_lshl_add_u32 v206, s3, 8, v225
	v_lshl_or_b32 v158, s2, 8, v227
	v_lshlrev_b32_e32 v232, 11, v206
	s_andn2_b64 vcc, exec, s[14:15]
	v_or_b32_e32 v231, 16, v158
	v_add_u32_e32 v194, v232, v158
	v_or_b32_e32 v230, 0x80, v158
	v_or_b32_e32 v229, 0x90, v158
	s_cbranch_vccnz .LBB0_80
	v_lshlrev_b64 v[132:133], 2, v[158:159]
	v_lshl_add_u64 v[140:141], s[16:17], 0, v[132:133]
	global_load_dwordx4 v[128:131], v[140:141], off
	v_lshl_add_u64 v[142:143], s[18:19], 0, v[132:133]
	v_readlane_b32 s2, v253, 8
	v_mov_b32_e32 v195, v159
	v_lshlrev_b32_e32 v136, 1, v206
	v_mov_b32_e32 v137, v159
	v_readlane_b32 s3, v253, 9
	v_lshlrev_b64 v[212:213], 2, v[194:195]
	v_add_u32_e32 v146, v232, v231
	v_lshl_add_u64 v[144:145], v[136:137], 2, s[2:3]
	v_lshl_add_u64 v[136:137], s[88:89], 0, v[212:213]
	v_mov_b32_e32 v147, v159
	v_lshl_add_u64 v[146:147], v[146:147], 2, s[88:89]
	v_or_b32_e32 v195, 16, v206
	v_mov_b32_e32 v201, v159
	v_mov_b32_e32 v209, v159
	v_lshl_add_u64 v[212:213], s[90:91], 0, v[212:213]
	s_waitcnt vmcnt(0)
	v_pk_mul_f32 v[152:153], v[130:131], s[78:79] op_sel_hi:[1,0]
	v_pk_mul_f32 v[154:155], v[128:129], s[78:79] op_sel_hi:[1,0]
	global_load_dwordx4 v[132:135], v[142:143], off
	global_load_dwordx4 v[128:131], v[140:141], off offset:64
	global_load_dwordx2 v[204:205], v[144:145], off
	global_load_dwordx4 v[196:199], v[146:147], off
	v_lshlrev_b32_e32 v146, 1, v195
	global_load_dwordx4 v[136:139], v[136:137], off
	v_lshlrev_b32_e32 v195, 11, v195
	v_mov_b32_e32 v147, v159
	v_add_u32_e32 v200, v195, v158
	v_lshl_add_u64 v[146:147], v[146:147], 2, s[2:3]
	v_lshl_add_u64 v[200:201], v[200:201], 2, s[88:89]
	global_load_dwordx2 v[214:215], v[146:147], off
	v_add_u32_e32 v208, v195, v231
	global_load_dwordx4 v[200:203], v[200:201], off
	v_lshl_add_u64 v[208:209], v[208:209], 2, s[88:89]
	global_load_dwordx4 v[208:211], v[208:209], off
	s_waitcnt vmcnt(0)
	v_pk_mul_f32 v[148:149], v[130:131], s[78:79] op_sel_hi:[1,0]
	v_pk_mul_f32 v[150:151], v[128:129], s[78:79] op_sel_hi:[1,0]
	global_load_dwordx4 v[128:131], v[142:143], off offset:64
	v_sub_f32_e32 v137, v137, v204
	v_sub_f32_e32 v136, v136, v204
	v_sub_f32_e32 v139, v139, v204
	v_sub_f32_e32 v138, v138, v204
	v_pk_mul_f32 v[138:139], v[204:205], v[138:139] op_sel:[1,0]
	v_pk_mul_f32 v[136:137], v[204:205], v[136:137] op_sel:[1,0]
	v_pk_fma_f32 v[138:139], v[152:153], v[138:139], v[126:127]
	v_pk_fma_f32 v[136:137], v[154:155], v[136:137], v[124:125]
	v_pk_fma_f32 v[138:139], v[134:135], s[78:79], v[138:139] op_sel_hi:[1,0,1]
	v_pk_fma_f32 v[136:137], v[132:133], s[78:79], v[136:137] op_sel_hi:[1,0,1]
	global_store_dwordx4 v[212:213], v[136:139], off
	s_nop 1
	v_sub_f32_e32 v137, v197, v204
	v_sub_f32_e32 v136, v196, v204
	v_sub_f32_e32 v139, v199, v204
	v_sub_f32_e32 v138, v198, v204
	v_pk_mul_f32 v[138:139], v[204:205], v[138:139] op_sel:[1,0]
	v_pk_mul_f32 v[136:137], v[204:205], v[136:137] op_sel:[1,0]
	v_pk_fma_f32 v[138:139], v[148:149], v[138:139], v[122:123]
	v_pk_fma_f32 v[136:137], v[150:151], v[136:137], v[120:121]
	v_or_b32_e32 v196, 16, v194
	v_mov_b32_e32 v197, v159
	v_lshl_add_u64 v[196:197], v[196:197], 2, s[90:91]
	s_waitcnt vmcnt(0)
;     template <bool LN, int BJ, int LO, int HI> DI void batch(const f32x4 (&acc)[2][2][4][2], unsigned row0, unsigned col0, const f32x4 (&gv)[2], const f32x4 (&bv)[2]) const {
;         f32x4 r[HI - LO]; float mean[(HI - LO) / 2], rstd[(HI - LO) / 2];
; #pragma unroll
;         for (int i = LO; i < HI; ++i) { const int ai = i >> 3, m = (i >> 1) & 3, n = i & 1; const unsigned row = row0 + ai * HALF + m * 16;
;             if (n == 0) { mean[(i - LO) >> 1] = 0.f; rstd[(i - LO) >> 1] = 1.f;
;                 if (LN) { const float2 st = *(const float2*)(stats + row * 2u); mean[(i - LO) >> 1] = st.x; rstd[(i - LO) >> 1] = st.y; } }
;             r[i - LO] = *(const f32x4*)(src + (row * (unsigned)DM + col0 + BJ * HALF + n * 16)); }
; #pragma unroll
;         for (int i = LO; i < HI; ++i) { const int ai = i >> 3, m = (i >> 1) & 3, n = i & 1; const unsigned row = row0 + ai * HALF + m * 16;
;             *(f32x4*)(Y + (row * (unsigned)DM + col0 + BJ * HALF + n * 16)) = acc[ai][BJ][m][n] + ((r[i - LO] - mean[(i - LO) >> 1]) * rstd[(i - LO) >> 1]) * gv[n] + bv[n]; }
	v_pk_fma_f32 v[138:139], v[130:131], s[78:79], v[138:139] op_sel_hi:[1,0,1]
	v_pk_fma_f32 v[136:137], v[128:129], s[78:79], v[136:137] op_sel_hi:[1,0,1]
	global_store_dwordx4 v[196:197], v[136:139], off
	v_add_u32_e32 v196, 0x8000, v194
	v_mov_b32_e32 v197, v159
	v_sub_f32_e32 v137, v201, v214
	v_sub_f32_e32 v136, v200, v214
	v_sub_f32_e32 v139, v203, v214
	v_sub_f32_e32 v138, v202, v214
	v_pk_mul_f32 v[138:139], v[214:215], v[138:139] op_sel:[1,0]
	v_pk_mul_f32 v[136:137], v[214:215], v[136:137] op_sel:[1,0]
	v_pk_fma_f32 v[138:139], v[152:153], v[138:139], v[118:119]
	v_pk_fma_f32 v[136:137], v[154:155], v[136:137], v[116:117]
	v_pk_fma_f32 v[138:139], v[134:135], s[78:79], v[138:139] op_sel_hi:[1,0,1]
	v_pk_fma_f32 v[136:137], v[132:133], s[78:79], v[136:137] op_sel_hi:[1,0,1]
	v_lshl_add_u64 v[196:197], v[196:197], 2, s[90:91]
	global_store_dwordx4 v[196:197], v[136:139], off
	v_add_u32_e32 v196, 0x8010, v194
	v_mov_b32_e32 v197, v159
	v_sub_f32_e32 v137, v209, v214
	v_sub_f32_e32 v136, v208, v214
	v_sub_f32_e32 v139, v211, v214
	v_sub_f32_e32 v138, v210, v214
	v_pk_mul_f32 v[138:139], v[214:215], v[138:139] op_sel:[1,0]
	v_pk_mul_f32 v[136:137], v[214:215], v[136:137] op_sel:[1,0]
	v_pk_fma_f32 v[138:139], v[148:149], v[138:139], v[114:115]
	v_pk_fma_f32 v[136:137], v[150:151], v[136:137], v[112:113]
	v_pk_fma_f32 v[138:139], v[130:131], s[78:79], v[138:139] op_sel_hi:[1,0,1]
	v_pk_fma_f32 v[136:137], v[128:129], s[78:79], v[136:137] op_sel_hi:[1,0,1]
	v_lshl_add_u64 v[196:197], v[196:197], 2, s[90:91]
	global_store_dwordx4 v[196:197], v[136:139], off
	s_nop 1
	v_or_b32_e32 v138, 32, v206
	v_lshlrev_b32_e32 v136, 1, v138
	v_mov_b32_e32 v137, v159
	v_lshlrev_b32_e32 v236, 11, v138
	v_lshl_add_u64 v[200:201], v[136:137], 2, s[2:3]
	v_add_u32_e32 v136, v236, v158
	v_lshl_add_u64 v[136:137], v[136:137], 2, s[88:89]
	global_load_dwordx2 v[204:205], v[200:201], off
	v_add_u32_e32 v196, v236, v231
	global_load_dwordx4 v[136:139], v[136:137], off
	v_mov_b32_e32 v197, v159
	v_lshl_add_u64 v[196:197], v[196:197], 2, s[88:89]
	global_load_dwordx4 v[196:199], v[196:197], off
	v_or_b32_e32 v207, 48, v206
	v_lshlrev_b32_e32 v235, 11, v207
	v_lshlrev_b32_e32 v202, 1, v207
	v_mov_b32_e32 v203, v159
	v_add_u32_e32 v208, v235, v158
	v_mov_b32_e32 v209, v159
	v_lshl_add_u64 v[202:203], v[202:203], 2, s[2:3]
	v_lshl_add_u64 v[208:209], v[208:209], 2, s[88:89]
	global_load_dwordx2 v[216:217], v[202:203], off
	v_add_u32_e32 v212, v235, v231
	global_load_dwordx4 v[208:211], v[208:209], off
	v_mov_b32_e32 v213, v159
	v_lshl_add_u64 v[212:213], v[212:213], 2, s[88:89]
	global_load_dwordx4 v[212:215], v[212:213], off
	v_add_u32_e32 v218, 0x10000, v194
	v_mov_b32_e32 v219, v159
	v_lshl_add_u64 v[218:219], v[218:219], 2, s[90:91]
	s_waitcnt vmcnt(0)
	v_sub_f32_e32 v137, v137, v204
	v_sub_f32_e32 v136, v136, v204
	v_sub_f32_e32 v139, v139, v204
	v_sub_f32_e32 v138, v138, v204
	v_pk_mul_f32 v[138:139], v[204:205], v[138:139] op_sel:[1,0]
	v_pk_mul_f32 v[136:137], v[204:205], v[136:137] op_sel:[1,0]
	v_pk_fma_f32 v[138:139], v[152:153], v[138:139], v[110:111]
	v_pk_fma_f32 v[136:137], v[154:155], v[136:137], v[108:109]
	v_pk_fma_f32 v[138:139], v[134:135], s[78:79], v[138:139] op_sel_hi:[1,0,1]
	v_pk_fma_f32 v[136:137], v[132:133], s[78:79], v[136:137] op_sel_hi:[1,0,1]
	global_store_dwordx4 v[218:219], v[136:139], off
	s_nop 1
	v_sub_f32_e32 v137, v197, v204
	v_sub_f32_e32 v136, v196, v204
	v_sub_f32_e32 v139, v199, v204
	v_sub_f32_e32 v138, v198, v204
	v_pk_mul_f32 v[138:139], v[204:205], v[138:139] op_sel:[1,0]
	v_pk_mul_f32 v[136:137], v[204:205], v[136:137] op_sel:[1,0]
	v_pk_fma_f32 v[138:139], v[148:149], v[138:139], v[106:107]
	v_pk_fma_f32 v[136:137], v[150:151], v[136:137], v[104:105]
	v_add_u32_e32 v196, 0x10010, v194
	v_mov_b32_e32 v197, v159
	v_pk_fma_f32 v[138:139], v[130:131], s[78:79], v[138:139] op_sel_hi:[1,0,1]
	v_pk_fma_f32 v[136:137], v[128:129], s[78:79], v[136:137] op_sel_hi:[1,0,1]
	v_lshl_add_u64 v[196:197], v[196:197], 2, s[90:91]
	global_store_dwordx4 v[196:197], v[136:139], off
	v_add_u32_e32 v196, 0x18000, v194
	v_mov_b32_e32 v197, v159
	v_sub_f32_e32 v137, v209, v216
	v_sub_f32_e32 v136, v208, v216
	v_sub_f32_e32 v139, v211, v216
	v_sub_f32_e32 v138, v210, v216
	v_pk_mul_f32 v[138:139], v[216:217], v[138:139] op_sel:[1,0]
	v_pk_mul_f32 v[136:137], v[216:217], v[136:137] op_sel:[1,0]
	v_pk_fma_f32 v[138:139], v[152:153], v[138:139], v[102:103]
	v_pk_fma_f32 v[136:137], v[154:155], v[136:137], v[100:101]
	v_pk_fma_f32 v[138:139], v[134:135], s[78:79], v[138:139] op_sel_hi:[1,0,1]
	v_pk_fma_f32 v[136:137], v[132:133], s[78:79], v[136:137] op_sel_hi:[1,0,1]
	v_lshl_add_u64 v[196:197], v[196:197], 2, s[90:91]
	global_store_dwordx4 v[196:197], v[136:139], off
	v_add_u32_e32 v196, 0x18010, v194
	v_mov_b32_e32 v197, v159
	v_sub_f32_e32 v137, v213, v216
	v_sub_f32_e32 v136, v212, v216
	v_sub_f32_e32 v139, v215, v216
	v_sub_f32_e32 v138, v214, v216
	v_pk_mul_f32 v[138:139], v[216:217], v[138:139] op_sel:[1,0]
	v_pk_mul_f32 v[136:137], v[216:217], v[136:137] op_sel:[1,0]
	v_pk_fma_f32 v[138:139], v[148:149], v[138:139], v[98:99]
	v_pk_fma_f32 v[136:137], v[150:151], v[136:137], v[96:97]
	v_pk_fma_f32 v[138:139], v[130:131], s[78:79], v[138:139] op_sel_hi:[1,0,1]
	v_pk_fma_f32 v[136:137], v[128:129], s[78:79], v[136:137] op_sel_hi:[1,0,1]
	v_lshl_add_u64 v[196:197], v[196:197], 2, s[90:91]
	global_store_dwordx4 v[196:197], v[136:139], off
	s_nop 1
	v_add_u32_e32 v138, 0x80, v206
	v_lshlrev_b32_e32 v136, 1, v138
	v_mov_b32_e32 v137, v159
	v_lshlrev_b32_e32 v233, 11, v138
	v_lshl_add_u64 v[196:197], v[136:137], 2, s[2:3]
	v_add_u32_e32 v136, v233, v158
	v_lshl_add_u64 v[136:137], v[136:137], 2, s[88:89]
	global_load_dwordx2 v[204:205], v[196:197], off
	v_add_u32_e32 v198, v233, v231
	global_load_dwordx4 v[136:139], v[136:137], off
	v_mov_b32_e32 v199, v159
	v_add_u32_e32 v207, 0x90, v206
	v_lshl_add_u64 v[198:199], v[198:199], 2, s[88:89]
	v_lshlrev_b32_e32 v234, 11, v207
	global_load_dwordx4 v[208:211], v[198:199], off
	v_add_u32_e32 v212, v234, v158
	v_mov_b32_e32 v213, v159
	v_lshl_add_u64 v[212:213], v[212:213], 2, s[88:89]
	global_load_dwordx4 v[212:215], v[212:213], off
	v_lshlrev_b32_e32 v198, 1, v207
	v_mov_b32_e32 v199, v159
	v_lshl_add_u64 v[198:199], v[198:199], 2, s[2:3]
	global_load_dwordx2 v[220:221], v[198:199], off
	v_add_u32_e32 v216, v234, v231
	v_mov_b32_e32 v217, v159
	v_lshl_add_u64 v[216:217], v[216:217], 2, s[88:89]
	global_load_dwordx4 v[216:219], v[216:217], off
	v_add_u32_e32 v238, 0x40000, v194
	v_mov_b32_e32 v239, v159
	v_lshl_add_u64 v[238:239], v[238:239], 2, s[90:91]
	s_waitcnt vmcnt(0)
;     template <bool LN, int BJ, int LO, int HI> DI void batch(const f32x4 (&acc)[2][2][4][2], unsigned row0, unsigned col0, const f32x4 (&gv)[2], const f32x4 (&bv)[2]) const {
;         f32x4 r[HI - LO]; float mean[(HI - LO) / 2], rstd[(HI - LO) / 2];
; #pragma unroll
;         for (int i = LO; i < HI; ++i) { const int ai = i >> 3, m = (i >> 1) & 3, n = i & 1; const unsigned row = row0 + ai * HALF + m * 16;
;             if (n == 0) { mean[(i - LO) >> 1] = 0.f; rstd[(i - LO) >> 1] = 1.f;
;                 if (LN) { const float2 st = *(const float2*)(stats + row * 2u); mean[(i - LO) >> 1] = st.x; rstd[(i - LO) >> 1] = st.y; } }
;             r[i - LO] = *(const f32x4*)(src + (row * (unsigned)DM + col0 + BJ * HALF + n * 16)); }
; #pragma unroll
;         for (int i = LO; i < HI; ++i) { const int ai = i >> 3, m = (i >> 1) & 3, n = i & 1; const unsigned row = row0 + ai * HALF + m * 16;
;             *(f32x4*)(Y + (row * (unsigned)DM + col0 + BJ * HALF + n * 16)) = acc[ai][BJ][m][n] + ((r[i - LO] - mean[(i - LO) >> 1]) * rstd[(i - LO) >> 1]) * gv[n] + bv[n]; }
;         __builtin_amdgcn_sched_barrier(0);
;     }
;     template <bool LN, int BJ> DI void load_gb(unsigned col0, f32x4 (&gv)[2], f32x4 (&bv)[2]) const {
; #pragma unroll
;         for (int n = 0; n < 2; ++n) {
;             if (LN) { gv[n] = *(const f32x4*)(gam + col0 + BJ * HALF + n * 16) * ALPHA; bv[n] = *(const f32x4*)(bet + col0 + BJ * HALF + n * 16) * ALPHA; }
;             else { gv[n] = (f32x4){ALPHA, ALPHA, ALPHA, ALPHA}; bv[n] = (f32x4){0.f, 0.f, 0.f, 0.f}; }
;         }
;     }
;     template <bool LN> DI void run(const f32x4 (&acc)[2][2][4][2], const Unit& u, int wr, int wc, int fr, int fq) const {
;         const unsigned row0 = u.pm * BM + wr * 64 + fr, col0 = u.pn * BM + wc * 32 + 4 * fq;
;         f32x4 gv[2], bv[2];
;         load_gb<LN, 0>(col0, gv, bv);
;         batch<LN, 0, 0, 4>(acc, row0, col0, gv, bv);
;         batch<LN, 0, 4, 8>(acc, row0, col0, gv, bv);
;         batch<LN, 0, 8, 12>(acc, row0, col0, gv, bv);
;         batch<LN, 0, 12, 16>(acc, row0, col0, gv, bv);
;         load_gb<LN, 1>(col0, gv, bv);
	v_sub_f32_e32 v137, v137, v204
	v_sub_f32_e32 v136, v136, v204
	v_sub_f32_e32 v139, v139, v204
	v_sub_f32_e32 v138, v138, v204
	v_pk_mul_f32 v[138:139], v[204:205], v[138:139] op_sel:[1,0]
	v_pk_mul_f32 v[136:137], v[204:205], v[136:137] op_sel:[1,0]
	v_pk_fma_f32 v[138:139], v[152:153], v[138:139], v[94:95]
	v_pk_fma_f32 v[136:137], v[154:155], v[136:137], v[92:93]
	v_pk_fma_f32 v[138:139], v[134:135], s[78:79], v[138:139] op_sel_hi:[1,0,1]
	v_pk_fma_f32 v[136:137], v[132:133], s[78:79], v[136:137] op_sel_hi:[1,0,1]
	global_store_dwordx4 v[238:239], v[136:139], off
	s_nop 1
	v_sub_f32_e32 v137, v209, v204
	v_sub_f32_e32 v136, v208, v204
	v_sub_f32_e32 v139, v211, v204
	v_sub_f32_e32 v138, v210, v204
	v_pk_mul_f32 v[138:139], v[204:205], v[138:139] op_sel:[1,0]
	v_pk_mul_f32 v[136:137], v[204:205], v[136:137] op_sel:[1,0]
	v_pk_fma_f32 v[138:139], v[148:149], v[138:139], v[90:91]
	v_pk_fma_f32 v[136:137], v[150:151], v[136:137], v[88:89]
	v_add_u32_e32 v204, 0x40010, v194
	v_mov_b32_e32 v205, v159
	v_pk_fma_f32 v[138:139], v[130:131], s[78:79], v[138:139] op_sel_hi:[1,0,1]
	v_pk_fma_f32 v[136:137], v[128:129], s[78:79], v[136:137] op_sel_hi:[1,0,1]
	v_lshl_add_u64 v[204:205], v[204:205], 2, s[90:91]
	global_store_dwordx4 v[204:205], v[136:139], off
	v_add_u32_e32 v204, 0x48000, v194
	v_mov_b32_e32 v205, v159
	v_sub_f32_e32 v137, v213, v220
	v_sub_f32_e32 v136, v212, v220
	v_sub_f32_e32 v139, v215, v220
	v_sub_f32_e32 v138, v214, v220
	v_pk_mul_f32 v[138:139], v[220:221], v[138:139] op_sel:[1,0]
	v_pk_mul_f32 v[136:137], v[220:221], v[136:137] op_sel:[1,0]
	v_pk_fma_f32 v[138:139], v[152:153], v[138:139], v[86:87]
	v_pk_fma_f32 v[136:137], v[154:155], v[136:137], v[84:85]
	v_pk_fma_f32 v[138:139], v[134:135], s[78:79], v[138:139] op_sel_hi:[1,0,1]
	v_pk_fma_f32 v[136:137], v[132:133], s[78:79], v[136:137] op_sel_hi:[1,0,1]
	v_lshl_add_u64 v[204:205], v[204:205], 2, s[90:91]
	global_store_dwordx4 v[204:205], v[136:139], off
	v_add_u32_e32 v204, 0x48010, v194
	v_mov_b32_e32 v205, v159
	v_sub_f32_e32 v137, v217, v220
	v_sub_f32_e32 v136, v216, v220
	v_sub_f32_e32 v139, v219, v220
	v_sub_f32_e32 v138, v218, v220
	v_pk_mul_f32 v[138:139], v[220:221], v[138:139] op_sel:[1,0]
	v_pk_mul_f32 v[136:137], v[220:221], v[136:137] op_sel:[1,0]
	v_pk_fma_f32 v[138:139], v[148:149], v[138:139], v[82:83]
	v_pk_fma_f32 v[136:137], v[150:151], v[136:137], v[80:81]
	v_pk_fma_f32 v[138:139], v[130:131], s[78:79], v[138:139] op_sel_hi:[1,0,1]
	v_pk_fma_f32 v[136:137], v[128:129], s[78:79], v[136:137] op_sel_hi:[1,0,1]
	v_lshl_add_u64 v[204:205], v[204:205], 2, s[90:91]
	global_store_dwordx4 v[204:205], v[136:139], off
	s_nop 1
	v_add_u32_e32 v138, 0xa0, v206
	v_lshlrev_b32_e32 v136, 1, v138
	v_mov_b32_e32 v137, v159
	v_lshlrev_b32_e32 v237, 11, v138
	v_lshl_add_u64 v[204:205], v[136:137], 2, s[2:3]
	v_add_u32_e32 v136, v237, v158
	v_lshl_add_u64 v[136:137], v[136:137], 2, s[88:89]
	global_load_dwordx2 v[220:221], v[204:205], off
	v_add_u32_e32 v208, v237, v231
	global_load_dwordx4 v[136:139], v[136:137], off
	v_mov_b32_e32 v209, v159
	v_lshl_add_u64 v[208:209], v[208:209], 2, s[88:89]
	global_load_dwordx4 v[212:215], v[208:209], off
	v_add_u32_e32 v208, 0xb0, v206
	v_lshlrev_b32_e32 v206, 1, v208
	v_mov_b32_e32 v207, v159
	v_lshlrev_b32_e32 v238, 11, v208
	v_lshl_add_u64 v[210:211], v[206:207], 2, s[2:3]
	v_add_u32_e32 v206, v238, v158
	v_lshl_add_u64 v[206:207], v[206:207], 2, s[88:89]
	global_load_dwordx2 v[240:241], v[210:211], off
	v_add_u32_e32 v216, v238, v231
	global_load_dwordx4 v[206:209], v[206:207], off
	v_mov_b32_e32 v217, v159
	v_lshl_add_u64 v[216:217], v[216:217], 2, s[88:89]
	global_load_dwordx4 v[216:219], v[216:217], off
	v_add_u32_e32 v242, 0x50000, v194
	v_mov_b32_e32 v243, v159
	v_lshl_add_u64 v[242:243], v[242:243], 2, s[90:91]
	s_waitcnt vmcnt(0)
	v_sub_f32_e32 v137, v137, v220
	v_sub_f32_e32 v136, v136, v220
	v_sub_f32_e32 v139, v139, v220
	v_sub_f32_e32 v138, v138, v220
	v_pk_mul_f32 v[138:139], v[220:221], v[138:139] op_sel:[1,0]
	v_pk_mul_f32 v[136:137], v[220:221], v[136:137] op_sel:[1,0]
	v_pk_fma_f32 v[138:139], v[152:153], v[138:139], v[78:79]
	v_pk_fma_f32 v[136:137], v[154:155], v[136:137], v[76:77]
	v_pk_fma_f32 v[138:139], v[134:135], s[78:79], v[138:139] op_sel_hi:[1,0,1]
	v_pk_fma_f32 v[136:137], v[132:133], s[78:79], v[136:137] op_sel_hi:[1,0,1]
	global_store_dwordx4 v[242:243], v[136:139], off
	s_nop 1
	v_sub_f32_e32 v137, v213, v220
	v_sub_f32_e32 v136, v212, v220
	v_sub_f32_e32 v139, v215, v220
	v_sub_f32_e32 v138, v214, v220
	v_pk_mul_f32 v[138:139], v[220:221], v[138:139] op_sel:[1,0]
	v_pk_mul_f32 v[136:137], v[220:221], v[136:137] op_sel:[1,0]
	v_pk_fma_f32 v[138:139], v[148:149], v[138:139], v[74:75]
	v_pk_fma_f32 v[136:137], v[150:151], v[136:137], v[72:73]
	v_add_u32_e32 v212, 0x50010, v194
	v_mov_b32_e32 v213, v159
	v_pk_fma_f32 v[138:139], v[130:131], s[78:79], v[138:139] op_sel_hi:[1,0,1]
	v_pk_fma_f32 v[136:137], v[128:129], s[78:79], v[136:137] op_sel_hi:[1,0,1]
	v_lshl_add_u64 v[212:213], v[212:213], 2, s[90:91]
	global_store_dwordx4 v[212:213], v[136:139], off
	s_nop 1
	v_sub_f32_e32 v137, v207, v240
	v_sub_f32_e32 v136, v206, v240
	v_sub_f32_e32 v139, v209, v240
	v_sub_f32_e32 v138, v208, v240
	v_pk_mul_f32 v[136:137], v[240:241], v[136:137] op_sel:[1,0]
	v_pk_mul_f32 v[138:139], v[240:241], v[138:139] op_sel:[1,0]
	v_pk_fma_f32 v[136:137], v[154:155], v[136:137], v[68:69]
	v_pk_fma_f32 v[138:139], v[152:153], v[138:139], v[70:71]
	v_pk_fma_f32 v[132:133], v[132:133], s[78:79], v[136:137] op_sel_hi:[1,0,1]
	v_add_u32_e32 v136, 0x58000, v194
	v_mov_b32_e32 v137, v159
	v_pk_fma_f32 v[134:135], v[134:135], s[78:79], v[138:139] op_sel_hi:[1,0,1]
	v_lshl_add_u64 v[136:137], v[136:137], 2, s[90:91]
	global_store_dwordx4 v[136:137], v[132:135], off
	s_nop 1
	v_sub_f32_e32 v133, v217, v240
	v_sub_f32_e32 v132, v216, v240
	v_sub_f32_e32 v135, v219, v240
	v_sub_f32_e32 v134, v218, v240
	v_pk_mul_f32 v[132:133], v[240:241], v[132:133] op_sel:[1,0]
	v_pk_mul_f32 v[134:135], v[240:241], v[134:135] op_sel:[1,0]
	v_pk_fma_f32 v[132:133], v[150:151], v[132:133], v[64:65]
	v_pk_fma_f32 v[134:135], v[148:149], v[134:135], v[66:67]
	v_pk_fma_f32 v[128:129], v[128:129], s[78:79], v[132:133] op_sel_hi:[1,0,1]
	v_add_u32_e32 v132, 0x58010, v194
	v_mov_b32_e32 v133, v159
	v_pk_fma_f32 v[130:131], v[130:131], s[78:79], v[134:135] op_sel_hi:[1,0,1]
	v_lshl_add_u64 v[132:133], v[132:133], 2, s[90:91]
	global_store_dwordx4 v[132:133], v[128:131], off
	global_load_dwordx4 v[128:131], v[140:141], off offset:512
	v_add_u32_e32 v136, v232, v230
	v_mov_b32_e32 v137, v159
	v_lshl_add_u64 v[136:137], v[136:137], 2, s[88:89]
	s_waitcnt vmcnt(0)
;     template <bool LN, int BJ, int LO, int HI> DI void batch(const f32x4 (&acc)[2][2][4][2], unsigned row0, unsigned col0, const f32x4 (&gv)[2], const f32x4 (&bv)[2]) const {
;         f32x4 r[HI - LO]; float mean[(HI - LO) / 2], rstd[(HI - LO) / 2];
; #pragma unroll
;         for (int i = LO; i < HI; ++i) { const int ai = i >> 3, m = (i >> 1) & 3, n = i & 1; const unsigned row = row0 + ai * HALF + m * 16;
;             if (n == 0) { mean[(i - LO) >> 1] = 0.f; rstd[(i - LO) >> 1] = 1.f;
;                 if (LN) { const float2 st = *(const float2*)(stats + row * 2u); mean[(i - LO) >> 1] = st.x; rstd[(i - LO) >> 1] = st.y; } }
;             r[i - LO] = *(const f32x4*)(src + (row * (unsigned)DM + col0 + BJ * HALF + n * 16)); }
; #pragma unroll
;         for (int i = LO; i < HI; ++i) { const int ai = i >> 3, m = (i >> 1) & 3, n = i & 1; const unsigned row = row0 + ai * HALF + m * 16;
;             *(f32x4*)(Y + (row * (unsigned)DM + col0 + BJ * HALF + n * 16)) = acc[ai][BJ][m][n] + ((r[i - LO] - mean[(i - LO) >> 1]) * rstd[(i - LO) >> 1]) * gv[n] + bv[n]; }
;         __builtin_amdgcn_sched_barrier(0);
;     }
;     template <bool LN, int BJ> DI void load_gb(unsigned col0, f32x4 (&gv)[2], f32x4 (&bv)[2]) const {
; #pragma unroll
;         for (int n = 0; n < 2; ++n) {
;             if (LN) { gv[n] = *(const f32x4*)(gam + col0 + BJ * HALF + n * 16) * ALPHA; bv[n] = *(const f32x4*)(bet + col0 + BJ * HALF + n * 16) * ALPHA; }
;             else { gv[n] = (f32x4){ALPHA, ALPHA, ALPHA, ALPHA}; bv[n] = (f32x4){0.f, 0.f, 0.f, 0.f}; }
;         }
;     }
;     template <bool LN> DI void run(const f32x4 (&acc)[2][2][4][2], const Unit& u, int wr, int wc, int fr, int fq) const {
;         const unsigned row0 = u.pm * BM + wr * 64 + fr, col0 = u.pn * BM + wc * 32 + 4 * fq;
;         f32x4 gv[2], bv[2];
;         load_gb<LN, 0>(col0, gv, bv);
;         batch<LN, 0, 0, 4>(acc, row0, col0, gv, bv);
;         batch<LN, 0, 4, 8>(acc, row0, col0, gv, bv);
;         batch<LN, 0, 8, 12>(acc, row0, col0, gv, bv);
;         batch<LN, 0, 12, 16>(acc, row0, col0, gv, bv);
;         load_gb<LN, 1>(col0, gv, bv);
;         batch<LN, 1, 0, 8>(acc, row0, col0, gv, bv);
;         batch<LN, 1, 8, 16>(acc, row0, col0, gv, bv);
	v_pk_mul_f32 v[212:213], v[130:131], s[78:79] op_sel_hi:[1,0]
	v_pk_mul_f32 v[214:215], v[128:129], s[78:79] op_sel_hi:[1,0]
	global_load_dwordx4 v[132:135], v[142:143], off offset:512
	global_load_dwordx4 v[128:131], v[140:141], off offset:576
	s_waitcnt vmcnt(0)
	v_pk_mul_f32 v[206:207], v[130:131], s[78:79] op_sel_hi:[1,0]
	v_pk_mul_f32 v[208:209], v[128:129], s[78:79] op_sel_hi:[1,0]
	global_load_dwordx4 v[128:131], v[142:143], off offset:576
	global_load_dwordx2 v[220:221], v[144:145], off
	global_load_dwordx4 v[240:243], v[136:137], off
	v_add_u32_e32 v136, v232, v229
	v_mov_b32_e32 v137, v159
	v_lshl_add_u64 v[136:137], v[136:137], 2, s[88:89]
	global_load_dwordx4 v[244:247], v[136:137], off
	global_load_dwordx2 v[218:219], v[146:147], off
	v_add_u32_e32 v136, v195, v230
	v_mov_b32_e32 v137, v159
	v_lshl_add_u64 v[136:137], v[136:137], 2, s[88:89]
	global_load_dwordx4 v[248:251], v[136:137], off
	v_add_u32_e32 v136, v195, v229
	v_mov_b32_e32 v137, v159
	v_lshl_add_u64 v[136:137], v[136:137], 2, s[88:89]
	global_load_dwordx4 v[152:155], v[136:137], off
	global_load_dwordx2 v[216:217], v[200:201], off
	v_add_u32_e32 v136, v236, v230
	v_mov_b32_e32 v137, v159
	v_lshl_add_u64 v[136:137], v[136:137], 2, s[88:89]
	global_load_dwordx4 v[148:151], v[136:137], off
	v_add_u32_e32 v136, v236, v229
	v_mov_b32_e32 v137, v159
	v_lshl_add_u64 v[136:137], v[136:137], 2, s[88:89]
	global_load_dwordx4 v[144:147], v[136:137], off
	global_load_dwordx2 v[200:201], v[202:203], off
	v_add_u32_e32 v136, v235, v230
	v_mov_b32_e32 v137, v159
	v_lshl_add_u64 v[136:137], v[136:137], 2, s[88:89]
	global_load_dwordx4 v[140:143], v[136:137], off
	v_add_u32_e32 v136, v235, v229
	v_mov_b32_e32 v137, v159
	v_lshl_add_u64 v[136:137], v[136:137], 2, s[88:89]
	global_load_dwordx4 v[136:139], v[136:137], off
	v_add_u32_e32 v202, 0x80, v194
	v_mov_b32_e32 v203, v159
	v_lshl_add_u64 v[202:203], v[202:203], 2, s[90:91]
	s_waitcnt vmcnt(0)
	v_sub_f32_e32 v241, v241, v220
	v_sub_f32_e32 v240, v240, v220
	v_sub_f32_e32 v243, v243, v220
	v_sub_f32_e32 v242, v242, v220
	v_pk_mul_f32 v[242:243], v[220:221], v[242:243] op_sel:[1,0]
	v_pk_mul_f32 v[240:241], v[220:221], v[240:241] op_sel:[1,0]
	v_pk_fma_f32 v[242:243], v[212:213], v[242:243], v[62:63]
	v_pk_fma_f32 v[240:241], v[214:215], v[240:241], v[60:61]
	v_pk_fma_f32 v[242:243], v[134:135], s[78:79], v[242:243] op_sel_hi:[1,0,1]
	v_pk_fma_f32 v[240:241], v[132:133], s[78:79], v[240:241] op_sel_hi:[1,0,1]
	global_store_dwordx4 v[202:203], v[240:243], off
	v_sub_f32_e32 v203, v245, v220
	v_sub_f32_e32 v202, v244, v220
	v_sub_f32_e32 v241, v247, v220
	v_sub_f32_e32 v240, v246, v220
	v_pk_mul_f32 v[202:203], v[220:221], v[202:203] op_sel:[1,0]
	v_pk_mul_f32 v[240:241], v[220:221], v[240:241] op_sel:[1,0]
	v_pk_fma_f32 v[202:203], v[208:209], v[202:203], v[56:57]
	v_pk_fma_f32 v[220:221], v[206:207], v[240:241], v[58:59]
	v_pk_fma_f32 v[240:241], v[128:129], s[78:79], v[202:203] op_sel_hi:[1,0,1]
	v_add_u32_e32 v202, 0x90, v194
	v_mov_b32_e32 v203, v159
	v_pk_fma_f32 v[242:243], v[130:131], s[78:79], v[220:221] op_sel_hi:[1,0,1]
	v_lshl_add_u64 v[202:203], v[202:203], 2, s[90:91]
	global_store_dwordx4 v[202:203], v[240:243], off
	v_sub_f32_e32 v203, v249, v218
	v_sub_f32_e32 v202, v248, v218
	v_sub_f32_e32 v221, v251, v218
	v_sub_f32_e32 v220, v250, v218
	v_pk_mul_f32 v[202:203], v[218:219], v[202:203] op_sel:[1,0]
	v_pk_mul_f32 v[220:221], v[218:219], v[220:221] op_sel:[1,0]
	v_pk_fma_f32 v[202:203], v[214:215], v[202:203], v[52:53]
	v_pk_fma_f32 v[220:221], v[212:213], v[220:221], v[54:55]
	v_pk_fma_f32 v[240:241], v[132:133], s[78:79], v[202:203] op_sel_hi:[1,0,1]
	v_add_u32_e32 v202, 0x8080, v194
	v_mov_b32_e32 v203, v159
	v_sub_f32_e32 v153, v153, v218
	v_sub_f32_e32 v152, v152, v218
	v_sub_f32_e32 v155, v155, v218
	v_sub_f32_e32 v154, v154, v218
	v_pk_fma_f32 v[242:243], v[134:135], s[78:79], v[220:221] op_sel_hi:[1,0,1]
	v_lshl_add_u64 v[202:203], v[202:203], 2, s[90:91]
	v_pk_mul_f32 v[154:155], v[218:219], v[154:155] op_sel:[1,0]
	v_pk_mul_f32 v[152:153], v[218:219], v[152:153] op_sel:[1,0]
	global_store_dwordx4 v[202:203], v[240:243], off
	v_pk_fma_f32 v[152:153], v[208:209], v[152:153], v[48:49]
	v_pk_fma_f32 v[154:155], v[206:207], v[154:155], v[50:51]
	v_add_u32_e32 v202, 0x8090, v194
	v_mov_b32_e32 v203, v159
	v_sub_f32_e32 v149, v149, v216
	v_sub_f32_e32 v148, v148, v216
	v_sub_f32_e32 v151, v151, v216
	v_sub_f32_e32 v150, v150, v216
	v_pk_fma_f32 v[154:155], v[130:131], s[78:79], v[154:155] op_sel_hi:[1,0,1]
	v_pk_fma_f32 v[152:153], v[128:129], s[78:79], v[152:153] op_sel_hi:[1,0,1]
	v_lshl_add_u64 v[202:203], v[202:203], 2, s[90:91]
	v_pk_mul_f32 v[150:151], v[216:217], v[150:151] op_sel:[1,0]
	v_pk_mul_f32 v[148:149], v[216:217], v[148:149] op_sel:[1,0]
	global_store_dwordx4 v[202:203], v[152:155], off
	v_pk_fma_f32 v[148:149], v[214:215], v[148:149], v[44:45]
	v_pk_fma_f32 v[150:151], v[212:213], v[150:151], v[46:47]
	v_add_u32_e32 v152, 0x10080, v194
	v_mov_b32_e32 v153, v159
	v_sub_f32_e32 v145, v145, v216
	v_sub_f32_e32 v144, v144, v216
	v_sub_f32_e32 v147, v147, v216
	v_sub_f32_e32 v146, v146, v216
	v_pk_fma_f32 v[150:151], v[134:135], s[78:79], v[150:151] op_sel_hi:[1,0,1]
	v_pk_fma_f32 v[148:149], v[132:133], s[78:79], v[148:149] op_sel_hi:[1,0,1]
	v_lshl_add_u64 v[152:153], v[152:153], 2, s[90:91]
	v_pk_mul_f32 v[146:147], v[216:217], v[146:147] op_sel:[1,0]
	v_pk_mul_f32 v[144:145], v[216:217], v[144:145] op_sel:[1,0]
	global_store_dwordx4 v[152:153], v[148:151], off
	v_pk_fma_f32 v[144:145], v[208:209], v[144:145], v[40:41]
	v_pk_fma_f32 v[146:147], v[206:207], v[146:147], v[42:43]
;     template <bool LN, int BJ, int LO, int HI> DI void batch(const f32x4 (&acc)[2][2][4][2], unsigned row0, unsigned col0, const f32x4 (&gv)[2], const f32x4 (&bv)[2]) const {
;         f32x4 r[HI - LO]; float mean[(HI - LO) / 2], rstd[(HI - LO) / 2];
; #pragma unroll
;         for (int i = LO; i < HI; ++i) { const int ai = i >> 3, m = (i >> 1) & 3, n = i & 1; const unsigned row = row0 + ai * HALF + m * 16;
;             if (n == 0) { mean[(i - LO) >> 1] = 0.f; rstd[(i - LO) >> 1] = 1.f;
;                 if (LN) { const float2 st = *(const float2*)(stats + row * 2u); mean[(i - LO) >> 1] = st.x; rstd[(i - LO) >> 1] = st.y; } }
;             r[i - LO] = *(const f32x4*)(src + (row * (unsigned)DM + col0 + BJ * HALF + n * 16)); }
; #pragma unroll
;         for (int i = LO; i < HI; ++i) { const int ai = i >> 3, m = (i >> 1) & 3, n = i & 1; const unsigned row = row0 + ai * HALF + m * 16;
;             *(f32x4*)(Y + (row * (unsigned)DM + col0 + BJ * HALF + n * 16)) = acc[ai][BJ][m][n] + ((r[i - LO] - mean[(i - LO) >> 1]) * rstd[(i - LO) >> 1]) * gv[n] + bv[n]; }
;         __builtin_amdgcn_sched_barrier(0);
;     }
;     template <bool LN, int BJ> DI void load_gb(unsigned col0, f32x4 (&gv)[2], f32x4 (&bv)[2]) const {
; #pragma unroll
;         for (int n = 0; n < 2; ++n) {
;             if (LN) { gv[n] = *(const f32x4*)(gam + col0 + BJ * HALF + n * 16) * ALPHA; bv[n] = *(const f32x4*)(bet + col0 + BJ * HALF + n * 16) * ALPHA; }
;             else { gv[n] = (f32x4){ALPHA, ALPHA, ALPHA, ALPHA}; bv[n] = (f32x4){0.f, 0.f, 0.f, 0.f}; }
;         }
;     }
;     template <bool LN> DI void run(const f32x4 (&acc)[2][2][4][2], const Unit& u, int wr, int wc, int fr, int fq) const {
;         const unsigned row0 = u.pm * BM + wr * 64 + fr, col0 = u.pn * BM + wc * 32 + 4 * fq;
;         f32x4 gv[2], bv[2];
;         load_gb<LN, 0>(col0, gv, bv);
;         batch<LN, 0, 0, 4>(acc, row0, col0, gv, bv);
;         batch<LN, 0, 4, 8>(acc, row0, col0, gv, bv);
;         batch<LN, 0, 8, 12>(acc, row0, col0, gv, bv);
;         batch<LN, 0, 12, 16>(acc, row0, col0, gv, bv);
;         load_gb<LN, 1>(col0, gv, bv);
;         batch<LN, 1, 0, 8>(acc, row0, col0, gv, bv);
;         batch<LN, 1, 8, 16>(acc, row0, col0, gv, bv);
	v_add_u32_e32 v148, 0x10090, v194
	v_mov_b32_e32 v149, v159
	v_sub_f32_e32 v141, v141, v200
	v_sub_f32_e32 v140, v140, v200
	v_sub_f32_e32 v143, v143, v200
	v_sub_f32_e32 v142, v142, v200
	v_pk_fma_f32 v[146:147], v[130:131], s[78:79], v[146:147] op_sel_hi:[1,0,1]
	v_pk_fma_f32 v[144:145], v[128:129], s[78:79], v[144:145] op_sel_hi:[1,0,1]
	v_lshl_add_u64 v[148:149], v[148:149], 2, s[90:91]
	v_pk_mul_f32 v[142:143], v[200:201], v[142:143] op_sel:[1,0]
	v_pk_mul_f32 v[140:141], v[200:201], v[140:141] op_sel:[1,0]
	global_store_dwordx4 v[148:149], v[144:147], off
	v_pk_fma_f32 v[140:141], v[214:215], v[140:141], v[36:37]
	v_pk_fma_f32 v[142:143], v[212:213], v[142:143], v[38:39]
	v_add_u32_e32 v144, 0x18080, v194
	v_mov_b32_e32 v145, v159
	v_sub_f32_e32 v137, v137, v200
	v_sub_f32_e32 v136, v136, v200
	v_sub_f32_e32 v139, v139, v200
	v_sub_f32_e32 v138, v138, v200
	v_pk_fma_f32 v[142:143], v[134:135], s[78:79], v[142:143] op_sel_hi:[1,0,1]
	v_pk_fma_f32 v[140:141], v[132:133], s[78:79], v[140:141] op_sel_hi:[1,0,1]
	v_lshl_add_u64 v[144:145], v[144:145], 2, s[90:91]
	v_pk_mul_f32 v[138:139], v[200:201], v[138:139] op_sel:[1,0]
	v_pk_mul_f32 v[136:137], v[200:201], v[136:137] op_sel:[1,0]
	global_store_dwordx4 v[144:145], v[140:143], off
	v_pk_fma_f32 v[136:137], v[208:209], v[136:137], v[32:33]
	v_pk_fma_f32 v[138:139], v[206:207], v[138:139], v[34:35]
	v_add_u32_e32 v140, 0x18090, v194
	v_mov_b32_e32 v141, v159
	v_pk_fma_f32 v[138:139], v[130:131], s[78:79], v[138:139] op_sel_hi:[1,0,1]
	v_pk_fma_f32 v[136:137], v[128:129], s[78:79], v[136:137] op_sel_hi:[1,0,1]
	v_lshl_add_u64 v[140:141], v[140:141], 2, s[90:91]
	global_store_dwordx4 v[140:141], v[136:139], off
	s_nop 1
	v_add_u32_e32 v136, v233, v230
	v_mov_b32_e32 v137, v159
	v_lshl_add_u64 v[136:137], v[136:137], 2, s[88:89]
	global_load_dwordx2 v[220:221], v[196:197], off
	global_load_dwordx4 v[216:219], v[136:137], off
	v_add_u32_e32 v136, v233, v229
	v_mov_b32_e32 v137, v159
	v_lshl_add_u64 v[136:137], v[136:137], 2, s[88:89]
	global_load_dwordx4 v[240:243], v[136:137], off
	global_load_dwordx2 v[200:201], v[198:199], off
	v_add_u32_e32 v136, v234, v230
	v_mov_b32_e32 v137, v159
	v_lshl_add_u64 v[136:137], v[136:137], 2, s[88:89]
	global_load_dwordx4 v[244:247], v[136:137], off
	v_add_u32_e32 v136, v234, v229
	v_mov_b32_e32 v137, v159
	v_lshl_add_u64 v[136:137], v[136:137], 2, s[88:89]
	global_load_dwordx4 v[152:155], v[136:137], off
	global_load_dwordx2 v[198:199], v[204:205], off
	v_add_u32_e32 v136, v237, v230
	v_mov_b32_e32 v137, v159
	v_lshl_add_u64 v[136:137], v[136:137], 2, s[88:89]
	global_load_dwordx4 v[148:151], v[136:137], off
	v_add_u32_e32 v136, v237, v229
	v_mov_b32_e32 v137, v159
	v_lshl_add_u64 v[136:137], v[136:137], 2, s[88:89]
	global_load_dwordx4 v[144:147], v[136:137], off
	global_load_dwordx2 v[196:197], v[210:211], off
	v_add_u32_e32 v136, v238, v230
	v_mov_b32_e32 v137, v159
	v_lshl_add_u64 v[136:137], v[136:137], 2, s[88:89]
	global_load_dwordx4 v[140:143], v[136:137], off
	v_add_u32_e32 v136, v238, v229
	v_mov_b32_e32 v137, v159
	v_lshl_add_u64 v[136:137], v[136:137], 2, s[88:89]
	global_load_dwordx4 v[136:139], v[136:137], off
	v_add_u32_e32 v210, 0x40080, v194
	v_mov_b32_e32 v211, v159
	v_lshl_add_u64 v[210:211], v[210:211], 2, s[90:91]
	s_waitcnt vmcnt(0)
;     template <bool LN, int BJ, int LO, int HI> DI void batch(const f32x4 (&acc)[2][2][4][2], unsigned row0, unsigned col0, const f32x4 (&gv)[2], const f32x4 (&bv)[2]) const {
;         f32x4 r[HI - LO]; float mean[(HI - LO) / 2], rstd[(HI - LO) / 2];
; #pragma unroll
;         for (int i = LO; i < HI; ++i) { const int ai = i >> 3, m = (i >> 1) & 3, n = i & 1; const unsigned row = row0 + ai * HALF + m * 16;
;             if (n == 0) { mean[(i - LO) >> 1] = 0.f; rstd[(i - LO) >> 1] = 1.f;
;                 if (LN) { const float2 st = *(const float2*)(stats + row * 2u); mean[(i - LO) >> 1] = st.x; rstd[(i - LO) >> 1] = st.y; } }
;             r[i - LO] = *(const f32x4*)(src + (row * (unsigned)DM + col0 + BJ * HALF + n * 16)); }
; #pragma unroll
;         for (int i = LO; i < HI; ++i) { const int ai = i >> 3, m = (i >> 1) & 3, n = i & 1; const unsigned row = row0 + ai * HALF + m * 16;
;             *(f32x4*)(Y + (row * (unsigned)DM + col0 + BJ * HALF + n * 16)) = acc[ai][BJ][m][n] + ((r[i - LO] - mean[(i - LO) >> 1]) * rstd[(i - LO) >> 1]) * gv[n] + bv[n]; }
;         __builtin_amdgcn_sched_barrier(0);
;     }
;     template <bool LN, int BJ> DI void load_gb(unsigned col0, f32x4 (&gv)[2], f32x4 (&bv)[2]) const {
; #pragma unroll
;         for (int n = 0; n < 2; ++n) {
;             if (LN) { gv[n] = *(const f32x4*)(gam + col0 + BJ * HALF + n * 16) * ALPHA; bv[n] = *(const f32x4*)(bet + col0 + BJ * HALF + n * 16) * ALPHA; }
;             else { gv[n] = (f32x4){ALPHA, ALPHA, ALPHA, ALPHA}; bv[n] = (f32x4){0.f, 0.f, 0.f, 0.f}; }
;         }
;     }
;     template <bool LN> DI void run(const f32x4 (&acc)[2][2][4][2], const Unit& u, int wr, int wc, int fr, int fq) const {
;         const unsigned row0 = u.pm * BM + wr * 64 + fr, col0 = u.pn * BM + wc * 32 + 4 * fq;
;         f32x4 gv[2], bv[2];
;         load_gb<LN, 0>(col0, gv, bv);
;         batch<LN, 0, 0, 4>(acc, row0, col0, gv, bv);
;         batch<LN, 0, 4, 8>(acc, row0, col0, gv, bv);
;         batch<LN, 0, 8, 12>(acc, row0, col0, gv, bv);
;         batch<LN, 0, 12, 16>(acc, row0, col0, gv, bv);
;         load_gb<LN, 1>(col0, gv, bv);
;         batch<LN, 1, 0, 8>(acc, row0, col0, gv, bv);
;         batch<LN, 1, 8, 16>(acc, row0, col0, gv, bv);
	v_sub_f32_e32 v203, v217, v220
	v_sub_f32_e32 v202, v216, v220
	v_sub_f32_e32 v205, v219, v220
	v_sub_f32_e32 v204, v218, v220
	v_pk_mul_f32 v[204:205], v[220:221], v[204:205] op_sel:[1,0]
	v_pk_mul_f32 v[202:203], v[220:221], v[202:203] op_sel:[1,0]
	v_pk_fma_f32 v[204:205], v[212:213], v[204:205], v[30:31]
	v_pk_fma_f32 v[202:203], v[214:215], v[202:203], v[28:29]
	v_pk_fma_f32 v[204:205], v[134:135], s[78:79], v[204:205] op_sel_hi:[1,0,1]
	v_pk_fma_f32 v[202:203], v[132:133], s[78:79], v[202:203] op_sel_hi:[1,0,1]
	global_store_dwordx4 v[210:211], v[202:205], off
	v_add_u32_e32 v210, 0x40090, v194
	v_mov_b32_e32 v211, v159
	v_sub_f32_e32 v203, v241, v220
	v_sub_f32_e32 v202, v240, v220
	v_sub_f32_e32 v205, v243, v220
	v_sub_f32_e32 v204, v242, v220
	v_pk_mul_f32 v[204:205], v[220:221], v[204:205] op_sel:[1,0]
	v_pk_mul_f32 v[202:203], v[220:221], v[202:203] op_sel:[1,0]
	v_pk_fma_f32 v[204:205], v[206:207], v[204:205], v[26:27]
	v_pk_fma_f32 v[202:203], v[208:209], v[202:203], v[24:25]
	v_pk_fma_f32 v[204:205], v[130:131], s[78:79], v[204:205] op_sel_hi:[1,0,1]
	v_pk_fma_f32 v[202:203], v[128:129], s[78:79], v[202:203] op_sel_hi:[1,0,1]
	v_lshl_add_u64 v[210:211], v[210:211], 2, s[90:91]
	global_store_dwordx4 v[210:211], v[202:205], off
	v_sub_f32_e32 v149, v149, v198
	v_sub_f32_e32 v148, v148, v198
	v_sub_f32_e32 v203, v245, v200
	v_sub_f32_e32 v202, v244, v200
	v_sub_f32_e32 v141, v141, v196
	v_sub_f32_e32 v140, v140, v196
	v_sub_f32_e32 v205, v247, v200
	v_sub_f32_e32 v204, v246, v200
	v_pk_mul_f32 v[202:203], v[200:201], v[202:203] op_sel:[1,0]
	v_sub_f32_e32 v151, v151, v198
	v_sub_f32_e32 v150, v150, v198
	v_pk_mul_f32 v[148:149], v[198:199], v[148:149] op_sel:[1,0]
	v_sub_f32_e32 v143, v143, v196
	v_sub_f32_e32 v142, v142, v196
	v_pk_mul_f32 v[140:141], v[196:197], v[140:141] op_sel:[1,0]
	v_pk_mul_f32 v[204:205], v[200:201], v[204:205] op_sel:[1,0]
	v_pk_fma_f32 v[202:203], v[214:215], v[202:203], v[20:21]
	v_sub_f32_e32 v153, v153, v200
	v_sub_f32_e32 v152, v152, v200
	v_sub_f32_e32 v155, v155, v200
	v_sub_f32_e32 v154, v154, v200
	v_pk_mul_f32 v[150:151], v[198:199], v[150:151] op_sel:[1,0]
	v_pk_fma_f32 v[148:149], v[214:215], v[148:149], v[12:13]
	v_pk_mul_f32 v[142:143], v[196:197], v[142:143] op_sel:[1,0]
	v_pk_fma_f32 v[140:141], v[214:215], v[140:141], v[4:5]
	v_pk_fma_f32 v[204:205], v[212:213], v[204:205], v[22:23]
	v_pk_fma_f32 v[202:203], v[132:133], s[78:79], v[202:203] op_sel_hi:[1,0,1]
	v_pk_mul_f32 v[154:155], v[200:201], v[154:155] op_sel:[1,0]
	v_pk_mul_f32 v[152:153], v[200:201], v[152:153] op_sel:[1,0]
	v_pk_fma_f32 v[150:151], v[212:213], v[150:151], v[14:15]
	v_pk_fma_f32 v[148:149], v[132:133], s[78:79], v[148:149] op_sel_hi:[1,0,1]
	v_pk_fma_f32 v[142:143], v[212:213], v[142:143], v[6:7]
	v_pk_fma_f32 v[132:133], v[132:133], s[78:79], v[140:141] op_sel_hi:[1,0,1]
	v_add_u32_e32 v140, 0x58080, v194
	v_mov_b32_e32 v141, v159
	v_pk_fma_f32 v[204:205], v[134:135], s[78:79], v[204:205] op_sel_hi:[1,0,1]
	v_pk_fma_f32 v[152:153], v[208:209], v[152:153], v[16:17]
	v_pk_fma_f32 v[154:155], v[206:207], v[154:155], v[18:19]
	v_add_u32_e32 v200, 0x48090, v194
	v_mov_b32_e32 v201, v159
	v_pk_fma_f32 v[150:151], v[134:135], s[78:79], v[150:151] op_sel_hi:[1,0,1]
	v_pk_fma_f32 v[134:135], v[134:135], s[78:79], v[142:143] op_sel_hi:[1,0,1]
	v_lshl_add_u64 v[140:141], v[140:141], 2, s[90:91]
	v_pk_fma_f32 v[154:155], v[130:131], s[78:79], v[154:155] op_sel_hi:[1,0,1]
	v_pk_fma_f32 v[152:153], v[128:129], s[78:79], v[152:153] op_sel_hi:[1,0,1]
	v_lshl_add_u64 v[200:201], v[200:201], 2, s[90:91]
	v_sub_f32_e32 v145, v145, v198
	v_sub_f32_e32 v144, v144, v198
	global_store_dwordx4 v[140:141], v[132:135], off
	global_store_dwordx4 v[200:201], v[152:155], off
	v_sub_f32_e32 v147, v147, v198
	v_sub_f32_e32 v133, v137, v196
	v_sub_f32_e32 v132, v136, v196
	v_add_u32_e32 v152, 0x50080, v194
	v_mov_b32_e32 v153, v159
	v_sub_f32_e32 v146, v146, v198
	v_pk_mul_f32 v[144:145], v[198:199], v[144:145] op_sel:[1,0]
	v_sub_f32_e32 v135, v139, v196
	v_sub_f32_e32 v134, v138, v196
	v_pk_mul_f32 v[132:133], v[196:197], v[132:133] op_sel:[1,0]
	v_lshl_add_u64 v[152:153], v[152:153], 2, s[90:91]
	v_pk_mul_f32 v[146:147], v[198:199], v[146:147] op_sel:[1,0]
	v_pk_fma_f32 v[144:145], v[208:209], v[144:145], v[8:9]
	v_pk_mul_f32 v[134:135], v[196:197], v[134:135] op_sel:[1,0]
	v_pk_fma_f32 v[132:133], v[208:209], v[132:133], v[0:1]
	v_add_u32_e32 v210, 0x48080, v194
	v_mov_b32_e32 v211, v159
	global_store_dwordx4 v[152:153], v[148:151], off
	v_pk_fma_f32 v[146:147], v[206:207], v[146:147], v[10:11]
	v_pk_fma_f32 v[144:145], v[128:129], s[78:79], v[144:145] op_sel_hi:[1,0,1]
	v_add_u32_e32 v148, 0x50090, v194
	v_mov_b32_e32 v149, v159
	v_pk_fma_f32 v[134:135], v[206:207], v[134:135], v[2:3]
	v_pk_fma_f32 v[128:129], v[128:129], s[78:79], v[132:133] op_sel_hi:[1,0,1]
	v_add_u32_e32 v132, 0x58090, v194
	v_mov_b32_e32 v133, v159
	v_lshl_add_u64 v[210:211], v[210:211], 2, s[90:91]
	v_pk_fma_f32 v[146:147], v[130:131], s[78:79], v[146:147] op_sel_hi:[1,0,1]
	v_lshl_add_u64 v[148:149], v[148:149], 2, s[90:91]
	v_pk_fma_f32 v[130:131], v[130:131], s[78:79], v[134:135] op_sel_hi:[1,0,1]
	v_lshl_add_u64 v[132:133], v[132:133], 2, s[90:91]
	global_store_dwordx4 v[210:211], v[202:205], off
	global_store_dwordx4 v[148:149], v[144:147], off
	global_store_dwordx4 v[132:133], v[128:131], off
	s_mov_b64 s[20:21], 0
	s_branch .LBB0_81

; #define PG8_STAGE(bufoff, gbase) do { _Pragma("unroll") for (int _i = 0; _i < 2; ++_i) \
;         __builtin_amdgcn_global_load_lds((const unsigned*)((const char*)(gbase) + voff[_i]), (LAS unsigned*)(lds + (bufoff) + ldsw + _i * 8192), 16, 0, 0); } while (0)
; #define PG8_LDA(dst, b, h) do { _Pragma("unroll") for (int m = 0; m < 4; ++m) _Pragma("unroll") for (int k = 0; k < 2; ++k) dst[m][k] = *(const LAS bf16x8*)(lds + PG8_SA(b, h) + aoff + m * 2048 + k * 1024); } while (0)
; #define PG8_LDB(dst, b, h) do { _Pragma("unroll") for (int n = 0; n < 2; ++n) _Pragma("unroll") for (int k = 0; k < 2; ++k) dst[n][k] = *(const LAS bf16x8*)(lds + PG8_SB(b, h) + boff + n * 2048 + k * 1024); } while (0)
; #define PG8_MMA(ai, bj, At, Bt) do { __builtin_amdgcn_s_setprio(1); _Pragma("unroll") for (int m = 0; m < 4; ++m) _Pragma("unroll") for (int n = 0; n < 2; ++n) _Pragma("unroll") for (int k = 0; k < 2; ++k) \
;         acc[ai][bj][m][n] = __builtin_amdgcn_mfma_f32_16x16x32_bf16(Bt[n][k], At[m][k], acc[ai][bj][m][n], 0, 0, 0); __builtin_amdgcn_s_setprio(0); } while (0)
; #define PG8_WAIT_V(n) asm volatile("s_waitcnt vmcnt(" #n ")" ::: "memory")
; #define PG8_WAIT_L(n) asm volatile("s_waitcnt lgkmcnt(" #n ")" ::: "memory")
; #define PG8_BAR __builtin_amdgcn_s_barrier()
; #define PG8_SCHED __builtin_amdgcn_sched_barrier(0)
; template <class Epi>
; DI void gemm_phase(LAS unsigned char* lds, const Gemm g, const StaticOrder& S, const Epi& E) {
;     ...
;         for (int t = 0; t < nt; t += 2) {
;             const bool last = (t == nt - 2);
;             const char* a1 = cA + (size_t)(t + 1) * kstep;
;             const char* a2 = last ? nA : cA + (size_t)(t + 2) * kstep; const char* b2 = last ? nB : cB + (size_t)(t + 2) * kstep;
;             const char* a3 = a2 + kstep; const char* b3 = b2 + kstep;
;             PG8_LDB(B0, 0, 0); PG8_SCHED; PG8_LDA(At, 0, 0); PG8_STAGE(PG8_SA(1, 1), a1 + hstep);
;             PG8_WAIT_L(8); PG8_BAR; PG8_WAIT_L(0); PG8_MMA(0, 0, At, B0); PG8_BAR; PG8_SCHED;
;             PG8_LDB(B1, 0, 1); PG8_STAGE(PG8_SB(0, 0), b2);
;             PG8_BAR; PG8_WAIT_L(0); PG8_MMA(0, 1, At, B1); PG8_BAR;
;             PG8_LDA(At, 0, 1); PG8_STAGE(PG8_SA(0, 0), a2);
;             PG8_BAR; PG8_WAIT_L(0); PG8_MMA(1, 0, At, B0); PG8_BAR; PG8_SCHED;
;             PG8_STAGE(PG8_SB(0, 1), b2 + hstep);
;             PG8_WAIT_V(6); PG8_BAR; PG8_MMA(1, 1, At, B1); PG8_BAR;
.LBB0_134:
	s_add_u32 s18, s16, 0x100
	s_addc_u32 s19, s17, 0
	s_add_i32 s39, 0, 0x10000
	v_add_u32_e32 v148, s39, v199
	ds_read_b128 v[96:99], v148
	ds_read_b128 v[100:103], v148 offset:1024
	ds_read_b128 v[136:139], v148 offset:2048
	ds_read_b128 v[148:151], v148 offset:3072
	s_cmpk_eq_i32 s33, 0x54
	s_cselect_b32 s23, s9, s19
	s_cselect_b32 s22, s8, s18
	s_cselect_b32 s21, s11, s5
	s_cselect_b32 s20, s10, s4
	v_lshl_add_u64 v[218:219], s[16:17], 0, v[144:145]
	s_add_i32 m0, s28, 0xc000
	ds_read_b128 v[152:155], v201
	ds_read_b128 v[186:189], v201 offset:1024
	ds_read_b128 v[190:193], v201 offset:2048
	ds_read_b128 v[194:197], v201 offset:3072
	ds_read_b128 v[202:205], v201 offset:4096
	ds_read_b128 v[206:209], v201 offset:5120
	ds_read_b128 v[210:213], v201 offset:6144
	ds_read_b128 v[214:217], v201 offset:7168
	global_load_lds_dwordx4 v[218:219], off
	v_lshl_add_u64 v[218:219], s[16:17], 0, v[146:147]
	s_add_i32 m0, s28, 0xe000
	s_nop 0
	global_load_lds_dwordx4 v[218:219], off
	s_waitcnt lgkmcnt(8)
	s_setprio 1
	s_barrier
	s_waitcnt lgkmcnt(0)
	v_mfma_f32_16x16x32_bf16 v[132:135], v[96:99], v[152:155], v[132:135]
	v_mfma_f32_16x16x32_bf16 v[128:131], v[136:139], v[152:155], v[128:131]
	v_mfma_f32_16x16x32_bf16 v[124:127], v[96:99], v[190:193], v[124:127]
	v_mfma_f32_16x16x32_bf16 v[120:123], v[136:139], v[190:193], v[120:123]
	v_mfma_f32_16x16x32_bf16 v[116:119], v[96:99], v[202:205], v[116:119]
	v_mfma_f32_16x16x32_bf16 v[112:115], v[136:139], v[202:205], v[112:115]
	v_mfma_f32_16x16x32_bf16 v[108:111], v[96:99], v[210:213], v[108:111]
	v_mfma_f32_16x16x32_bf16 v[104:107], v[136:139], v[210:213], v[104:107]
	v_mfma_f32_16x16x32_bf16 v[132:135], v[100:103], v[186:189], v[132:135]
	v_mfma_f32_16x16x32_bf16 v[128:131], v[148:151], v[186:189], v[128:131]
	v_mfma_f32_16x16x32_bf16 v[124:127], v[100:103], v[194:197], v[124:127]
	v_mfma_f32_16x16x32_bf16 v[120:123], v[148:151], v[194:197], v[120:123]
	s_add_i32 s40, 0, 0x14000
	s_add_i32 s16, s39, s27
	v_add_u32_e32 v158, s40, v199
	v_lshl_add_u64 v[218:219], s[20:21], 0, v[142:143]
	s_mov_b32 m0, s16
	v_mfma_f32_16x16x32_bf16 v[116:119], v[100:103], v[206:209], v[116:119]
	v_mfma_f32_16x16x32_bf16 v[112:115], v[148:151], v[206:209], v[112:115]
	v_mfma_f32_16x16x32_bf16 v[108:111], v[100:103], v[214:217], v[108:111]
	v_mfma_f32_16x16x32_bf16 v[104:107], v[148:151], v[214:217], v[104:107]
	s_setprio 0
	s_barrier
	ds_read_b128 v[226:229], v158
	ds_read_b128 v[230:233], v158 offset:1024
	ds_read_b128 v[234:237], v158 offset:2048
	ds_read_b128 v[238:241], v158 offset:3072
	global_load_lds_dwordx4 v[218:219], off
	v_lshl_add_u64 v[220:221], s[20:21], 0, v[140:141]
	s_add_i32 m0, s16, 0x2000
	s_nop 0
	global_load_lds_dwordx4 v[220:221], off
	s_waitcnt lgkmcnt(0)
	s_setprio 1
	s_barrier
	v_mfma_f32_16x16x32_bf16 v[60:63], v[226:229], v[152:155], v[60:63]
	v_mfma_f32_16x16x32_bf16 v[56:59], v[234:237], v[152:155], v[56:59]
	v_mfma_f32_16x16x32_bf16 v[52:55], v[226:229], v[190:193], v[52:55]
	v_mfma_f32_16x16x32_bf16 v[48:51], v[234:237], v[190:193], v[48:51]
	v_mfma_f32_16x16x32_bf16 v[44:47], v[226:229], v[202:205], v[44:47]
	v_mfma_f32_16x16x32_bf16 v[40:43], v[234:237], v[202:205], v[40:43]
	v_mfma_f32_16x16x32_bf16 v[36:39], v[226:229], v[210:213], v[36:39]
	v_mfma_f32_16x16x32_bf16 v[32:35], v[234:237], v[210:213], v[32:35]
	v_mfma_f32_16x16x32_bf16 v[60:63], v[230:233], v[186:189], v[60:63]
	v_mfma_f32_16x16x32_bf16 v[56:59], v[238:241], v[186:189], v[56:59]
	v_mfma_f32_16x16x32_bf16 v[52:55], v[230:233], v[194:197], v[52:55]
	v_mfma_f32_16x16x32_bf16 v[48:51], v[238:241], v[194:197], v[48:51]
	s_mov_b32 m0, s28
	v_lshl_add_u64 v[242:243], s[22:23], 0, v[142:143]
	v_mfma_f32_16x16x32_bf16 v[44:47], v[230:233], v[206:209], v[44:47]
	v_mfma_f32_16x16x32_bf16 v[40:43], v[238:241], v[206:209], v[40:43]
	v_mfma_f32_16x16x32_bf16 v[36:39], v[230:233], v[214:217], v[36:39]
	v_mfma_f32_16x16x32_bf16 v[32:35], v[238:241], v[214:217], v[32:35]
	s_setprio 0
	s_barrier
	ds_read_b128 v[152:155], v201 offset:16384
	ds_read_b128 v[186:189], v201 offset:17408
	ds_read_b128 v[190:193], v201 offset:18432
	ds_read_b128 v[194:197], v201 offset:19456
	ds_read_b128 v[202:205], v201 offset:20480
	ds_read_b128 v[206:209], v201 offset:21504
	ds_read_b128 v[210:213], v201 offset:22528
	ds_read_b128 v[214:217], v201 offset:23552
	global_load_lds_dwordx4 v[242:243], off
	v_lshl_add_u64 v[244:245], s[22:23], 0, v[140:141]
	s_mov_b32 m0, s29
	s_nop 0
	global_load_lds_dwordx4 v[244:245], off
	s_waitcnt lgkmcnt(0)
	s_setprio 1
	s_barrier
	v_mfma_f32_16x16x32_bf16 v[92:95], v[96:99], v[152:155], v[92:95]
	v_mfma_f32_16x16x32_bf16 v[88:91], v[136:139], v[152:155], v[88:91]
	v_mfma_f32_16x16x32_bf16 v[84:87], v[96:99], v[190:193], v[84:87]
	v_mfma_f32_16x16x32_bf16 v[80:83], v[136:139], v[190:193], v[80:83]
	v_mfma_f32_16x16x32_bf16 v[76:79], v[96:99], v[202:205], v[76:79]
	v_mfma_f32_16x16x32_bf16 v[72:75], v[136:139], v[202:205], v[72:75]
	v_mfma_f32_16x16x32_bf16 v[68:71], v[96:99], v[210:213], v[68:71]
	v_mfma_f32_16x16x32_bf16 v[64:67], v[136:139], v[210:213], v[64:67]
	v_mfma_f32_16x16x32_bf16 v[92:95], v[100:103], v[186:189], v[92:95]
	v_mfma_f32_16x16x32_bf16 v[88:91], v[148:151], v[186:189], v[88:91]
	v_mfma_f32_16x16x32_bf16 v[84:87], v[100:103], v[194:197], v[84:87]
	v_mfma_f32_16x16x32_bf16 v[80:83], v[148:151], v[194:197], v[80:83]
	s_add_u32 s16, s20, 0x160000
	s_addc_u32 s17, s21, 0
	s_add_i32 s39, s40, s27
	v_lshl_add_u64 v[96:97], s[16:17], 0, v[142:143]
	s_mov_b32 m0, s39
	v_mfma_f32_16x16x32_bf16 v[76:79], v[100:103], v[206:209], v[76:79]
	v_mfma_f32_16x16x32_bf16 v[72:75], v[148:151], v[206:209], v[72:75]
	v_mfma_f32_16x16x32_bf16 v[68:71], v[100:103], v[214:217], v[68:71]
	v_mfma_f32_16x16x32_bf16 v[64:67], v[148:151], v[214:217], v[64:67]
	s_setprio 0
	s_barrier
; #define PG8_STAGE(bufoff, gbase) do { _Pragma("unroll") for (int _i = 0; _i < 2; ++_i) \
;         __builtin_amdgcn_global_load_lds((const unsigned*)((const char*)(gbase) + voff[_i]), (LAS unsigned*)(lds + (bufoff) + ldsw + _i * 8192), 16, 0, 0); } while (0)
; #define PG8_LDA(dst, b, h) do { _Pragma("unroll") for (int m = 0; m < 4; ++m) _Pragma("unroll") for (int k = 0; k < 2; ++k) dst[m][k] = *(const LAS bf16x8*)(lds + PG8_SA(b, h) + aoff + m * 2048 + k * 1024); } while (0)
; #define PG8_LDB(dst, b, h) do { _Pragma("unroll") for (int n = 0; n < 2; ++n) _Pragma("unroll") for (int k = 0; k < 2; ++k) dst[n][k] = *(const LAS bf16x8*)(lds + PG8_SB(b, h) + boff + n * 2048 + k * 1024); } while (0)
; #define PG8_MMA(ai, bj, At, Bt) do { __builtin_amdgcn_s_setprio(1); _Pragma("unroll") for (int m = 0; m < 4; ++m) _Pragma("unroll") for (int n = 0; n < 2; ++n) _Pragma("unroll") for (int k = 0; k < 2; ++k) \
;         acc[ai][bj][m][n] = __builtin_amdgcn_mfma_f32_16x16x32_bf16(Bt[n][k], At[m][k], acc[ai][bj][m][n], 0, 0, 0); __builtin_amdgcn_s_setprio(0); } while (0)
; #define PG8_WAIT_V(n) asm volatile("s_waitcnt vmcnt(" #n ")" ::: "memory")
; #define PG8_WAIT_L(n) asm volatile("s_waitcnt lgkmcnt(" #n ")" ::: "memory")
; #define PG8_BAR __builtin_amdgcn_s_barrier()
; #define PG8_SCHED __builtin_amdgcn_sched_barrier(0)
; template <class Epi>
; DI void gemm_phase(LAS unsigned char* lds, const Gemm g, const StaticOrder& S, const Epi& E) {
;     ...
;             PG8_BAR; PG8_WAIT_L(0); PG8_MMA(1, 0, At, B0); PG8_BAR; PG8_SCHED;
;             PG8_STAGE(PG8_SB(0, 1), b2 + hstep);
;             PG8_WAIT_V(6); PG8_BAR; PG8_MMA(1, 1, At, B1); PG8_BAR;
;             PG8_LDB(B0, 1, 0); PG8_SCHED; PG8_LDA(At, 1, 0); PG8_STAGE(PG8_SA(0, 1), a2 + hstep);
;             PG8_WAIT_L(8); PG8_BAR; PG8_WAIT_L(0); PG8_MMA(0, 0, At, B0); PG8_BAR; PG8_SCHED;
;             PG8_LDB(B1, 1, 1); PG8_STAGE(PG8_SB(1, 0), b3);
;             PG8_BAR; PG8_WAIT_L(0); PG8_MMA(0, 1, At, B1); PG8_BAR;
;             PG8_LDA(At, 1, 1); PG8_STAGE(PG8_SA(1, 0), a3);
;             PG8_BAR; PG8_WAIT_L(0); PG8_MMA(1, 0, At, B0); PG8_BAR; PG8_SCHED;
	s_nop 0
	global_load_lds_dwordx4 v[96:97], off
	v_lshl_add_u64 v[96:97], s[16:17], 0, v[140:141]
	s_add_i32 m0, s39, 0x2000
	s_nop 0
	global_load_lds_dwordx4 v[96:97], off
	s_waitcnt vmcnt(6)
	s_setprio 1
	s_barrier
	v_mfma_f32_16x16x32_bf16 v[28:31], v[226:229], v[152:155], v[28:31]
	v_mfma_f32_16x16x32_bf16 v[24:27], v[234:237], v[152:155], v[24:27]
	v_mfma_f32_16x16x32_bf16 v[20:23], v[226:229], v[190:193], v[20:23]
	v_mfma_f32_16x16x32_bf16 v[16:19], v[234:237], v[190:193], v[16:19]
	v_mfma_f32_16x16x32_bf16 v[12:15], v[226:229], v[202:205], v[12:15]
	v_mfma_f32_16x16x32_bf16 v[8:11], v[234:237], v[202:205], v[8:11]
	v_mfma_f32_16x16x32_bf16 v[4:7], v[226:229], v[210:213], v[4:7]
	v_mfma_f32_16x16x32_bf16 v[0:3], v[234:237], v[210:213], v[0:3]
	v_mfma_f32_16x16x32_bf16 v[28:31], v[230:233], v[186:189], v[28:31]
	v_mfma_f32_16x16x32_bf16 v[24:27], v[238:241], v[186:189], v[24:27]
	v_mfma_f32_16x16x32_bf16 v[20:23], v[230:233], v[194:197], v[20:23]
	v_mfma_f32_16x16x32_bf16 v[16:19], v[238:241], v[194:197], v[16:19]
	s_add_i32 s39, 0, 0x18000
	v_add_u32_e32 v148, s39, v199
	v_mfma_f32_16x16x32_bf16 v[12:15], v[230:233], v[206:209], v[12:15]
	v_mfma_f32_16x16x32_bf16 v[8:11], v[238:241], v[206:209], v[8:11]
	v_mfma_f32_16x16x32_bf16 v[4:7], v[230:233], v[214:217], v[4:7]
	v_mfma_f32_16x16x32_bf16 v[0:3], v[238:241], v[214:217], v[0:3]
	s_setprio 0
	s_barrier
	ds_read_b128 v[96:99], v148
	ds_read_b128 v[100:103], v148 offset:1024
	ds_read_b128 v[136:139], v148 offset:2048
	ds_read_b128 v[148:151], v148 offset:3072
	s_add_u32 s16, s22, 0x160000
	s_addc_u32 s17, s23, 0
	s_mov_b32 m0, s30
	v_lshl_add_u64 v[226:227], s[16:17], 0, v[142:143]
	ds_read_b128 v[152:155], v201 offset:32768
	ds_read_b128 v[186:189], v201 offset:33792
	ds_read_b128 v[190:193], v201 offset:34816
	ds_read_b128 v[194:197], v201 offset:35840
	ds_read_b128 v[202:205], v201 offset:36864
	ds_read_b128 v[206:209], v201 offset:37888
	ds_read_b128 v[210:213], v201 offset:38912
	ds_read_b128 v[214:217], v201 offset:39936
	global_load_lds_dwordx4 v[226:227], off
	v_lshl_add_u64 v[226:227], s[16:17], 0, v[140:141]
	s_mov_b32 m0, s31
	s_nop 0
	global_load_lds_dwordx4 v[226:227], off
	s_waitcnt lgkmcnt(8)
	s_setprio 1
	s_barrier
	s_waitcnt lgkmcnt(0)
	v_mfma_f32_16x16x32_bf16 v[132:135], v[96:99], v[152:155], v[132:135]
	v_mfma_f32_16x16x32_bf16 v[128:131], v[136:139], v[152:155], v[128:131]
	v_mfma_f32_16x16x32_bf16 v[124:127], v[96:99], v[190:193], v[124:127]
	v_mfma_f32_16x16x32_bf16 v[120:123], v[136:139], v[190:193], v[120:123]
	v_mfma_f32_16x16x32_bf16 v[116:119], v[96:99], v[202:205], v[116:119]
	v_mfma_f32_16x16x32_bf16 v[112:115], v[136:139], v[202:205], v[112:115]
	v_mfma_f32_16x16x32_bf16 v[108:111], v[96:99], v[210:213], v[108:111]
	v_mfma_f32_16x16x32_bf16 v[104:107], v[136:139], v[210:213], v[104:107]
	v_mfma_f32_16x16x32_bf16 v[132:135], v[100:103], v[186:189], v[132:135]
	v_mfma_f32_16x16x32_bf16 v[128:131], v[148:151], v[186:189], v[128:131]
	v_mfma_f32_16x16x32_bf16 v[124:127], v[100:103], v[194:197], v[124:127]
	v_mfma_f32_16x16x32_bf16 v[120:123], v[148:151], v[194:197], v[120:123]
	s_add_i32 s22, 0, 0x1c000
	s_add_i32 s16, s39, s27
	v_add_u32_e32 v158, s22, v199
	v_lshl_add_u64 v[218:219], v[218:219], 0, s[94:95]
	s_mov_b32 m0, s16
	v_mfma_f32_16x16x32_bf16 v[116:119], v[100:103], v[206:209], v[116:119]
	v_mfma_f32_16x16x32_bf16 v[112:115], v[148:151], v[206:209], v[112:115]
	v_mfma_f32_16x16x32_bf16 v[108:111], v[100:103], v[214:217], v[108:111]
	v_mfma_f32_16x16x32_bf16 v[104:107], v[148:151], v[214:217], v[104:107]
	s_setprio 0
	s_barrier
	ds_read_b128 v[226:229], v158
	ds_read_b128 v[230:233], v158 offset:1024
	ds_read_b128 v[234:237], v158 offset:2048
	ds_read_b128 v[238:241], v158 offset:3072
	global_load_lds_dwordx4 v[218:219], off
	v_lshl_add_u64 v[218:219], v[220:221], 0, s[94:95]
	s_add_i32 m0, s16, 0x2000
	s_nop 0
	global_load_lds_dwordx4 v[218:219], off
	s_waitcnt lgkmcnt(0)
	s_setprio 1
	s_barrier
	v_mfma_f32_16x16x32_bf16 v[60:63], v[226:229], v[152:155], v[60:63]
	v_mfma_f32_16x16x32_bf16 v[56:59], v[234:237], v[152:155], v[56:59]
	v_mfma_f32_16x16x32_bf16 v[52:55], v[226:229], v[190:193], v[52:55]
	v_mfma_f32_16x16x32_bf16 v[48:51], v[234:237], v[190:193], v[48:51]
	v_mfma_f32_16x16x32_bf16 v[44:47], v[226:229], v[202:205], v[44:47]
	v_mfma_f32_16x16x32_bf16 v[40:43], v[234:237], v[202:205], v[40:43]
	v_mfma_f32_16x16x32_bf16 v[36:39], v[226:229], v[210:213], v[36:39]
	v_mfma_f32_16x16x32_bf16 v[32:35], v[234:237], v[210:213], v[32:35]
	v_mfma_f32_16x16x32_bf16 v[60:63], v[230:233], v[186:189], v[60:63]
	v_mfma_f32_16x16x32_bf16 v[56:59], v[238:241], v[186:189], v[56:59]
	v_mfma_f32_16x16x32_bf16 v[52:55], v[230:233], v[194:197], v[52:55]
	v_mfma_f32_16x16x32_bf16 v[48:51], v[238:241], v[194:197], v[48:51]
	s_mov_b32 m0, s34
	v_lshl_add_u64 v[218:219], v[242:243], 0, s[94:95]
	v_mfma_f32_16x16x32_bf16 v[44:47], v[230:233], v[206:209], v[44:47]
	v_mfma_f32_16x16x32_bf16 v[40:43], v[238:241], v[206:209], v[40:43]
	v_mfma_f32_16x16x32_bf16 v[36:39], v[230:233], v[214:217], v[36:39]
	v_mfma_f32_16x16x32_bf16 v[32:35], v[238:241], v[214:217], v[32:35]
	s_setprio 0
	s_barrier
	ds_read_b128 v[152:155], v201 offset:49152
	ds_read_b128 v[186:189], v201 offset:50176
	ds_read_b128 v[190:193], v201 offset:51200
	ds_read_b128 v[194:197], v201 offset:52224
	ds_read_b128 v[202:205], v201 offset:53248
	ds_read_b128 v[206:209], v201 offset:54272
	ds_read_b128 v[210:213], v201 offset:55296
	ds_read_b128 v[214:217], v201 offset:56320
	global_load_lds_dwordx4 v[218:219], off
	v_lshl_add_u64 v[218:219], v[244:245], 0, s[94:95]
	s_mov_b32 m0, s35
	s_nop 0
	global_load_lds_dwordx4 v[218:219], off
	s_waitcnt lgkmcnt(0)
	s_setprio 1
	s_barrier
; #define PG8_STAGE(bufoff, gbase) do { _Pragma("unroll") for (int _i = 0; _i < 2; ++_i) \
;         __builtin_amdgcn_global_load_lds((const unsigned*)((const char*)(gbase) + voff[_i]), (LAS unsigned*)(lds + (bufoff) + ldsw + _i * 8192), 16, 0, 0); } while (0)
; #define PG8_MMA(ai, bj, At, Bt) do { __builtin_amdgcn_s_setprio(1); _Pragma("unroll") for (int m = 0; m < 4; ++m) _Pragma("unroll") for (int n = 0; n < 2; ++n) _Pragma("unroll") for (int k = 0; k < 2; ++k) \
;         acc[ai][bj][m][n] = __builtin_amdgcn_mfma_f32_16x16x32_bf16(Bt[n][k], At[m][k], acc[ai][bj][m][n], 0, 0, 0); __builtin_amdgcn_s_setprio(0); } while (0)
; #define PG8_WAIT_V(n) asm volatile("s_waitcnt vmcnt(" #n ")" ::: "memory")
; #define PG8_WAIT_L(n) asm volatile("s_waitcnt lgkmcnt(" #n ")" ::: "memory")
; #define PG8_BAR __builtin_amdgcn_s_barrier()
; #define PG8_SCHED __builtin_amdgcn_sched_barrier(0)
; template <class Epi>
; DI void gemm_phase(LAS unsigned char* lds, const Gemm g, const StaticOrder& S, const Epi& E) {
;     ...
;             PG8_BAR; PG8_WAIT_L(0); PG8_MMA(1, 0, At, B0); PG8_BAR; PG8_SCHED;
;             PG8_STAGE(PG8_SB(1, 1), b3 + hstep);
;             PG8_WAIT_V(6); PG8_BAR; PG8_MMA(1, 1, At, B1); PG8_BAR;
;         }
;     template <bool LN, int BJ> DI void load_gb(unsigned col0, f32x4 (&gv)[2], f32x4 (&bv)[2]) const {
; #pragma unroll
;         for (int n = 0; n < 2; ++n) {
;             if (LN) { gv[n] = *(const f32x4*)(gam + col0 + BJ * HALF + n * 16) * ALPHA; bv[n] = *(const f32x4*)(bet + col0 + BJ * HALF + n * 16) * ALPHA; }
;             else { gv[n] = (f32x4){ALPHA, ALPHA, ALPHA, ALPHA}; bv[n] = (f32x4){0.f, 0.f, 0.f, 0.f}; }
;         }
;     }
;     template <bool LN> DI void run(const f32x4 (&acc)[2][2][4][2], const Unit& u, int wr, int wc, int fr, int fq) const {
;         const unsigned row0 = u.pm * BM + wr * 64 + fr, col0 = u.pn * BM + wc * 32 + 4 * fq;
;         f32x4 gv[2], bv[2];
;         load_gb<LN, 0>(col0, gv, bv);
;         batch<LN, 0, 0, 4>(acc, row0, col0, gv, bv);
;         batch<LN, 0, 4, 8>(acc, row0, col0, gv, bv);
;         batch<LN, 0, 8, 12>(acc, row0, col0, gv, bv);
	v_mfma_f32_16x16x32_bf16 v[92:95], v[96:99], v[152:155], v[92:95]
	v_mfma_f32_16x16x32_bf16 v[88:91], v[136:139], v[152:155], v[88:91]
	v_mfma_f32_16x16x32_bf16 v[84:87], v[96:99], v[190:193], v[84:87]
	v_mfma_f32_16x16x32_bf16 v[80:83], v[136:139], v[190:193], v[80:83]
	v_mfma_f32_16x16x32_bf16 v[76:79], v[96:99], v[202:205], v[76:79]
	v_mfma_f32_16x16x32_bf16 v[72:75], v[136:139], v[202:205], v[72:75]
	v_mfma_f32_16x16x32_bf16 v[68:71], v[96:99], v[210:213], v[68:71]
	v_mfma_f32_16x16x32_bf16 v[64:67], v[136:139], v[210:213], v[64:67]
	v_mfma_f32_16x16x32_bf16 v[92:95], v[100:103], v[186:189], v[92:95]
	v_mfma_f32_16x16x32_bf16 v[88:91], v[148:151], v[186:189], v[88:91]
	v_mfma_f32_16x16x32_bf16 v[84:87], v[100:103], v[194:197], v[84:87]
	v_mfma_f32_16x16x32_bf16 v[80:83], v[148:151], v[194:197], v[80:83]
	s_add_u32 s16, s20, 0x160080
	s_addc_u32 s17, s21, 0
	s_add_i32 s20, s22, s27
	v_lshl_add_u64 v[96:97], s[16:17], 0, v[142:143]
	s_mov_b32 m0, s20
	v_mfma_f32_16x16x32_bf16 v[76:79], v[100:103], v[206:209], v[76:79]
	v_mfma_f32_16x16x32_bf16 v[72:75], v[148:151], v[206:209], v[72:75]
	v_mfma_f32_16x16x32_bf16 v[68:71], v[100:103], v[214:217], v[68:71]
	v_mfma_f32_16x16x32_bf16 v[64:67], v[148:151], v[214:217], v[64:67]
	s_setprio 0
	s_barrier
	s_nop 0
	global_load_lds_dwordx4 v[96:97], off
	v_lshl_add_u64 v[96:97], s[16:17], 0, v[140:141]
	s_add_i32 m0, s20, 0x2000
	s_nop 0
	global_load_lds_dwordx4 v[96:97], off
	s_waitcnt vmcnt(6)
	s_setprio 1
	s_barrier
	v_mfma_f32_16x16x32_bf16 v[28:31], v[226:229], v[152:155], v[28:31]
	v_mfma_f32_16x16x32_bf16 v[24:27], v[234:237], v[152:155], v[24:27]
	v_mfma_f32_16x16x32_bf16 v[20:23], v[226:229], v[190:193], v[20:23]
	v_mfma_f32_16x16x32_bf16 v[16:19], v[234:237], v[190:193], v[16:19]
	v_mfma_f32_16x16x32_bf16 v[12:15], v[226:229], v[202:205], v[12:15]
	v_mfma_f32_16x16x32_bf16 v[8:11], v[234:237], v[202:205], v[8:11]
	v_mfma_f32_16x16x32_bf16 v[4:7], v[226:229], v[210:213], v[4:7]
	v_mfma_f32_16x16x32_bf16 v[0:3], v[234:237], v[210:213], v[0:3]
	v_mfma_f32_16x16x32_bf16 v[28:31], v[230:233], v[186:189], v[28:31]
	v_mfma_f32_16x16x32_bf16 v[24:27], v[238:241], v[186:189], v[24:27]
	v_mfma_f32_16x16x32_bf16 v[20:23], v[230:233], v[194:197], v[20:23]
	v_mfma_f32_16x16x32_bf16 v[16:19], v[238:241], v[194:197], v[16:19]
	s_add_i32 s33, s33, 2
	s_add_u32 s4, s4, 0x100
	s_addc_u32 s5, s5, 0
	s_cmpk_gt_u32 s33, 0x55
	s_mov_b64 s[16:17], s[18:19]
	v_mfma_f32_16x16x32_bf16 v[12:15], v[230:233], v[206:209], v[12:15]
	v_mfma_f32_16x16x32_bf16 v[8:11], v[238:241], v[206:209], v[8:11]
	v_mfma_f32_16x16x32_bf16 v[4:7], v[230:233], v[214:217], v[4:7]
	v_mfma_f32_16x16x32_bf16 v[0:3], v[238:241], v[214:217], v[0:3]
	s_setprio 0
	s_barrier
	s_cbranch_scc0 .LBB0_134
	v_lshl_or_b32 v158, s2, 8, v200
	v_lshlrev_b64 v[100:101], 2, v[158:159]
	v_lshl_add_u64 v[150:151], s[12:13], 0, v[100:101]
	global_load_dwordx4 v[96:99], v[150:151], off
	v_lshl_add_u64 v[152:153], s[14:15], 0, v[100:101]
	v_lshl_add_u32 v203, s3, 8, v198
	v_lshlrev_b32_e32 v202, 11, v203
	v_add_u32_e32 v148, v202, v158
	v_mov_b32_e32 v149, v159
	v_lshlrev_b32_e32 v136, 1, v203
	v_mov_b32_e32 v137, v159
	v_lshlrev_b64 v[220:221], 2, v[148:149]
	v_lshl_add_u64 v[154:155], v[136:137], 2, s[96:97]
	v_lshl_add_u64 v[136:137], s[90:91], 0, v[220:221]
	v_or_b32_e32 v204, 16, v158
	v_or_b32_e32 v138, 16, v203
	v_lshlrev_b32_e32 v149, 11, v138
	s_waitcnt vmcnt(0)
	v_pk_mul_f32 v[192:193], v[98:99], s[78:79] op_sel_hi:[1,0]
	v_pk_mul_f32 v[194:195], v[96:97], s[78:79] op_sel_hi:[1,0]
	global_load_dwordx4 v[100:103], v[152:153], off
	global_load_dwordx4 v[96:99], v[150:151], off offset:64
	global_load_dwordx2 v[218:219], v[154:155], off
	global_load_dwordx4 v[206:209], v[136:137], off
	v_add_u32_e32 v136, v202, v204
	v_mov_b32_e32 v137, v159
	v_lshl_add_u64 v[136:137], v[136:137], 2, s[90:91]
	global_load_dwordx4 v[210:213], v[136:137], off
	v_lshlrev_b32_e32 v136, 1, v138
	v_mov_b32_e32 v137, v159
	v_lshl_add_u64 v[186:187], v[136:137], 2, s[96:97]
	v_add_u32_e32 v136, v149, v158
	v_lshl_add_u64 v[136:137], v[136:137], 2, s[90:91]
	global_load_dwordx2 v[196:197], v[186:187], off
	global_load_dwordx4 v[214:217], v[136:137], off
	v_add_u32_e32 v136, v149, v204
	v_mov_b32_e32 v137, v159
	v_lshl_add_u64 v[136:137], v[136:137], 2, s[90:91]
	global_load_dwordx4 v[136:139], v[136:137], off
	s_waitcnt vmcnt(0)
	v_pk_mul_f32 v[188:189], v[98:99], s[78:79] op_sel_hi:[1,0]
	v_pk_mul_f32 v[190:191], v[96:97], s[78:79] op_sel_hi:[1,0]
	global_load_dwordx4 v[96:99], v[152:153], off offset:64
	v_sub_f32_e32 v207, v207, v218
	v_sub_f32_e32 v206, v206, v218
	v_sub_f32_e32 v209, v209, v218
	v_sub_f32_e32 v208, v208, v218
	v_pk_mul_f32 v[208:209], v[218:219], v[208:209] op_sel:[1,0]
	v_pk_mul_f32 v[206:207], v[218:219], v[206:207] op_sel:[1,0]
	v_pk_fma_f32 v[134:135], v[192:193], v[208:209], v[134:135]
	v_pk_fma_f32 v[132:133], v[194:195], v[206:207], v[132:133]
	v_pk_fma_f32 v[134:135], v[102:103], s[78:79], v[134:135] op_sel_hi:[1,0,1]
	v_pk_fma_f32 v[132:133], v[100:101], s[78:79], v[132:133] op_sel_hi:[1,0,1]
	v_lshl_add_u64 v[206:207], s[88:89], 0, v[220:221]
	global_store_dwordx4 v[206:207], v[132:135], off
	s_nop 1
	v_sub_f32_e32 v133, v211, v218
	v_sub_f32_e32 v132, v210, v218
	v_sub_f32_e32 v135, v213, v218
	v_sub_f32_e32 v134, v212, v218
	v_pk_mul_f32 v[134:135], v[218:219], v[134:135] op_sel:[1,0]
	v_pk_mul_f32 v[132:133], v[218:219], v[132:133] op_sel:[1,0]
	v_pk_fma_f32 v[130:131], v[188:189], v[134:135], v[130:131]
	v_pk_fma_f32 v[128:129], v[190:191], v[132:133], v[128:129]
	v_or_b32_e32 v132, 16, v148
	v_mov_b32_e32 v133, v159
	v_lshl_add_u64 v[132:133], v[132:133], 2, s[88:89]
	s_waitcnt vmcnt(0)
;     template <bool LN, int BJ, int LO, int HI> DI void batch(const f32x4 (&acc)[2][2][4][2], unsigned row0, unsigned col0, const f32x4 (&gv)[2], const f32x4 (&bv)[2]) const {
;         f32x4 r[HI - LO]; float mean[(HI - LO) / 2], rstd[(HI - LO) / 2];
; #pragma unroll
;         for (int i = LO; i < HI; ++i) { const int ai = i >> 3, m = (i >> 1) & 3, n = i & 1; const unsigned row = row0 + ai * HALF + m * 16;
;             if (n == 0) { mean[(i - LO) >> 1] = 0.f; rstd[(i - LO) >> 1] = 1.f;
;                 if (LN) { const float2 st = *(const float2*)(stats + row * 2u); mean[(i - LO) >> 1] = st.x; rstd[(i - LO) >> 1] = st.y; } }
;             r[i - LO] = *(const f32x4*)(src + (row * (unsigned)DM + col0 + BJ * HALF + n * 16)); }
; #pragma unroll
;         for (int i = LO; i < HI; ++i) { const int ai = i >> 3, m = (i >> 1) & 3, n = i & 1; const unsigned row = row0 + ai * HALF + m * 16;
;             *(f32x4*)(Y + (row * (unsigned)DM + col0 + BJ * HALF + n * 16)) = acc[ai][BJ][m][n] + ((r[i - LO] - mean[(i - LO) >> 1]) * rstd[(i - LO) >> 1]) * gv[n] + bv[n]; }
;         __builtin_amdgcn_sched_barrier(0);
;     }
;     template <bool LN, int BJ> DI void load_gb(unsigned col0, f32x4 (&gv)[2], f32x4 (&bv)[2]) const {
; #pragma unroll
;         for (int n = 0; n < 2; ++n) {
;             if (LN) { gv[n] = *(const f32x4*)(gam + col0 + BJ * HALF + n * 16) * ALPHA; bv[n] = *(const f32x4*)(bet + col0 + BJ * HALF + n * 16) * ALPHA; }
;             else { gv[n] = (f32x4){ALPHA, ALPHA, ALPHA, ALPHA}; bv[n] = (f32x4){0.f, 0.f, 0.f, 0.f}; }
;         }
;     }
;     template <bool LN> DI void run(const f32x4 (&acc)[2][2][4][2], const Unit& u, int wr, int wc, int fr, int fq) const {
;         const unsigned row0 = u.pm * BM + wr * 64 + fr, col0 = u.pn * BM + wc * 32 + 4 * fq;
;         f32x4 gv[2], bv[2];
;         load_gb<LN, 0>(col0, gv, bv);
;         batch<LN, 0, 0, 4>(acc, row0, col0, gv, bv);
;         batch<LN, 0, 4, 8>(acc, row0, col0, gv, bv);
;         batch<LN, 0, 8, 12>(acc, row0, col0, gv, bv);
;         batch<LN, 0, 12, 16>(acc, row0, col0, gv, bv);
;         load_gb<LN, 1>(col0, gv, bv);
;         batch<LN, 1, 0, 8>(acc, row0, col0, gv, bv);
;         batch<LN, 1, 8, 16>(acc, row0, col0, gv, bv);
	v_pk_fma_f32 v[130:131], v[98:99], s[78:79], v[130:131] op_sel_hi:[1,0,1]
	v_pk_fma_f32 v[128:129], v[96:97], s[78:79], v[128:129] op_sel_hi:[1,0,1]
	global_store_dwordx4 v[132:133], v[128:131], off
	s_nop 1
	v_sub_f32_e32 v129, v215, v196
	v_sub_f32_e32 v128, v214, v196
	v_sub_f32_e32 v131, v217, v196
	v_sub_f32_e32 v130, v216, v196
	v_pk_mul_f32 v[130:131], v[196:197], v[130:131] op_sel:[1,0]
	v_pk_mul_f32 v[128:129], v[196:197], v[128:129] op_sel:[1,0]
	v_pk_fma_f32 v[126:127], v[192:193], v[130:131], v[126:127]
	v_pk_fma_f32 v[124:125], v[194:195], v[128:129], v[124:125]
	v_add_u32_e32 v128, 0x8000, v148
	v_mov_b32_e32 v129, v159
	v_pk_fma_f32 v[126:127], v[102:103], s[78:79], v[126:127] op_sel_hi:[1,0,1]
	v_pk_fma_f32 v[124:125], v[100:101], s[78:79], v[124:125] op_sel_hi:[1,0,1]
	v_lshl_add_u64 v[128:129], v[128:129], 2, s[88:89]
	global_store_dwordx4 v[128:129], v[124:127], off
	s_nop 1
	v_sub_f32_e32 v125, v137, v196
	v_sub_f32_e32 v124, v136, v196
	v_sub_f32_e32 v127, v139, v196
	v_sub_f32_e32 v126, v138, v196
	v_pk_mul_f32 v[126:127], v[196:197], v[126:127] op_sel:[1,0]
	v_pk_mul_f32 v[124:125], v[196:197], v[124:125] op_sel:[1,0]
	v_pk_fma_f32 v[122:123], v[188:189], v[126:127], v[122:123]
	v_pk_fma_f32 v[120:121], v[190:191], v[124:125], v[120:121]
	v_add_u32_e32 v124, 0x8010, v148
	v_mov_b32_e32 v125, v159
	v_pk_fma_f32 v[122:123], v[98:99], s[78:79], v[122:123] op_sel_hi:[1,0,1]
	v_pk_fma_f32 v[120:121], v[96:97], s[78:79], v[120:121] op_sel_hi:[1,0,1]
	v_lshl_add_u64 v[124:125], v[124:125], 2, s[88:89]
	global_store_dwordx4 v[124:125], v[120:123], off
	s_nop 1
	v_or_b32_e32 v122, 32, v203
	v_lshlrev_b32_e32 v124, 11, v122
	v_lshlrev_b32_e32 v120, 1, v122
	v_mov_b32_e32 v121, v159
	v_add_u32_e32 v122, v124, v158
	v_mov_b32_e32 v123, v159
	v_lshl_add_u64 v[120:121], v[120:121], 2, s[96:97]
	v_lshl_add_u64 v[122:123], v[122:123], 2, s[90:91]
	global_load_dwordx2 v[138:139], v[120:121], off
	global_load_dwordx4 v[126:129], v[122:123], off
	v_add_u32_e32 v122, v124, v204
	v_mov_b32_e32 v123, v159
	v_lshl_add_u64 v[122:123], v[122:123], 2, s[90:91]
	global_load_dwordx4 v[130:133], v[122:123], off
	v_or_b32_e32 v125, 48, v203
	v_lshlrev_b32_e32 v122, 1, v125
	v_lshlrev_b32_e32 v125, 11, v125
	v_mov_b32_e32 v123, v159
	v_add_u32_e32 v134, v125, v158
	v_mov_b32_e32 v135, v159
	v_lshl_add_u64 v[122:123], v[122:123], 2, s[96:97]
	v_lshl_add_u64 v[134:135], v[134:135], 2, s[90:91]
	global_load_dwordx2 v[196:197], v[122:123], off
	v_add_u32_e32 v206, v125, v204
	global_load_dwordx4 v[134:137], v[134:135], off
	v_mov_b32_e32 v207, v159
	v_lshl_add_u64 v[206:207], v[206:207], 2, s[90:91]
	global_load_dwordx4 v[206:209], v[206:207], off
	s_waitcnt vmcnt(0)
	v_sub_f32_e32 v127, v127, v138
	v_sub_f32_e32 v126, v126, v138
	v_sub_f32_e32 v129, v129, v138
	v_sub_f32_e32 v128, v128, v138
	v_pk_mul_f32 v[128:129], v[138:139], v[128:129] op_sel:[1,0]
	v_pk_mul_f32 v[126:127], v[138:139], v[126:127] op_sel:[1,0]
	v_pk_fma_f32 v[118:119], v[192:193], v[128:129], v[118:119]
	v_pk_fma_f32 v[116:117], v[194:195], v[126:127], v[116:117]
	v_add_u32_e32 v126, 0x10000, v148
	v_mov_b32_e32 v127, v159
	v_pk_fma_f32 v[118:119], v[102:103], s[78:79], v[118:119] op_sel_hi:[1,0,1]
	v_pk_fma_f32 v[116:117], v[100:101], s[78:79], v[116:117] op_sel_hi:[1,0,1]
	v_lshl_add_u64 v[126:127], v[126:127], 2, s[88:89]
	global_store_dwordx4 v[126:127], v[116:119], off
	s_nop 1
	v_sub_f32_e32 v117, v131, v138
	v_sub_f32_e32 v116, v130, v138
	v_sub_f32_e32 v119, v133, v138
	v_sub_f32_e32 v118, v132, v138
	v_pk_mul_f32 v[118:119], v[138:139], v[118:119] op_sel:[1,0]
	v_pk_mul_f32 v[116:117], v[138:139], v[116:117] op_sel:[1,0]
	v_pk_fma_f32 v[114:115], v[188:189], v[118:119], v[114:115]
	v_pk_fma_f32 v[112:113], v[190:191], v[116:117], v[112:113]
	v_add_u32_e32 v116, 0x10010, v148
	v_mov_b32_e32 v117, v159
	v_pk_fma_f32 v[114:115], v[98:99], s[78:79], v[114:115] op_sel_hi:[1,0,1]
	v_pk_fma_f32 v[112:113], v[96:97], s[78:79], v[112:113] op_sel_hi:[1,0,1]
	v_lshl_add_u64 v[116:117], v[116:117], 2, s[88:89]
	global_store_dwordx4 v[116:117], v[112:115], off
	s_nop 1
	v_sub_f32_e32 v113, v135, v196
	v_sub_f32_e32 v112, v134, v196
	v_sub_f32_e32 v115, v137, v196
	v_sub_f32_e32 v114, v136, v196
	v_pk_mul_f32 v[114:115], v[196:197], v[114:115] op_sel:[1,0]
	v_pk_mul_f32 v[112:113], v[196:197], v[112:113] op_sel:[1,0]
	v_pk_fma_f32 v[110:111], v[192:193], v[114:115], v[110:111]
	v_pk_fma_f32 v[108:109], v[194:195], v[112:113], v[108:109]
	v_add_u32_e32 v112, 0x18000, v148
	v_mov_b32_e32 v113, v159
	v_pk_fma_f32 v[110:111], v[102:103], s[78:79], v[110:111] op_sel_hi:[1,0,1]
	v_pk_fma_f32 v[108:109], v[100:101], s[78:79], v[108:109] op_sel_hi:[1,0,1]
	v_lshl_add_u64 v[112:113], v[112:113], 2, s[88:89]
	global_store_dwordx4 v[112:113], v[108:111], off
	s_nop 1
	v_sub_f32_e32 v109, v207, v196
	v_sub_f32_e32 v108, v206, v196
	v_sub_f32_e32 v111, v209, v196
	v_sub_f32_e32 v110, v208, v196
	v_pk_mul_f32 v[110:111], v[196:197], v[110:111] op_sel:[1,0]
	v_pk_mul_f32 v[108:109], v[196:197], v[108:109] op_sel:[1,0]
	v_pk_fma_f32 v[106:107], v[188:189], v[110:111], v[106:107]
	v_pk_fma_f32 v[104:105], v[190:191], v[108:109], v[104:105]
	v_add_u32_e32 v108, 0x18010, v148
	v_mov_b32_e32 v109, v159
	v_pk_fma_f32 v[106:107], v[98:99], s[78:79], v[106:107] op_sel_hi:[1,0,1]
	v_pk_fma_f32 v[104:105], v[96:97], s[78:79], v[104:105] op_sel_hi:[1,0,1]
	v_lshl_add_u64 v[108:109], v[108:109], 2, s[88:89]
	global_store_dwordx4 v[108:109], v[104:107], off
	s_nop 1
	v_add_u32_e32 v106, 0x80, v203
	v_lshlrev_b32_e32 v114, 11, v106
	v_lshlrev_b32_e32 v104, 1, v106
	v_mov_b32_e32 v105, v159
	v_add_u32_e32 v106, v114, v158
	v_mov_b32_e32 v107, v159
	v_lshl_add_u64 v[104:105], v[104:105], 2, s[96:97]
	v_lshl_add_u64 v[106:107], v[106:107], 2, s[90:91]
	global_load_dwordx2 v[112:113], v[104:105], off
	global_load_dwordx4 v[108:111], v[106:107], off
	v_add_u32_e32 v106, v114, v204
	v_mov_b32_e32 v107, v159
	v_lshl_add_u64 v[106:107], v[106:107], 2, s[90:91]
	global_load_dwordx4 v[116:119], v[106:107], off
	v_add_u32_e32 v115, 0x90, v203
	v_lshlrev_b32_e32 v106, 1, v115
	v_lshlrev_b32_e32 v115, 11, v115
	v_mov_b32_e32 v107, v159
	v_add_u32_e32 v126, v115, v158
	v_mov_b32_e32 v127, v159
	v_lshl_add_u64 v[106:107], v[106:107], 2, s[96:97]
	v_lshl_add_u64 v[126:127], v[126:127], 2, s[90:91]
	global_load_dwordx2 v[134:135], v[106:107], off
	v_add_u32_e32 v130, v115, v204
	global_load_dwordx4 v[126:129], v[126:127], off
	v_mov_b32_e32 v131, v159
	v_lshl_add_u64 v[130:131], v[130:131], 2, s[90:91]
	global_load_dwordx4 v[130:133], v[130:131], off
	s_waitcnt vmcnt(0)
;     template <bool LN, int BJ, int LO, int HI> DI void batch(const f32x4 (&acc)[2][2][4][2], unsigned row0, unsigned col0, const f32x4 (&gv)[2], const f32x4 (&bv)[2]) const {
;         f32x4 r[HI - LO]; float mean[(HI - LO) / 2], rstd[(HI - LO) / 2];
; #pragma unroll
;         for (int i = LO; i < HI; ++i) { const int ai = i >> 3, m = (i >> 1) & 3, n = i & 1; const unsigned row = row0 + ai * HALF + m * 16;
;             if (n == 0) { mean[(i - LO) >> 1] = 0.f; rstd[(i - LO) >> 1] = 1.f;
;                 if (LN) { const float2 st = *(const float2*)(stats + row * 2u); mean[(i - LO) >> 1] = st.x; rstd[(i - LO) >> 1] = st.y; } }
;             r[i - LO] = *(const f32x4*)(src + (row * (unsigned)DM + col0 + BJ * HALF + n * 16)); }
; #pragma unroll
;         for (int i = LO; i < HI; ++i) { const int ai = i >> 3, m = (i >> 1) & 3, n = i & 1; const unsigned row = row0 + ai * HALF + m * 16;
;             *(f32x4*)(Y + (row * (unsigned)DM + col0 + BJ * HALF + n * 16)) = acc[ai][BJ][m][n] + ((r[i - LO] - mean[(i - LO) >> 1]) * rstd[(i - LO) >> 1]) * gv[n] + bv[n]; }
;         __builtin_amdgcn_sched_barrier(0);
;     }
;     template <bool LN, int BJ> DI void load_gb(unsigned col0, f32x4 (&gv)[2], f32x4 (&bv)[2]) const {
; #pragma unroll
;         for (int n = 0; n < 2; ++n) {
;             if (LN) { gv[n] = *(const f32x4*)(gam + col0 + BJ * HALF + n * 16) * ALPHA; bv[n] = *(const f32x4*)(bet + col0 + BJ * HALF + n * 16) * ALPHA; }
;             else { gv[n] = (f32x4){ALPHA, ALPHA, ALPHA, ALPHA}; bv[n] = (f32x4){0.f, 0.f, 0.f, 0.f}; }
;         }
;     }
;     template <bool LN> DI void run(const f32x4 (&acc)[2][2][4][2], const Unit& u, int wr, int wc, int fr, int fq) const {
;         const unsigned row0 = u.pm * BM + wr * 64 + fr, col0 = u.pn * BM + wc * 32 + 4 * fq;
;         f32x4 gv[2], bv[2];
;         load_gb<LN, 0>(col0, gv, bv);
;         batch<LN, 0, 0, 4>(acc, row0, col0, gv, bv);
;         batch<LN, 0, 4, 8>(acc, row0, col0, gv, bv);
;         batch<LN, 0, 8, 12>(acc, row0, col0, gv, bv);
;         batch<LN, 0, 12, 16>(acc, row0, col0, gv, bv);
;         load_gb<LN, 1>(col0, gv, bv);
;         batch<LN, 1, 0, 8>(acc, row0, col0, gv, bv);
;         batch<LN, 1, 8, 16>(acc, row0, col0, gv, bv);
	v_sub_f32_e32 v109, v109, v112
	v_sub_f32_e32 v108, v108, v112
	v_sub_f32_e32 v111, v111, v112
	v_sub_f32_e32 v110, v110, v112
	v_pk_mul_f32 v[110:111], v[112:113], v[110:111] op_sel:[1,0]
	v_pk_mul_f32 v[108:109], v[112:113], v[108:109] op_sel:[1,0]
	v_pk_fma_f32 v[94:95], v[192:193], v[110:111], v[94:95]
	v_pk_fma_f32 v[92:93], v[194:195], v[108:109], v[92:93]
	v_add_u32_e32 v108, 0x40000, v148
	v_mov_b32_e32 v109, v159
	v_pk_fma_f32 v[94:95], v[102:103], s[78:79], v[94:95] op_sel_hi:[1,0,1]
	v_pk_fma_f32 v[92:93], v[100:101], s[78:79], v[92:93] op_sel_hi:[1,0,1]
	v_lshl_add_u64 v[108:109], v[108:109], 2, s[88:89]
	global_store_dwordx4 v[108:109], v[92:95], off
	s_nop 1
	v_sub_f32_e32 v93, v117, v112
	v_sub_f32_e32 v92, v116, v112
	v_sub_f32_e32 v95, v119, v112
	v_sub_f32_e32 v94, v118, v112
	v_pk_mul_f32 v[94:95], v[112:113], v[94:95] op_sel:[1,0]
	v_pk_mul_f32 v[92:93], v[112:113], v[92:93] op_sel:[1,0]
	v_pk_fma_f32 v[90:91], v[188:189], v[94:95], v[90:91]
	v_pk_fma_f32 v[88:89], v[190:191], v[92:93], v[88:89]
	v_add_u32_e32 v92, 0x40010, v148
	v_mov_b32_e32 v93, v159
	v_pk_fma_f32 v[90:91], v[98:99], s[78:79], v[90:91] op_sel_hi:[1,0,1]
	v_pk_fma_f32 v[88:89], v[96:97], s[78:79], v[88:89] op_sel_hi:[1,0,1]
	v_lshl_add_u64 v[92:93], v[92:93], 2, s[88:89]
	global_store_dwordx4 v[92:93], v[88:91], off
	s_nop 1
	v_sub_f32_e32 v89, v127, v134
	v_sub_f32_e32 v88, v126, v134
	v_sub_f32_e32 v91, v129, v134
	v_sub_f32_e32 v90, v128, v134
	v_pk_mul_f32 v[90:91], v[134:135], v[90:91] op_sel:[1,0]
	v_pk_mul_f32 v[88:89], v[134:135], v[88:89] op_sel:[1,0]
	v_pk_fma_f32 v[86:87], v[192:193], v[90:91], v[86:87]
	v_pk_fma_f32 v[84:85], v[194:195], v[88:89], v[84:85]
	v_add_u32_e32 v88, 0x48000, v148
	v_mov_b32_e32 v89, v159
	v_pk_fma_f32 v[86:87], v[102:103], s[78:79], v[86:87] op_sel_hi:[1,0,1]
	v_pk_fma_f32 v[84:85], v[100:101], s[78:79], v[84:85] op_sel_hi:[1,0,1]
	v_lshl_add_u64 v[88:89], v[88:89], 2, s[88:89]
	global_store_dwordx4 v[88:89], v[84:87], off
	s_nop 1
	v_sub_f32_e32 v85, v131, v134
	v_sub_f32_e32 v84, v130, v134
	v_sub_f32_e32 v87, v133, v134
	v_sub_f32_e32 v86, v132, v134
	v_pk_mul_f32 v[86:87], v[134:135], v[86:87] op_sel:[1,0]
	v_pk_mul_f32 v[84:85], v[134:135], v[84:85] op_sel:[1,0]
	v_pk_fma_f32 v[82:83], v[188:189], v[86:87], v[82:83]
	v_pk_fma_f32 v[80:81], v[190:191], v[84:85], v[80:81]
	v_add_u32_e32 v84, 0x48010, v148
	v_mov_b32_e32 v85, v159
	v_pk_fma_f32 v[82:83], v[98:99], s[78:79], v[82:83] op_sel_hi:[1,0,1]
	v_pk_fma_f32 v[80:81], v[96:97], s[78:79], v[80:81] op_sel_hi:[1,0,1]
	v_lshl_add_u64 v[84:85], v[84:85], 2, s[88:89]
	global_store_dwordx4 v[84:85], v[80:83], off
	s_nop 1
	v_add_u32_e32 v82, 0xa0, v203
	v_lshlrev_b32_e32 v80, 1, v82
	v_mov_b32_e32 v81, v159
	v_lshlrev_b32_e32 v116, 11, v82
	v_lshl_add_u64 v[108:109], v[80:81], 2, s[96:97]
	v_add_u32_e32 v80, v116, v158
	v_lshl_add_u64 v[80:81], v[80:81], 2, s[90:91]
	global_load_dwordx2 v[112:113], v[108:109], off
	v_add_u32_e32 v84, v116, v204
	global_load_dwordx4 v[80:83], v[80:81], off
	v_mov_b32_e32 v85, v159
	v_lshl_add_u64 v[84:85], v[84:85], 2, s[90:91]
	global_load_dwordx4 v[84:87], v[84:85], off
	v_add_u32_e32 v90, 0xb0, v203
	v_lshlrev_b32_e32 v88, 1, v90
	v_mov_b32_e32 v89, v159
	v_lshlrev_b32_e32 v117, 11, v90
	v_lshl_add_u64 v[110:111], v[88:89], 2, s[96:97]
	v_add_u32_e32 v88, v117, v158
	v_lshl_add_u64 v[88:89], v[88:89], 2, s[90:91]
	global_load_dwordx2 v[118:119], v[110:111], off
	v_add_u32_e32 v92, v117, v204
	global_load_dwordx4 v[88:91], v[88:89], off
	v_mov_b32_e32 v93, v159
	v_lshl_add_u64 v[92:93], v[92:93], 2, s[90:91]
	global_load_dwordx4 v[92:95], v[92:93], off
	s_waitcnt vmcnt(0)
	v_sub_f32_e32 v81, v81, v112
	v_sub_f32_e32 v80, v80, v112
	v_sub_f32_e32 v83, v83, v112
	v_sub_f32_e32 v82, v82, v112
	v_pk_mul_f32 v[82:83], v[112:113], v[82:83] op_sel:[1,0]
	v_pk_mul_f32 v[80:81], v[112:113], v[80:81] op_sel:[1,0]
	v_pk_fma_f32 v[78:79], v[192:193], v[82:83], v[78:79]
	v_pk_fma_f32 v[76:77], v[194:195], v[80:81], v[76:77]
	v_add_u32_e32 v80, 0x50000, v148
	v_mov_b32_e32 v81, v159
	v_pk_fma_f32 v[78:79], v[102:103], s[78:79], v[78:79] op_sel_hi:[1,0,1]
	v_pk_fma_f32 v[76:77], v[100:101], s[78:79], v[76:77] op_sel_hi:[1,0,1]
	v_lshl_add_u64 v[80:81], v[80:81], 2, s[88:89]
	global_store_dwordx4 v[80:81], v[76:79], off
	s_nop 1
	v_sub_f32_e32 v77, v85, v112
	v_sub_f32_e32 v76, v84, v112
	v_sub_f32_e32 v79, v87, v112
	v_sub_f32_e32 v78, v86, v112
	v_pk_mul_f32 v[78:79], v[112:113], v[78:79] op_sel:[1,0]
	v_pk_mul_f32 v[76:77], v[112:113], v[76:77] op_sel:[1,0]
	v_pk_fma_f32 v[74:75], v[188:189], v[78:79], v[74:75]
	v_pk_fma_f32 v[72:73], v[190:191], v[76:77], v[72:73]
	v_add_u32_e32 v76, 0x50010, v148
	v_mov_b32_e32 v77, v159
	v_pk_fma_f32 v[74:75], v[98:99], s[78:79], v[74:75] op_sel_hi:[1,0,1]
	v_pk_fma_f32 v[72:73], v[96:97], s[78:79], v[72:73] op_sel_hi:[1,0,1]
	v_lshl_add_u64 v[76:77], v[76:77], 2, s[88:89]
	global_store_dwordx4 v[76:77], v[72:75], off
	s_nop 1
	v_sub_f32_e32 v73, v89, v118
	v_sub_f32_e32 v72, v88, v118
	v_sub_f32_e32 v75, v91, v118
	v_sub_f32_e32 v74, v90, v118
	v_pk_mul_f32 v[74:75], v[118:119], v[74:75] op_sel:[1,0]
	v_pk_mul_f32 v[72:73], v[118:119], v[72:73] op_sel:[1,0]
	v_pk_fma_f32 v[70:71], v[192:193], v[74:75], v[70:71]
	v_pk_fma_f32 v[68:69], v[194:195], v[72:73], v[68:69]
	v_add_u32_e32 v72, 0x58000, v148
	v_mov_b32_e32 v73, v159
	v_pk_fma_f32 v[70:71], v[102:103], s[78:79], v[70:71] op_sel_hi:[1,0,1]
	v_pk_fma_f32 v[68:69], v[100:101], s[78:79], v[68:69] op_sel_hi:[1,0,1]
	v_lshl_add_u64 v[72:73], v[72:73], 2, s[88:89]
	global_store_dwordx4 v[72:73], v[68:71], off
	s_nop 1
	v_sub_f32_e32 v69, v93, v118
	v_sub_f32_e32 v68, v92, v118
	v_sub_f32_e32 v71, v95, v118
	v_sub_f32_e32 v70, v94, v118
	v_pk_mul_f32 v[70:71], v[118:119], v[70:71] op_sel:[1,0]
	v_pk_mul_f32 v[68:69], v[118:119], v[68:69] op_sel:[1,0]
	v_pk_fma_f32 v[66:67], v[188:189], v[70:71], v[66:67]
	v_pk_fma_f32 v[64:65], v[190:191], v[68:69], v[64:65]
	v_add_u32_e32 v68, 0x58010, v148
	v_mov_b32_e32 v69, v159
	v_pk_fma_f32 v[66:67], v[98:99], s[78:79], v[66:67] op_sel_hi:[1,0,1]
	v_pk_fma_f32 v[64:65], v[96:97], s[78:79], v[64:65] op_sel_hi:[1,0,1]
	v_lshl_add_u64 v[68:69], v[68:69], 2, s[88:89]
	global_store_dwordx4 v[68:69], v[64:67], off
	global_load_dwordx4 v[64:67], v[150:151], off offset:512
	v_or_b32_e32 v119, 0x80, v158
	v_add_u32_e32 v72, v202, v119
	v_mov_b32_e32 v73, v159
	v_lshl_add_u64 v[72:73], v[72:73], 2, s[90:91]
	v_or_b32_e32 v118, 0x90, v158
	v_add_u32_e32 v158, v202, v118
	s_waitcnt vmcnt(0)
;     template <bool LN, int BJ, int LO, int HI> DI void batch(const f32x4 (&acc)[2][2][4][2], unsigned row0, unsigned col0, const f32x4 (&gv)[2], const f32x4 (&bv)[2]) const {
;         f32x4 r[HI - LO]; float mean[(HI - LO) / 2], rstd[(HI - LO) / 2];
; #pragma unroll
;         for (int i = LO; i < HI; ++i) { const int ai = i >> 3, m = (i >> 1) & 3, n = i & 1; const unsigned row = row0 + ai * HALF + m * 16;
;             if (n == 0) { mean[(i - LO) >> 1] = 0.f; rstd[(i - LO) >> 1] = 1.f;
;                 if (LN) { const float2 st = *(const float2*)(stats + row * 2u); mean[(i - LO) >> 1] = st.x; rstd[(i - LO) >> 1] = st.y; } }
;             r[i - LO] = *(const f32x4*)(src + (row * (unsigned)DM + col0 + BJ * HALF + n * 16)); }
; #pragma unroll
;         for (int i = LO; i < HI; ++i) { const int ai = i >> 3, m = (i >> 1) & 3, n = i & 1; const unsigned row = row0 + ai * HALF + m * 16;
;             *(f32x4*)(Y + (row * (unsigned)DM + col0 + BJ * HALF + n * 16)) = acc[ai][BJ][m][n] + ((r[i - LO] - mean[(i - LO) >> 1]) * rstd[(i - LO) >> 1]) * gv[n] + bv[n]; }
;         __builtin_amdgcn_sched_barrier(0);
;     }
;     template <bool LN, int BJ> DI void load_gb(unsigned col0, f32x4 (&gv)[2], f32x4 (&bv)[2]) const {
; #pragma unroll
;         for (int n = 0; n < 2; ++n) {
;             if (LN) { gv[n] = *(const f32x4*)(gam + col0 + BJ * HALF + n * 16) * ALPHA; bv[n] = *(const f32x4*)(bet + col0 + BJ * HALF + n * 16) * ALPHA; }
;             else { gv[n] = (f32x4){ALPHA, ALPHA, ALPHA, ALPHA}; bv[n] = (f32x4){0.f, 0.f, 0.f, 0.f}; }
;         }
;     }
;     template <bool LN> DI void run(const f32x4 (&acc)[2][2][4][2], const Unit& u, int wr, int wc, int fr, int fq) const {
;         const unsigned row0 = u.pm * BM + wr * 64 + fr, col0 = u.pn * BM + wc * 32 + 4 * fq;
;         f32x4 gv[2], bv[2];
;         load_gb<LN, 0>(col0, gv, bv);
;         batch<LN, 0, 0, 4>(acc, row0, col0, gv, bv);
;         batch<LN, 0, 4, 8>(acc, row0, col0, gv, bv);
;         batch<LN, 0, 8, 12>(acc, row0, col0, gv, bv);
;         batch<LN, 0, 12, 16>(acc, row0, col0, gv, bv);
;         load_gb<LN, 1>(col0, gv, bv);
;         batch<LN, 1, 0, 8>(acc, row0, col0, gv, bv);
;         batch<LN, 1, 8, 16>(acc, row0, col0, gv, bv);
	v_pk_mul_f32 v[96:97], v[66:67], s[78:79] op_sel_hi:[1,0]
	v_pk_mul_f32 v[98:99], v[64:65], s[78:79] op_sel_hi:[1,0]
	global_load_dwordx4 v[68:71], v[152:153], off offset:512
	global_load_dwordx4 v[64:67], v[150:151], off offset:576
	global_load_dwordx2 v[138:139], v[154:155], off
	global_load_dwordx4 v[126:129], v[72:73], off
	v_lshl_add_u64 v[72:73], v[158:159], 2, s[90:91]
	v_add_u32_e32 v158, v149, v119
	s_waitcnt vmcnt(0)
	v_pk_mul_f32 v[92:93], v[66:67], s[78:79] op_sel_hi:[1,0]
	v_pk_mul_f32 v[94:95], v[64:65], s[78:79] op_sel_hi:[1,0]
	global_load_dwordx4 v[64:67], v[152:153], off offset:576
	global_load_dwordx4 v[130:133], v[72:73], off
	global_load_dwordx2 v[112:113], v[186:187], off
	v_lshl_add_u64 v[72:73], v[158:159], 2, s[90:91]
	global_load_dwordx4 v[134:137], v[72:73], off
	v_add_u32_e32 v158, v149, v118
	v_lshl_add_u64 v[72:73], v[158:159], 2, s[90:91]
	global_load_dwordx4 v[88:91], v[72:73], off
	global_load_dwordx2 v[102:103], v[120:121], off
	v_add_u32_e32 v158, v124, v119
	v_lshl_add_u64 v[72:73], v[158:159], 2, s[90:91]
	global_load_dwordx4 v[84:87], v[72:73], off
	v_add_u32_e32 v158, v124, v118
	v_lshl_add_u64 v[72:73], v[158:159], 2, s[90:91]
	global_load_dwordx4 v[80:83], v[72:73], off
	global_load_dwordx2 v[100:101], v[122:123], off
	v_add_u32_e32 v158, v125, v119
	v_lshl_add_u64 v[72:73], v[158:159], 2, s[90:91]
	global_load_dwordx4 v[76:79], v[72:73], off
	v_add_u32_e32 v158, v125, v118
	v_lshl_add_u64 v[72:73], v[158:159], 2, s[90:91]
	global_load_dwordx4 v[72:75], v[72:73], off
	v_sub_f32_e32 v121, v127, v138
	v_sub_f32_e32 v120, v126, v138
	v_sub_f32_e32 v123, v129, v138
	v_sub_f32_e32 v122, v128, v138
	v_pk_mul_f32 v[122:123], v[138:139], v[122:123] op_sel:[1,0]
	v_pk_mul_f32 v[120:121], v[138:139], v[120:121] op_sel:[1,0]
	v_or_b32_e32 v158, 0x80, v148
	v_pk_fma_f32 v[60:61], v[98:99], v[120:121], v[60:61]
	v_pk_fma_f32 v[62:63], v[96:97], v[122:123], v[62:63]
	v_pk_fma_f32 v[60:61], v[68:69], s[78:79], v[60:61] op_sel_hi:[1,0,1]
	v_pk_fma_f32 v[62:63], v[70:71], s[78:79], v[62:63] op_sel_hi:[1,0,1]
	v_lshl_add_u64 v[120:121], v[158:159], 2, s[88:89]
	global_store_dwordx4 v[120:121], v[60:63], off
	v_or_b32_e32 v158, 0x90, v148
	s_waitcnt vmcnt(0)
	v_sub_f32_e32 v61, v131, v138
	v_sub_f32_e32 v60, v130, v138
	v_sub_f32_e32 v63, v133, v138
	v_sub_f32_e32 v62, v132, v138
	v_pk_mul_f32 v[62:63], v[138:139], v[62:63] op_sel:[1,0]
	v_pk_mul_f32 v[60:61], v[138:139], v[60:61] op_sel:[1,0]
	v_pk_fma_f32 v[58:59], v[92:93], v[62:63], v[58:59]
	v_pk_fma_f32 v[56:57], v[94:95], v[60:61], v[56:57]
	v_pk_fma_f32 v[58:59], v[66:67], s[78:79], v[58:59] op_sel_hi:[1,0,1]
	v_pk_fma_f32 v[56:57], v[64:65], s[78:79], v[56:57] op_sel_hi:[1,0,1]
	v_lshl_add_u64 v[60:61], v[158:159], 2, s[88:89]
	global_store_dwordx4 v[60:61], v[56:59], off
	v_add_u32_e32 v158, 0x8080, v148
	s_nop 0
	v_sub_f32_e32 v57, v135, v112
	v_sub_f32_e32 v56, v134, v112
	v_sub_f32_e32 v59, v137, v112
	v_sub_f32_e32 v58, v136, v112
	v_pk_mul_f32 v[58:59], v[112:113], v[58:59] op_sel:[1,0]
	v_pk_mul_f32 v[56:57], v[112:113], v[56:57] op_sel:[1,0]
	v_pk_fma_f32 v[54:55], v[96:97], v[58:59], v[54:55]
	v_pk_fma_f32 v[52:53], v[98:99], v[56:57], v[52:53]
	v_pk_fma_f32 v[54:55], v[70:71], s[78:79], v[54:55] op_sel_hi:[1,0,1]
	v_pk_fma_f32 v[52:53], v[68:69], s[78:79], v[52:53] op_sel_hi:[1,0,1]
	v_lshl_add_u64 v[56:57], v[158:159], 2, s[88:89]
	global_store_dwordx4 v[56:57], v[52:55], off
	v_add_u32_e32 v158, 0x8090, v148
	s_nop 0
	v_sub_f32_e32 v53, v89, v112
	v_sub_f32_e32 v52, v88, v112
	v_sub_f32_e32 v55, v91, v112
	v_sub_f32_e32 v54, v90, v112
	v_pk_mul_f32 v[54:55], v[112:113], v[54:55] op_sel:[1,0]
	v_pk_mul_f32 v[52:53], v[112:113], v[52:53] op_sel:[1,0]
	v_pk_fma_f32 v[50:51], v[92:93], v[54:55], v[50:51]
	v_pk_fma_f32 v[48:49], v[94:95], v[52:53], v[48:49]
	v_pk_fma_f32 v[50:51], v[66:67], s[78:79], v[50:51] op_sel_hi:[1,0,1]
	v_pk_fma_f32 v[48:49], v[64:65], s[78:79], v[48:49] op_sel_hi:[1,0,1]
	v_lshl_add_u64 v[52:53], v[158:159], 2, s[88:89]
	global_store_dwordx4 v[52:53], v[48:51], off
	v_add_u32_e32 v158, 0x10080, v148
	s_nop 0
	v_sub_f32_e32 v49, v85, v102
	v_sub_f32_e32 v48, v84, v102
	v_sub_f32_e32 v51, v87, v102
	v_sub_f32_e32 v50, v86, v102
	v_pk_mul_f32 v[50:51], v[102:103], v[50:51] op_sel:[1,0]
	v_pk_mul_f32 v[48:49], v[102:103], v[48:49] op_sel:[1,0]
	v_pk_fma_f32 v[46:47], v[96:97], v[50:51], v[46:47]
	v_pk_fma_f32 v[44:45], v[98:99], v[48:49], v[44:45]
	v_pk_fma_f32 v[46:47], v[70:71], s[78:79], v[46:47] op_sel_hi:[1,0,1]
	v_pk_fma_f32 v[44:45], v[68:69], s[78:79], v[44:45] op_sel_hi:[1,0,1]
	v_lshl_add_u64 v[48:49], v[158:159], 2, s[88:89]
	global_store_dwordx4 v[48:49], v[44:47], off
	v_add_u32_e32 v158, 0x10090, v148
	s_nop 0
	v_sub_f32_e32 v45, v81, v102
	v_sub_f32_e32 v44, v80, v102
	v_sub_f32_e32 v47, v83, v102
	v_sub_f32_e32 v46, v82, v102
	v_pk_mul_f32 v[46:47], v[102:103], v[46:47] op_sel:[1,0]
	v_pk_mul_f32 v[44:45], v[102:103], v[44:45] op_sel:[1,0]
	v_pk_fma_f32 v[42:43], v[92:93], v[46:47], v[42:43]
	v_pk_fma_f32 v[40:41], v[94:95], v[44:45], v[40:41]
	v_pk_fma_f32 v[42:43], v[66:67], s[78:79], v[42:43] op_sel_hi:[1,0,1]
	v_pk_fma_f32 v[40:41], v[64:65], s[78:79], v[40:41] op_sel_hi:[1,0,1]
	v_lshl_add_u64 v[44:45], v[158:159], 2, s[88:89]
	global_store_dwordx4 v[44:45], v[40:43], off
	v_add_u32_e32 v158, 0x18080, v148
	s_nop 0
	v_sub_f32_e32 v41, v77, v100
	v_sub_f32_e32 v40, v76, v100
	v_sub_f32_e32 v43, v79, v100
	v_sub_f32_e32 v42, v78, v100
	v_pk_mul_f32 v[42:43], v[100:101], v[42:43] op_sel:[1,0]
	v_pk_mul_f32 v[40:41], v[100:101], v[40:41] op_sel:[1,0]
	v_pk_fma_f32 v[38:39], v[96:97], v[42:43], v[38:39]
;     template <bool LN, int BJ, int LO, int HI> DI void batch(const f32x4 (&acc)[2][2][4][2], unsigned row0, unsigned col0, const f32x4 (&gv)[2], const f32x4 (&bv)[2]) const {
;         f32x4 r[HI - LO]; float mean[(HI - LO) / 2], rstd[(HI - LO) / 2];
; #pragma unroll
;         for (int i = LO; i < HI; ++i) { const int ai = i >> 3, m = (i >> 1) & 3, n = i & 1; const unsigned row = row0 + ai * HALF + m * 16;
;             if (n == 0) { mean[(i - LO) >> 1] = 0.f; rstd[(i - LO) >> 1] = 1.f;
;                 if (LN) { const float2 st = *(const float2*)(stats + row * 2u); mean[(i - LO) >> 1] = st.x; rstd[(i - LO) >> 1] = st.y; } }
;             r[i - LO] = *(const f32x4*)(src + (row * (unsigned)DM + col0 + BJ * HALF + n * 16)); }
; #pragma unroll
;         for (int i = LO; i < HI; ++i) { const int ai = i >> 3, m = (i >> 1) & 3, n = i & 1; const unsigned row = row0 + ai * HALF + m * 16;
;             *(f32x4*)(Y + (row * (unsigned)DM + col0 + BJ * HALF + n * 16)) = acc[ai][BJ][m][n] + ((r[i - LO] - mean[(i - LO) >> 1]) * rstd[(i - LO) >> 1]) * gv[n] + bv[n]; }
;         __builtin_amdgcn_sched_barrier(0);
;     }
;     template <bool LN, int BJ> DI void load_gb(unsigned col0, f32x4 (&gv)[2], f32x4 (&bv)[2]) const {
; #pragma unroll
;         for (int n = 0; n < 2; ++n) {
;             if (LN) { gv[n] = *(const f32x4*)(gam + col0 + BJ * HALF + n * 16) * ALPHA; bv[n] = *(const f32x4*)(bet + col0 + BJ * HALF + n * 16) * ALPHA; }
;             else { gv[n] = (f32x4){ALPHA, ALPHA, ALPHA, ALPHA}; bv[n] = (f32x4){0.f, 0.f, 0.f, 0.f}; }
;         }
;     }
;     template <bool LN> DI void run(const f32x4 (&acc)[2][2][4][2], const Unit& u, int wr, int wc, int fr, int fq) const {
;         const unsigned row0 = u.pm * BM + wr * 64 + fr, col0 = u.pn * BM + wc * 32 + 4 * fq;
;         f32x4 gv[2], bv[2];
;         load_gb<LN, 0>(col0, gv, bv);
;         batch<LN, 0, 0, 4>(acc, row0, col0, gv, bv);
;         batch<LN, 0, 4, 8>(acc, row0, col0, gv, bv);
;         batch<LN, 0, 8, 12>(acc, row0, col0, gv, bv);
;         batch<LN, 0, 12, 16>(acc, row0, col0, gv, bv);
;         load_gb<LN, 1>(col0, gv, bv);
;         batch<LN, 1, 0, 8>(acc, row0, col0, gv, bv);
;         batch<LN, 1, 8, 16>(acc, row0, col0, gv, bv);
	v_pk_fma_f32 v[36:37], v[98:99], v[40:41], v[36:37]
	v_pk_fma_f32 v[38:39], v[70:71], s[78:79], v[38:39] op_sel_hi:[1,0,1]
	v_pk_fma_f32 v[36:37], v[68:69], s[78:79], v[36:37] op_sel_hi:[1,0,1]
	v_lshl_add_u64 v[40:41], v[158:159], 2, s[88:89]
	global_store_dwordx4 v[40:41], v[36:39], off
	v_add_u32_e32 v158, 0x18090, v148
	s_nop 0
	v_sub_f32_e32 v37, v73, v100
	v_sub_f32_e32 v36, v72, v100
	v_sub_f32_e32 v39, v75, v100
	v_sub_f32_e32 v38, v74, v100
	v_pk_mul_f32 v[38:39], v[100:101], v[38:39] op_sel:[1,0]
	v_pk_mul_f32 v[36:37], v[100:101], v[36:37] op_sel:[1,0]
	v_pk_fma_f32 v[34:35], v[92:93], v[38:39], v[34:35]
	v_pk_fma_f32 v[32:33], v[94:95], v[36:37], v[32:33]
	v_pk_fma_f32 v[34:35], v[66:67], s[78:79], v[34:35] op_sel_hi:[1,0,1]
	v_pk_fma_f32 v[32:33], v[64:65], s[78:79], v[32:33] op_sel_hi:[1,0,1]
	v_lshl_add_u64 v[36:37], v[158:159], 2, s[88:89]
	global_store_dwordx4 v[36:37], v[32:35], off
	v_add_u32_e32 v158, v114, v119
	s_nop 0
	v_lshl_add_u64 v[32:33], v[158:159], 2, s[90:91]
	global_load_dwordx2 v[62:63], v[104:105], off
	global_load_dwordx4 v[54:57], v[32:33], off
	v_add_u32_e32 v158, v114, v118
	v_lshl_add_u64 v[32:33], v[158:159], 2, s[90:91]
	global_load_dwordx4 v[58:61], v[32:33], off
	global_load_dwordx2 v[52:53], v[106:107], off
	v_add_u32_e32 v158, v115, v119
	v_lshl_add_u64 v[32:33], v[158:159], 2, s[90:91]
	global_load_dwordx4 v[72:75], v[32:33], off
	v_add_u32_e32 v158, v115, v118
	v_lshl_add_u64 v[32:33], v[158:159], 2, s[90:91]
	global_load_dwordx4 v[76:79], v[32:33], off
	global_load_dwordx2 v[50:51], v[108:109], off
	v_add_u32_e32 v158, v116, v119
	v_lshl_add_u64 v[32:33], v[158:159], 2, s[90:91]
	global_load_dwordx4 v[44:47], v[32:33], off
	v_add_u32_e32 v158, v116, v118
	v_lshl_add_u64 v[32:33], v[158:159], 2, s[90:91]
	global_load_dwordx4 v[40:43], v[32:33], off
	global_load_dwordx2 v[48:49], v[110:111], off
	v_add_u32_e32 v158, v117, v119
	v_lshl_add_u64 v[32:33], v[158:159], 2, s[90:91]
	global_load_dwordx4 v[36:39], v[32:33], off
	v_add_u32_e32 v158, v117, v118
	v_lshl_add_u64 v[32:33], v[158:159], 2, s[90:91]
	global_load_dwordx4 v[32:35], v[32:33], off
	v_add_u32_e32 v158, 0x40080, v148
	s_waitcnt vmcnt(0)
; template <class Epi>
; DI void gemm_phase(LAS unsigned char* lds, const Gemm g, const StaticOrder& S, const Epi& E) {
;     ...
;         E(acc, cur, wr, wc, fr, fq);
;     template <bool LN, int BJ, int LO, int HI> DI void batch(const f32x4 (&acc)[2][2][4][2], unsigned row0, unsigned col0, const f32x4 (&gv)[2], const f32x4 (&bv)[2]) const {
;         f32x4 r[HI - LO]; float mean[(HI - LO) / 2], rstd[(HI - LO) / 2];
; #pragma unroll
;         for (int i = LO; i < HI; ++i) { const int ai = i >> 3, m = (i >> 1) & 3, n = i & 1; const unsigned row = row0 + ai * HALF + m * 16;
;             if (n == 0) { mean[(i - LO) >> 1] = 0.f; rstd[(i - LO) >> 1] = 1.f;
;                 if (LN) { const float2 st = *(const float2*)(stats + row * 2u); mean[(i - LO) >> 1] = st.x; rstd[(i - LO) >> 1] = st.y; } }
;             r[i - LO] = *(const f32x4*)(src + (row * (unsigned)DM + col0 + BJ * HALF + n * 16)); }
; #pragma unroll
;         for (int i = LO; i < HI; ++i) { const int ai = i >> 3, m = (i >> 1) & 3, n = i & 1; const unsigned row = row0 + ai * HALF + m * 16;
;             *(f32x4*)(Y + (row * (unsigned)DM + col0 + BJ * HALF + n * 16)) = acc[ai][BJ][m][n] + ((r[i - LO] - mean[(i - LO) >> 1]) * rstd[(i - LO) >> 1]) * gv[n] + bv[n]; }
;         __builtin_amdgcn_sched_barrier(0);
;     }
;     template <bool LN, int BJ> DI void load_gb(unsigned col0, f32x4 (&gv)[2], f32x4 (&bv)[2]) const {
; #pragma unroll
;         for (int n = 0; n < 2; ++n) {
;             if (LN) { gv[n] = *(const f32x4*)(gam + col0 + BJ * HALF + n * 16) * ALPHA; bv[n] = *(const f32x4*)(bet + col0 + BJ * HALF + n * 16) * ALPHA; }
;             else { gv[n] = (f32x4){ALPHA, ALPHA, ALPHA, ALPHA}; bv[n] = (f32x4){0.f, 0.f, 0.f, 0.f}; }
;         }
;     }
;     template <bool LN> DI void run(const f32x4 (&acc)[2][2][4][2], const Unit& u, int wr, int wc, int fr, int fq) const {
;         const unsigned row0 = u.pm * BM + wr * 64 + fr, col0 = u.pn * BM + wc * 32 + 4 * fq;
;         f32x4 gv[2], bv[2];
;         load_gb<LN, 0>(col0, gv, bv);
;         batch<LN, 0, 0, 4>(acc, row0, col0, gv, bv);
;         batch<LN, 0, 4, 8>(acc, row0, col0, gv, bv);
;         batch<LN, 0, 8, 12>(acc, row0, col0, gv, bv);
;         batch<LN, 0, 12, 16>(acc, row0, col0, gv, bv);
;         load_gb<LN, 1>(col0, gv, bv);
;         batch<LN, 1, 0, 8>(acc, row0, col0, gv, bv);
;         batch<LN, 1, 8, 16>(acc, row0, col0, gv, bv);
	v_sub_f32_e32 v55, v55, v62
	v_sub_f32_e32 v54, v54, v62
	v_sub_f32_e32 v57, v57, v62
	v_sub_f32_e32 v56, v56, v62
	v_pk_mul_f32 v[56:57], v[62:63], v[56:57] op_sel:[1,0]
	v_pk_mul_f32 v[54:55], v[62:63], v[54:55] op_sel:[1,0]
	v_pk_fma_f32 v[30:31], v[96:97], v[56:57], v[30:31]
	v_pk_fma_f32 v[28:29], v[98:99], v[54:55], v[28:29]
	v_pk_fma_f32 v[30:31], v[70:71], s[78:79], v[30:31] op_sel_hi:[1,0,1]
	v_pk_fma_f32 v[28:29], v[68:69], s[78:79], v[28:29] op_sel_hi:[1,0,1]
	v_lshl_add_u64 v[54:55], v[158:159], 2, s[88:89]
	global_store_dwordx4 v[54:55], v[28:31], off
	v_add_u32_e32 v158, 0x40090, v148
	s_nop 0
	v_sub_f32_e32 v29, v59, v62
	v_sub_f32_e32 v28, v58, v62
	v_sub_f32_e32 v31, v61, v62
	v_sub_f32_e32 v30, v60, v62
	v_pk_mul_f32 v[30:31], v[62:63], v[30:31] op_sel:[1,0]
	v_pk_mul_f32 v[28:29], v[62:63], v[28:29] op_sel:[1,0]
	v_pk_fma_f32 v[26:27], v[92:93], v[30:31], v[26:27]
	v_pk_fma_f32 v[24:25], v[94:95], v[28:29], v[24:25]
	v_pk_fma_f32 v[26:27], v[66:67], s[78:79], v[26:27] op_sel_hi:[1,0,1]
	v_pk_fma_f32 v[24:25], v[64:65], s[78:79], v[24:25] op_sel_hi:[1,0,1]
	v_lshl_add_u64 v[28:29], v[158:159], 2, s[88:89]
	global_store_dwordx4 v[28:29], v[24:27], off
	v_add_u32_e32 v158, 0x48080, v148
	s_nop 0
	v_sub_f32_e32 v25, v73, v52
	v_sub_f32_e32 v24, v72, v52
	v_sub_f32_e32 v27, v75, v52
	v_sub_f32_e32 v26, v74, v52
	v_pk_mul_f32 v[26:27], v[52:53], v[26:27] op_sel:[1,0]
	v_pk_mul_f32 v[24:25], v[52:53], v[24:25] op_sel:[1,0]
	v_pk_fma_f32 v[22:23], v[96:97], v[26:27], v[22:23]
	v_pk_fma_f32 v[20:21], v[98:99], v[24:25], v[20:21]
	v_pk_fma_f32 v[22:23], v[70:71], s[78:79], v[22:23] op_sel_hi:[1,0,1]
	v_pk_fma_f32 v[20:21], v[68:69], s[78:79], v[20:21] op_sel_hi:[1,0,1]
	v_lshl_add_u64 v[24:25], v[158:159], 2, s[88:89]
	global_store_dwordx4 v[24:25], v[20:23], off
	v_add_u32_e32 v158, 0x48090, v148
	s_nop 0
	v_sub_f32_e32 v21, v77, v52
	v_sub_f32_e32 v20, v76, v52
	v_sub_f32_e32 v23, v79, v52
	v_sub_f32_e32 v22, v78, v52
	v_pk_mul_f32 v[22:23], v[52:53], v[22:23] op_sel:[1,0]
	v_pk_mul_f32 v[20:21], v[52:53], v[20:21] op_sel:[1,0]
	v_pk_fma_f32 v[18:19], v[92:93], v[22:23], v[18:19]
	v_pk_fma_f32 v[16:17], v[94:95], v[20:21], v[16:17]
	v_pk_fma_f32 v[18:19], v[66:67], s[78:79], v[18:19] op_sel_hi:[1,0,1]
	v_pk_fma_f32 v[16:17], v[64:65], s[78:79], v[16:17] op_sel_hi:[1,0,1]
	v_lshl_add_u64 v[20:21], v[158:159], 2, s[88:89]
	global_store_dwordx4 v[20:21], v[16:19], off
	v_add_u32_e32 v158, 0x50080, v148
	s_nop 0
	v_sub_f32_e32 v17, v45, v50
	v_sub_f32_e32 v16, v44, v50
	v_sub_f32_e32 v19, v47, v50
	v_sub_f32_e32 v18, v46, v50
	v_pk_mul_f32 v[18:19], v[50:51], v[18:19] op_sel:[1,0]
	v_pk_mul_f32 v[16:17], v[50:51], v[16:17] op_sel:[1,0]
	v_pk_fma_f32 v[14:15], v[96:97], v[18:19], v[14:15]
	v_pk_fma_f32 v[12:13], v[98:99], v[16:17], v[12:13]
	v_pk_fma_f32 v[14:15], v[70:71], s[78:79], v[14:15] op_sel_hi:[1,0,1]
	v_pk_fma_f32 v[12:13], v[68:69], s[78:79], v[12:13] op_sel_hi:[1,0,1]
	v_lshl_add_u64 v[16:17], v[158:159], 2, s[88:89]
	global_store_dwordx4 v[16:17], v[12:15], off
	v_add_u32_e32 v158, 0x50090, v148
	s_nop 0
	v_sub_f32_e32 v13, v41, v50
	v_sub_f32_e32 v12, v40, v50
	v_sub_f32_e32 v15, v43, v50
	v_sub_f32_e32 v14, v42, v50
	v_pk_mul_f32 v[14:15], v[50:51], v[14:15] op_sel:[1,0]
	v_pk_mul_f32 v[12:13], v[50:51], v[12:13] op_sel:[1,0]
	v_pk_fma_f32 v[10:11], v[92:93], v[14:15], v[10:11]
	v_pk_fma_f32 v[8:9], v[94:95], v[12:13], v[8:9]
	v_pk_fma_f32 v[10:11], v[66:67], s[78:79], v[10:11] op_sel_hi:[1,0,1]
	v_pk_fma_f32 v[8:9], v[64:65], s[78:79], v[8:9] op_sel_hi:[1,0,1]
	v_lshl_add_u64 v[12:13], v[158:159], 2, s[88:89]
	global_store_dwordx4 v[12:13], v[8:11], off
	v_add_u32_e32 v158, 0x58080, v148
	s_nop 0
	v_sub_f32_e32 v9, v37, v48
	v_sub_f32_e32 v8, v36, v48
	v_sub_f32_e32 v11, v39, v48
	v_sub_f32_e32 v10, v38, v48
	v_pk_mul_f32 v[10:11], v[48:49], v[10:11] op_sel:[1,0]
	v_pk_mul_f32 v[8:9], v[48:49], v[8:9] op_sel:[1,0]
	v_pk_fma_f32 v[6:7], v[96:97], v[10:11], v[6:7]
	v_pk_fma_f32 v[4:5], v[98:99], v[8:9], v[4:5]
	v_pk_fma_f32 v[6:7], v[70:71], s[78:79], v[6:7] op_sel_hi:[1,0,1]
	v_pk_fma_f32 v[4:5], v[68:69], s[78:79], v[4:5] op_sel_hi:[1,0,1]
	v_lshl_add_u64 v[8:9], v[158:159], 2, s[88:89]
	global_store_dwordx4 v[8:9], v[4:7], off
	v_add_u32_e32 v158, 0x58090, v148
	s_nop 0
	v_sub_f32_e32 v5, v33, v48
	v_sub_f32_e32 v4, v32, v48
	v_sub_f32_e32 v7, v35, v48
	v_sub_f32_e32 v6, v34, v48
	v_pk_mul_f32 v[6:7], v[48:49], v[6:7] op_sel:[1,0]
	v_pk_mul_f32 v[4:5], v[48:49], v[4:5] op_sel:[1,0]
	v_pk_fma_f32 v[2:3], v[92:93], v[6:7], v[2:3]
	v_pk_fma_f32 v[0:1], v[94:95], v[4:5], v[0:1]
	v_pk_fma_f32 v[2:3], v[66:67], s[78:79], v[2:3] op_sel_hi:[1,0,1]
	v_pk_fma_f32 v[0:1], v[64:65], s[78:79], v[0:1] op_sel_hi:[1,0,1]
	v_lshl_add_u64 v[4:5], v[158:159], 2, s[88:89]
	global_store_dwordx4 v[4:5], v[0:3], off
	s_and_b64 vcc, exec, s[6:7]
	s_mov_b32 s2, s37
	s_mov_b32 s3, s38
	s_mov_b64 s[18:19], s[10:11]
	s_mov_b64 s[16:17], s[8:9]
	v_readlane_b32 s33, v255, 39
	s_cbranch_vccz .LBB0_123
	s_waitcnt vmcnt(0)
	s_cmpk_gt_u32 s24, 0xff
	s_cbranch_scc1 .LBB0_138
	s_barrier

; #define PG8_STAGE(bufoff, gbase) do { _Pragma("unroll") for (int _i = 0; _i < 2; ++_i) \
;         __builtin_amdgcn_global_load_lds((const unsigned*)((const char*)(gbase) + voff[_i]), (LAS unsigned*)(lds + (bufoff) + ldsw + _i * 8192), 16, 0, 0); } while (0)
; #define PG8_LDA(dst, b, h) do { _Pragma("unroll") for (int m = 0; m < 4; ++m) _Pragma("unroll") for (int k = 0; k < 2; ++k) dst[m][k] = *(const LAS bf16x8*)(lds + PG8_SA(b, h) + aoff + m * 2048 + k * 1024); } while (0)
; #define PG8_LDB(dst, b, h) do { _Pragma("unroll") for (int n = 0; n < 2; ++n) _Pragma("unroll") for (int k = 0; k < 2; ++k) dst[n][k] = *(const LAS bf16x8*)(lds + PG8_SB(b, h) + boff + n * 2048 + k * 1024); } while (0)
; #define PG8_MMA(ai, bj, At, Bt) do { __builtin_amdgcn_s_setprio(1); _Pragma("unroll") for (int m = 0; m < 4; ++m) _Pragma("unroll") for (int n = 0; n < 2; ++n) _Pragma("unroll") for (int k = 0; k < 2; ++k) \
;         acc[ai][bj][m][n] = __builtin_amdgcn_mfma_f32_16x16x32_bf16(Bt[n][k], At[m][k], acc[ai][bj][m][n], 0, 0, 0); __builtin_amdgcn_s_setprio(0); } while (0)
; #define PG8_WAIT_V(n) asm volatile("s_waitcnt vmcnt(" #n ")" ::: "memory")
; #define PG8_WAIT_L(n) asm volatile("s_waitcnt lgkmcnt(" #n ")" ::: "memory")
; #define PG8_BAR __builtin_amdgcn_s_barrier()
; #define PG8_SCHED __builtin_amdgcn_sched_barrier(0)
; template <class Epi>
; DI void gemm_phase(LAS unsigned char* lds, const Gemm g, const StaticOrder& S, const Epi& E) {
;     ...
;         for (int t = 0; t < nt; t += 2) {
;             const bool last = (t == nt - 2);
;             const char* a1 = cA + (size_t)(t + 1) * kstep;
;             const char* a2 = last ? nA : cA + (size_t)(t + 2) * kstep; const char* b2 = last ? nB : cB + (size_t)(t + 2) * kstep;
;             const char* a3 = a2 + kstep; const char* b3 = b2 + kstep;
;             PG8_LDB(B0, 0, 0); PG8_SCHED; PG8_LDA(At, 0, 0); PG8_STAGE(PG8_SA(1, 1), a1 + hstep);
;             PG8_WAIT_L(8); PG8_BAR; PG8_WAIT_L(0); PG8_MMA(0, 0, At, B0); PG8_BAR; PG8_SCHED;
;             PG8_LDB(B1, 0, 1); PG8_STAGE(PG8_SB(0, 0), b2);
;             PG8_BAR; PG8_WAIT_L(0); PG8_MMA(0, 1, At, B1); PG8_BAR;
;             PG8_LDA(At, 0, 1); PG8_STAGE(PG8_SA(0, 0), a2);
;             PG8_BAR; PG8_WAIT_L(0); PG8_MMA(1, 0, At, B0); PG8_BAR; PG8_SCHED;
;             PG8_STAGE(PG8_SB(0, 1), b2 + hstep);
;             PG8_WAIT_V(6); PG8_BAR; PG8_MMA(1, 1, At, B1); PG8_BAR;
.LBB0_202:
	s_add_u32 s18, s8, 0xfff80080
	s_addc_u32 s19, s9, -1
	s_add_i32 s37, 0, 0x10000
	v_add_u32_e32 v140, s37, v187
	s_waitcnt lgkmcnt(0)
	ds_read_b128 v[128:131], v140
	ds_read_b128 v[132:135], v140 offset:1024
	ds_read_b128 v[136:139], v140 offset:2048
	ds_read_b128 v[190:193], v140 offset:3072
	s_cmp_eq_u32 s36, 28
	s_cselect_b32 s21, s4, s19
	s_cselect_b32 s20, s5, s18
	s_cselect_b32 s19, s11, s35
	s_cselect_b32 s18, s13, s33
	v_lshl_add_u64 v[140:141], s[8:9], 0, v[150:151]
	s_add_i32 m0, s26, 0xc000
	ds_read_b128 v[194:197], v189
	ds_read_b128 v[198:201], v189 offset:1024
	ds_read_b128 v[202:205], v189 offset:2048
	ds_read_b128 v[206:209], v189 offset:3072
	ds_read_b128 v[210:213], v189 offset:4096
	ds_read_b128 v[214:217], v189 offset:5120
	ds_read_b128 v[226:229], v189 offset:6144
	ds_read_b128 v[230:233], v189 offset:7168
	global_load_lds_dwordx4 v[140:141], off
	v_lshl_add_u64 v[140:141], s[8:9], 0, v[152:153]
	s_add_i32 m0, s26, 0xe000
	s_nop 0
	global_load_lds_dwordx4 v[140:141], off
	s_waitcnt lgkmcnt(8)
	s_setprio 1
	s_barrier
	s_waitcnt lgkmcnt(0)
	v_mfma_f32_16x16x32_bf16 v[124:127], v[128:131], v[194:197], v[124:127]
	v_mfma_f32_16x16x32_bf16 v[120:123], v[136:139], v[194:197], v[120:123]
	v_mfma_f32_16x16x32_bf16 v[108:111], v[128:131], v[202:205], v[108:111]
	v_mfma_f32_16x16x32_bf16 v[104:107], v[136:139], v[202:205], v[104:107]
	v_mfma_f32_16x16x32_bf16 v[92:95], v[128:131], v[210:213], v[92:95]
	v_mfma_f32_16x16x32_bf16 v[88:91], v[136:139], v[210:213], v[88:91]
	v_mfma_f32_16x16x32_bf16 v[76:79], v[128:131], v[226:229], v[76:79]
	v_mfma_f32_16x16x32_bf16 v[72:75], v[136:139], v[226:229], v[72:75]
	v_mfma_f32_16x16x32_bf16 v[124:127], v[132:135], v[198:201], v[124:127]
	v_mfma_f32_16x16x32_bf16 v[120:123], v[190:193], v[198:201], v[120:123]
	v_mfma_f32_16x16x32_bf16 v[108:111], v[132:135], v[206:209], v[108:111]
	v_mfma_f32_16x16x32_bf16 v[104:107], v[190:193], v[206:209], v[104:107]
	s_add_i32 s40, 0, 0x14000
	v_add_u32_e32 v140, s40, v187
	s_add_i32 s37, s37, s25
	v_mfma_f32_16x16x32_bf16 v[92:95], v[132:135], v[214:217], v[92:95]
	v_mfma_f32_16x16x32_bf16 v[88:91], v[190:193], v[214:217], v[88:91]
	v_mfma_f32_16x16x32_bf16 v[76:79], v[132:135], v[230:233], v[76:79]
	v_mfma_f32_16x16x32_bf16 v[72:75], v[190:193], v[230:233], v[72:75]
	s_setprio 0
	s_barrier
	ds_read_b128 v[234:237], v140
	ds_read_b128 v[238:241], v140 offset:1024
	ds_read_b128 v[242:245], v140 offset:2048
	ds_read_b128 v[246:249], v140 offset:3072
	v_lshl_add_u64 v[140:141], s[18:19], 0, v[144:145]
	s_mov_b32 m0, s37
	v_lshl_add_u64 v[154:155], s[18:19], 0, v[142:143]
	global_load_lds_dwordx4 v[140:141], off
	s_add_i32 m0, s37, 0x2000
	s_nop 0
	global_load_lds_dwordx4 v[154:155], off
	s_waitcnt lgkmcnt(0)
	s_setprio 1
	s_barrier
	v_mfma_f32_16x16x32_bf16 v[116:119], v[234:237], v[194:197], v[116:119]
	v_mfma_f32_16x16x32_bf16 v[112:115], v[242:245], v[194:197], v[112:115]
	v_mfma_f32_16x16x32_bf16 v[100:103], v[234:237], v[202:205], v[100:103]
	v_mfma_f32_16x16x32_bf16 v[96:99], v[242:245], v[202:205], v[96:99]
	v_mfma_f32_16x16x32_bf16 v[84:87], v[234:237], v[210:213], v[84:87]
	v_mfma_f32_16x16x32_bf16 v[80:83], v[242:245], v[210:213], v[80:83]
	v_mfma_f32_16x16x32_bf16 v[68:71], v[234:237], v[226:229], v[68:71]
	v_mfma_f32_16x16x32_bf16 v[64:67], v[242:245], v[226:229], v[64:67]
	v_mfma_f32_16x16x32_bf16 v[116:119], v[238:241], v[198:201], v[116:119]
	v_mfma_f32_16x16x32_bf16 v[112:115], v[246:249], v[198:201], v[112:115]
	v_mfma_f32_16x16x32_bf16 v[100:103], v[238:241], v[206:209], v[100:103]
	v_mfma_f32_16x16x32_bf16 v[96:99], v[246:249], v[206:209], v[96:99]
	s_mov_b32 m0, s26
	v_lshl_add_u64 v[218:219], s[20:21], 0, v[144:145]
	v_mfma_f32_16x16x32_bf16 v[84:87], v[238:241], v[214:217], v[84:87]
	v_mfma_f32_16x16x32_bf16 v[80:83], v[246:249], v[214:217], v[80:83]
	v_mfma_f32_16x16x32_bf16 v[68:71], v[238:241], v[230:233], v[68:71]
	v_mfma_f32_16x16x32_bf16 v[64:67], v[246:249], v[230:233], v[64:67]
	s_setprio 0
	s_barrier
	ds_read_b128 v[194:197], v189 offset:16384
	ds_read_b128 v[198:201], v189 offset:17408
	ds_read_b128 v[202:205], v189 offset:18432
	ds_read_b128 v[206:209], v189 offset:19456
	ds_read_b128 v[210:213], v189 offset:20480
	ds_read_b128 v[214:217], v189 offset:21504
	ds_read_b128 v[226:229], v189 offset:22528
	ds_read_b128 v[230:233], v189 offset:23552
	global_load_lds_dwordx4 v[218:219], off
	v_lshl_add_u64 v[250:251], s[20:21], 0, v[142:143]
	s_mov_b32 m0, s27
	s_nop 0
	global_load_lds_dwordx4 v[250:251], off
	s_waitcnt lgkmcnt(0)
	s_setprio 1
	s_barrier
	v_mfma_f32_16x16x32_bf16 v[60:63], v[128:131], v[194:197], v[60:63]
	v_mfma_f32_16x16x32_bf16 v[56:59], v[136:139], v[194:197], v[56:59]
	v_mfma_f32_16x16x32_bf16 v[44:47], v[128:131], v[202:205], v[44:47]
	v_mfma_f32_16x16x32_bf16 v[40:43], v[136:139], v[202:205], v[40:43]
	v_mfma_f32_16x16x32_bf16 v[28:31], v[128:131], v[210:213], v[28:31]
	v_mfma_f32_16x16x32_bf16 v[24:27], v[136:139], v[210:213], v[24:27]
	v_mfma_f32_16x16x32_bf16 v[12:15], v[128:131], v[226:229], v[12:15]
	v_mfma_f32_16x16x32_bf16 v[8:11], v[136:139], v[226:229], v[8:11]
	v_mfma_f32_16x16x32_bf16 v[60:63], v[132:135], v[198:201], v[60:63]
	v_mfma_f32_16x16x32_bf16 v[56:59], v[190:193], v[198:201], v[56:59]
	v_mfma_f32_16x16x32_bf16 v[44:47], v[132:135], v[206:209], v[44:47]
	v_mfma_f32_16x16x32_bf16 v[40:43], v[190:193], v[206:209], v[40:43]
	s_add_u32 s38, s18, 0x80000
	s_addc_u32 s39, s19, 0
	s_add_i32 s37, s40, s25
	v_lshl_add_u64 v[128:129], s[38:39], 0, v[144:145]
	s_mov_b32 m0, s37
	v_mfma_f32_16x16x32_bf16 v[28:31], v[132:135], v[214:217], v[28:31]
	v_mfma_f32_16x16x32_bf16 v[24:27], v[190:193], v[214:217], v[24:27]
	v_mfma_f32_16x16x32_bf16 v[12:15], v[132:135], v[230:233], v[12:15]
	v_mfma_f32_16x16x32_bf16 v[8:11], v[190:193], v[230:233], v[8:11]
	s_setprio 0
	s_barrier
; #define PG8_STAGE(bufoff, gbase) do { _Pragma("unroll") for (int _i = 0; _i < 2; ++_i) \
;         __builtin_amdgcn_global_load_lds((const unsigned*)((const char*)(gbase) + voff[_i]), (LAS unsigned*)(lds + (bufoff) + ldsw + _i * 8192), 16, 0, 0); } while (0)
; #define PG8_LDA(dst, b, h) do { _Pragma("unroll") for (int m = 0; m < 4; ++m) _Pragma("unroll") for (int k = 0; k < 2; ++k) dst[m][k] = *(const LAS bf16x8*)(lds + PG8_SA(b, h) + aoff + m * 2048 + k * 1024); } while (0)
; #define PG8_LDB(dst, b, h) do { _Pragma("unroll") for (int n = 0; n < 2; ++n) _Pragma("unroll") for (int k = 0; k < 2; ++k) dst[n][k] = *(const LAS bf16x8*)(lds + PG8_SB(b, h) + boff + n * 2048 + k * 1024); } while (0)
; #define PG8_MMA(ai, bj, At, Bt) do { __builtin_amdgcn_s_setprio(1); _Pragma("unroll") for (int m = 0; m < 4; ++m) _Pragma("unroll") for (int n = 0; n < 2; ++n) _Pragma("unroll") for (int k = 0; k < 2; ++k) \
;         acc[ai][bj][m][n] = __builtin_amdgcn_mfma_f32_16x16x32_bf16(Bt[n][k], At[m][k], acc[ai][bj][m][n], 0, 0, 0); __builtin_amdgcn_s_setprio(0); } while (0)
; #define PG8_WAIT_V(n) asm volatile("s_waitcnt vmcnt(" #n ")" ::: "memory")
; #define PG8_WAIT_L(n) asm volatile("s_waitcnt lgkmcnt(" #n ")" ::: "memory")
; #define PG8_BAR __builtin_amdgcn_s_barrier()
; #define PG8_SCHED __builtin_amdgcn_sched_barrier(0)
; template <class Epi>
; DI void gemm_phase(LAS unsigned char* lds, const Gemm g, const StaticOrder& S, const Epi& E) {
;     ...
;             PG8_BAR; PG8_WAIT_L(0); PG8_MMA(1, 0, At, B0); PG8_BAR; PG8_SCHED;
;             PG8_STAGE(PG8_SB(0, 1), b2 + hstep);
;             PG8_WAIT_V(6); PG8_BAR; PG8_MMA(1, 1, At, B1); PG8_BAR;
;             PG8_LDB(B0, 1, 0); PG8_SCHED; PG8_LDA(At, 1, 0); PG8_STAGE(PG8_SA(0, 1), a2 + hstep);
;             PG8_WAIT_L(8); PG8_BAR; PG8_WAIT_L(0); PG8_MMA(0, 0, At, B0); PG8_BAR; PG8_SCHED;
;             PG8_LDB(B1, 1, 1); PG8_STAGE(PG8_SB(1, 0), b3);
;             PG8_BAR; PG8_WAIT_L(0); PG8_MMA(0, 1, At, B1); PG8_BAR;
;             PG8_LDA(At, 1, 1); PG8_STAGE(PG8_SA(1, 0), a3);
;             PG8_BAR; PG8_WAIT_L(0); PG8_MMA(1, 0, At, B0); PG8_BAR; PG8_SCHED;
	s_nop 0
	global_load_lds_dwordx4 v[128:129], off
	v_lshl_add_u64 v[128:129], s[38:39], 0, v[142:143]
	s_add_i32 m0, s37, 0x2000
	s_nop 0
	global_load_lds_dwordx4 v[128:129], off
	s_waitcnt vmcnt(6)
	s_setprio 1
	s_barrier
	v_mfma_f32_16x16x32_bf16 v[52:55], v[234:237], v[194:197], v[52:55]
	v_mfma_f32_16x16x32_bf16 v[48:51], v[242:245], v[194:197], v[48:51]
	v_mfma_f32_16x16x32_bf16 v[36:39], v[234:237], v[202:205], v[36:39]
	v_mfma_f32_16x16x32_bf16 v[32:35], v[242:245], v[202:205], v[32:35]
	v_mfma_f32_16x16x32_bf16 v[20:23], v[234:237], v[210:213], v[20:23]
	v_mfma_f32_16x16x32_bf16 v[16:19], v[242:245], v[210:213], v[16:19]
	v_mfma_f32_16x16x32_bf16 v[4:7], v[234:237], v[226:229], v[4:7]
	v_mfma_f32_16x16x32_bf16 v[0:3], v[242:245], v[226:229], v[0:3]
	v_mfma_f32_16x16x32_bf16 v[52:55], v[238:241], v[198:201], v[52:55]
	v_mfma_f32_16x16x32_bf16 v[48:51], v[246:249], v[198:201], v[48:51]
	v_mfma_f32_16x16x32_bf16 v[36:39], v[238:241], v[206:209], v[36:39]
	v_mfma_f32_16x16x32_bf16 v[32:35], v[246:249], v[206:209], v[32:35]
	s_add_i32 s37, 0, 0x18000
	v_add_u32_e32 v158, s37, v187
	v_mfma_f32_16x16x32_bf16 v[20:23], v[238:241], v[214:217], v[20:23]
	v_mfma_f32_16x16x32_bf16 v[16:19], v[246:249], v[214:217], v[16:19]
	v_mfma_f32_16x16x32_bf16 v[4:7], v[238:241], v[230:233], v[4:7]
	v_mfma_f32_16x16x32_bf16 v[0:3], v[246:249], v[230:233], v[0:3]
	s_setprio 0
	s_barrier
	ds_read_b128 v[128:131], v158
	ds_read_b128 v[132:135], v158 offset:1024
	ds_read_b128 v[136:139], v158 offset:2048
	ds_read_b128 v[190:193], v158 offset:3072
	s_add_u32 s20, s20, 0x80000
	s_addc_u32 s21, s21, 0
	s_mov_b32 m0, s28
	v_lshl_add_u64 v[234:235], s[20:21], 0, v[144:145]
	ds_read_b128 v[194:197], v189 offset:32768
	ds_read_b128 v[198:201], v189 offset:33792
	ds_read_b128 v[202:205], v189 offset:34816
	ds_read_b128 v[206:209], v189 offset:35840
	ds_read_b128 v[210:213], v189 offset:36864
	ds_read_b128 v[214:217], v189 offset:37888
	ds_read_b128 v[226:229], v189 offset:38912
	ds_read_b128 v[230:233], v189 offset:39936
	global_load_lds_dwordx4 v[234:235], off
	v_lshl_add_u64 v[234:235], s[20:21], 0, v[142:143]
	s_mov_b32 m0, s29
	s_nop 0
	global_load_lds_dwordx4 v[234:235], off
	s_waitcnt lgkmcnt(8)
	s_setprio 1
	s_barrier
	s_waitcnt lgkmcnt(0)
	v_mfma_f32_16x16x32_bf16 v[124:127], v[128:131], v[194:197], v[124:127]
	v_mfma_f32_16x16x32_bf16 v[120:123], v[136:139], v[194:197], v[120:123]
	v_mfma_f32_16x16x32_bf16 v[108:111], v[128:131], v[202:205], v[108:111]
	v_mfma_f32_16x16x32_bf16 v[104:107], v[136:139], v[202:205], v[104:107]
	v_mfma_f32_16x16x32_bf16 v[92:95], v[128:131], v[210:213], v[92:95]
	v_mfma_f32_16x16x32_bf16 v[88:91], v[136:139], v[210:213], v[88:91]
	v_mfma_f32_16x16x32_bf16 v[76:79], v[128:131], v[226:229], v[76:79]
	v_mfma_f32_16x16x32_bf16 v[72:75], v[136:139], v[226:229], v[72:75]
	v_mfma_f32_16x16x32_bf16 v[124:127], v[132:135], v[198:201], v[124:127]
	v_mfma_f32_16x16x32_bf16 v[120:123], v[190:193], v[198:201], v[120:123]
	v_mfma_f32_16x16x32_bf16 v[108:111], v[132:135], v[206:209], v[108:111]
	v_mfma_f32_16x16x32_bf16 v[104:107], v[190:193], v[206:209], v[104:107]
	s_add_i32 s20, 0, 0x1c000
	s_add_i32 s21, s37, s25
	v_add_u32_e32 v158, s20, v187
	v_lshl_add_u64 v[140:141], v[140:141], 0, s[94:95]
	s_mov_b32 m0, s21
	v_mfma_f32_16x16x32_bf16 v[92:95], v[132:135], v[214:217], v[92:95]
	v_mfma_f32_16x16x32_bf16 v[88:91], v[190:193], v[214:217], v[88:91]
	v_mfma_f32_16x16x32_bf16 v[76:79], v[132:135], v[230:233], v[76:79]
	v_mfma_f32_16x16x32_bf16 v[72:75], v[190:193], v[230:233], v[72:75]
	s_setprio 0
	s_barrier
	ds_read_b128 v[234:237], v158
	ds_read_b128 v[238:241], v158 offset:1024
	ds_read_b128 v[242:245], v158 offset:2048
	ds_read_b128 v[246:249], v158 offset:3072
	global_load_lds_dwordx4 v[140:141], off
	v_lshl_add_u64 v[140:141], v[154:155], 0, s[94:95]
	s_add_i32 m0, s21, 0x2000
	s_nop 0
	global_load_lds_dwordx4 v[140:141], off
	s_waitcnt lgkmcnt(0)
	s_setprio 1
	s_barrier
	v_mfma_f32_16x16x32_bf16 v[116:119], v[234:237], v[194:197], v[116:119]
	v_mfma_f32_16x16x32_bf16 v[112:115], v[242:245], v[194:197], v[112:115]
	v_mfma_f32_16x16x32_bf16 v[100:103], v[234:237], v[202:205], v[100:103]
	v_mfma_f32_16x16x32_bf16 v[96:99], v[242:245], v[202:205], v[96:99]
	v_mfma_f32_16x16x32_bf16 v[84:87], v[234:237], v[210:213], v[84:87]
	v_mfma_f32_16x16x32_bf16 v[80:83], v[242:245], v[210:213], v[80:83]
	v_mfma_f32_16x16x32_bf16 v[68:71], v[234:237], v[226:229], v[68:71]
	v_mfma_f32_16x16x32_bf16 v[64:67], v[242:245], v[226:229], v[64:67]
	v_mfma_f32_16x16x32_bf16 v[116:119], v[238:241], v[198:201], v[116:119]
	v_mfma_f32_16x16x32_bf16 v[112:115], v[246:249], v[198:201], v[112:115]
	v_mfma_f32_16x16x32_bf16 v[100:103], v[238:241], v[206:209], v[100:103]
	v_mfma_f32_16x16x32_bf16 v[96:99], v[246:249], v[206:209], v[96:99]
	s_mov_b32 m0, s30
	v_lshl_add_u64 v[140:141], v[218:219], 0, s[94:95]
	v_mfma_f32_16x16x32_bf16 v[84:87], v[238:241], v[214:217], v[84:87]
	v_mfma_f32_16x16x32_bf16 v[80:83], v[246:249], v[214:217], v[80:83]
	v_mfma_f32_16x16x32_bf16 v[68:71], v[238:241], v[230:233], v[68:71]
	v_mfma_f32_16x16x32_bf16 v[64:67], v[246:249], v[230:233], v[64:67]
	s_setprio 0
	s_barrier
; #define PG8_STAGE(bufoff, gbase) do { _Pragma("unroll") for (int _i = 0; _i < 2; ++_i) \
;         __builtin_amdgcn_global_load_lds((const unsigned*)((const char*)(gbase) + voff[_i]), (LAS unsigned*)(lds + (bufoff) + ldsw + _i * 8192), 16, 0, 0); } while (0)
; #define PG8_MMA(ai, bj, At, Bt) do { __builtin_amdgcn_s_setprio(1); _Pragma("unroll") for (int m = 0; m < 4; ++m) _Pragma("unroll") for (int n = 0; n < 2; ++n) _Pragma("unroll") for (int k = 0; k < 2; ++k) \
;         acc[ai][bj][m][n] = __builtin_amdgcn_mfma_f32_16x16x32_bf16(Bt[n][k], At[m][k], acc[ai][bj][m][n], 0, 0, 0); __builtin_amdgcn_s_setprio(0); } while (0)
; #define PG8_WAIT_V(n) asm volatile("s_waitcnt vmcnt(" #n ")" ::: "memory")
; #define PG8_WAIT_L(n) asm volatile("s_waitcnt lgkmcnt(" #n ")" ::: "memory")
; #define PG8_BAR __builtin_amdgcn_s_barrier()
; #define PG8_SCHED __builtin_amdgcn_sched_barrier(0)
; template <class Epi>
; DI void gemm_phase(LAS unsigned char* lds, const Gemm g, const StaticOrder& S, const Epi& E) {
;     ...
;             PG8_BAR; PG8_WAIT_L(0); PG8_MMA(1, 0, At, B0); PG8_BAR; PG8_SCHED;
;             PG8_STAGE(PG8_SB(1, 1), b3 + hstep);
;             PG8_WAIT_V(6); PG8_BAR; PG8_MMA(1, 1, At, B1); PG8_BAR;
;         }
;     DI void operator()(const f32x4 (&acc)[2][2][4][2], const Unit& u, int wr, int wc, int fr, int fq) const {
;         const int row0 = u.pm * BM + wr * 64 + fr, col0 = u.pn * BM + wc * 16 + 4 * fq;
;         const bool rot = u.pn < 18;
; #pragma unroll
;         for (int ai = 0; ai < 2; ++ai)
; #pragma unroll
;             for (int m = 0; m < 4; ++m) { const int row = row0 + ai * HALF + m * 16; u16* rowp = O + (size_t)row * NQKV_DIL + col0;
;                 f32x4 c4 = (f32x4){1.f, 1.f, 1.f, 1.f}, s4 = (f32x4){0.f, 0.f, 0.f, 0.f};
;                 if (rot) { const int pos = row & (SEQ - 1); c4 = *(const f32x4*)(cs + pos * 64 + wc * 16 + 4 * fq); s4 = *(const f32x4*)(sn + pos * 64 + wc * 16 + 4 * fq); }
	ds_read_b128 v[194:197], v189 offset:49152
	ds_read_b128 v[198:201], v189 offset:50176
	ds_read_b128 v[202:205], v189 offset:51200
	ds_read_b128 v[206:209], v189 offset:52224
	ds_read_b128 v[210:213], v189 offset:53248
	ds_read_b128 v[214:217], v189 offset:54272
	ds_read_b128 v[226:229], v189 offset:55296
	ds_read_b128 v[230:233], v189 offset:56320
	global_load_lds_dwordx4 v[140:141], off
	v_lshl_add_u64 v[140:141], v[250:251], 0, s[94:95]
	s_mov_b32 m0, s31
	s_nop 0
	global_load_lds_dwordx4 v[140:141], off
	s_waitcnt lgkmcnt(0)
	s_setprio 1
	s_barrier
	v_mfma_f32_16x16x32_bf16 v[60:63], v[128:131], v[194:197], v[60:63]
	v_mfma_f32_16x16x32_bf16 v[56:59], v[136:139], v[194:197], v[56:59]
	v_mfma_f32_16x16x32_bf16 v[44:47], v[128:131], v[202:205], v[44:47]
	v_mfma_f32_16x16x32_bf16 v[40:43], v[136:139], v[202:205], v[40:43]
	v_mfma_f32_16x16x32_bf16 v[28:31], v[128:131], v[210:213], v[28:31]
	v_mfma_f32_16x16x32_bf16 v[24:27], v[136:139], v[210:213], v[24:27]
	v_mfma_f32_16x16x32_bf16 v[12:15], v[128:131], v[226:229], v[12:15]
	v_mfma_f32_16x16x32_bf16 v[8:11], v[136:139], v[226:229], v[8:11]
	v_mfma_f32_16x16x32_bf16 v[60:63], v[132:135], v[198:201], v[60:63]
	v_mfma_f32_16x16x32_bf16 v[56:59], v[190:193], v[198:201], v[56:59]
	v_mfma_f32_16x16x32_bf16 v[44:47], v[132:135], v[206:209], v[44:47]
	v_mfma_f32_16x16x32_bf16 v[40:43], v[190:193], v[206:209], v[40:43]
	s_add_u32 s18, s18, 0x80080
	s_addc_u32 s19, s19, 0
	s_add_i32 s20, s20, s25
	v_lshl_add_u64 v[128:129], s[18:19], 0, v[144:145]
	s_mov_b32 m0, s20
	v_mfma_f32_16x16x32_bf16 v[28:31], v[132:135], v[214:217], v[28:31]
	v_mfma_f32_16x16x32_bf16 v[24:27], v[190:193], v[214:217], v[24:27]
	v_mfma_f32_16x16x32_bf16 v[12:15], v[132:135], v[230:233], v[12:15]
	v_mfma_f32_16x16x32_bf16 v[8:11], v[190:193], v[230:233], v[8:11]
	s_setprio 0
	s_barrier
	s_nop 0
	global_load_lds_dwordx4 v[128:129], off
	v_lshl_add_u64 v[128:129], s[18:19], 0, v[142:143]
	s_add_i32 m0, s20, 0x2000
	s_nop 0
	global_load_lds_dwordx4 v[128:129], off
	s_waitcnt vmcnt(6)
	s_setprio 1
	s_barrier
	v_mfma_f32_16x16x32_bf16 v[52:55], v[234:237], v[194:197], v[52:55]
	v_mfma_f32_16x16x32_bf16 v[48:51], v[242:245], v[194:197], v[48:51]
	v_mfma_f32_16x16x32_bf16 v[36:39], v[234:237], v[202:205], v[36:39]
	v_mfma_f32_16x16x32_bf16 v[32:35], v[242:245], v[202:205], v[32:35]
	v_mfma_f32_16x16x32_bf16 v[20:23], v[234:237], v[210:213], v[20:23]
	v_mfma_f32_16x16x32_bf16 v[16:19], v[242:245], v[210:213], v[16:19]
	v_mfma_f32_16x16x32_bf16 v[4:7], v[234:237], v[226:229], v[4:7]
	v_mfma_f32_16x16x32_bf16 v[0:3], v[242:245], v[226:229], v[0:3]
	v_mfma_f32_16x16x32_bf16 v[52:55], v[238:241], v[198:201], v[52:55]
	v_mfma_f32_16x16x32_bf16 v[48:51], v[246:249], v[198:201], v[48:51]
	v_mfma_f32_16x16x32_bf16 v[36:39], v[238:241], v[206:209], v[36:39]
	v_mfma_f32_16x16x32_bf16 v[32:35], v[246:249], v[206:209], v[32:35]
	s_add_i32 s36, s36, 2
	s_add_u32 s8, s8, 0x100
	s_addc_u32 s9, s9, 0
	s_add_u32 s33, s33, 0x100
	s_addc_u32 s35, s35, 0
	s_cmp_gt_u32 s36, 29
	v_mfma_f32_16x16x32_bf16 v[20:23], v[238:241], v[214:217], v[20:23]
	v_mfma_f32_16x16x32_bf16 v[16:19], v[246:249], v[214:217], v[16:19]
	v_mfma_f32_16x16x32_bf16 v[4:7], v[238:241], v[230:233], v[4:7]
	v_mfma_f32_16x16x32_bf16 v[0:3], v[246:249], v[230:233], v[0:3]
	s_setprio 0
	s_barrier
	s_cbranch_scc0 .LBB0_202
	s_cmp_lt_i32 s2, 18
	v_lshl_add_u32 v190, s3, 8, v186
	v_mov_b32_e32 v128, 1.0
	v_mov_b32_e32 v132, 0
	s_cselect_b64 s[18:19], -1, 0
	s_cmp_gt_i32 s2, 17
	v_mov_b32_e32 v134, 0
	v_mov_b32_e32 v135, 0
	v_mov_b32_e32 v136, 0
	v_mov_b32_e32 v137, 0
	v_mov_b32_e32 v138, 1.0
	v_mov_b32_e32 v139, 1.0
	v_mov_b32_e32 v140, 1.0
	v_mov_b32_e32 v141, 1.0
	s_cbranch_scc1 .LBB0_205
	v_lshlrev_b32_e32 v129, 8, v190
	v_and_b32_e32 v158, 0xfcf00, v129
	v_lshl_add_u64 v[130:131], v[146:147], 0, v[158:159]
	v_lshl_add_u64 v[134:135], v[148:149], 0, v[158:159]
	global_load_dwordx4 v[138:141], v[130:131], off
	s_nop 0
	global_load_dwordx4 v[134:137], v[134:135], off

; #define PG8_STAGE(bufoff, gbase) do { _Pragma("unroll") for (int _i = 0; _i < 2; ++_i) \
;         __builtin_amdgcn_global_load_lds((const unsigned*)((const char*)(gbase) + voff[_i]), (LAS unsigned*)(lds + (bufoff) + ldsw + _i * 8192), 16, 0, 0); } while (0)
; #define PG8_LDA(dst, b, h) do { _Pragma("unroll") for (int m = 0; m < 4; ++m) _Pragma("unroll") for (int k = 0; k < 2; ++k) dst[m][k] = *(const LAS bf16x8*)(lds + PG8_SA(b, h) + aoff + m * 2048 + k * 1024); } while (0)
; #define PG8_LDB(dst, b, h) do { _Pragma("unroll") for (int n = 0; n < 2; ++n) _Pragma("unroll") for (int k = 0; k < 2; ++k) dst[n][k] = *(const LAS bf16x8*)(lds + PG8_SB(b, h) + boff + n * 2048 + k * 1024); } while (0)
; #define PG8_MMA(ai, bj, At, Bt) do { __builtin_amdgcn_s_setprio(1); _Pragma("unroll") for (int m = 0; m < 4; ++m) _Pragma("unroll") for (int n = 0; n < 2; ++n) _Pragma("unroll") for (int k = 0; k < 2; ++k) \
;         acc[ai][bj][m][n] = __builtin_amdgcn_mfma_f32_16x16x32_bf16(Bt[n][k], At[m][k], acc[ai][bj][m][n], 0, 0, 0); __builtin_amdgcn_s_setprio(0); } while (0)
; #define PG8_WAIT_V(n) asm volatile("s_waitcnt vmcnt(" #n ")" ::: "memory")
; #define PG8_WAIT_L(n) asm volatile("s_waitcnt lgkmcnt(" #n ")" ::: "memory")
; #define PG8_BAR __builtin_amdgcn_s_barrier()
; #define PG8_SCHED __builtin_amdgcn_sched_barrier(0)
; template <class Epi>
; DI void gemm_phase(LAS unsigned char* lds, const Gemm g, const StaticOrder& S, const Epi& E) {
;     ...
;         for (int t = 0; t < nt; t += 2) {
;             const bool last = (t == nt - 2);
;             const char* a1 = cA + (size_t)(t + 1) * kstep;
;             const char* a2 = last ? nA : cA + (size_t)(t + 2) * kstep; const char* b2 = last ? nB : cB + (size_t)(t + 2) * kstep;
;             const char* a3 = a2 + kstep; const char* b3 = b2 + kstep;
;             PG8_LDB(B0, 0, 0); PG8_SCHED; PG8_LDA(At, 0, 0); PG8_STAGE(PG8_SA(1, 1), a1 + hstep);
;             PG8_WAIT_L(8); PG8_BAR; PG8_WAIT_L(0); PG8_MMA(0, 0, At, B0); PG8_BAR; PG8_SCHED;
;             PG8_LDB(B1, 0, 1); PG8_STAGE(PG8_SB(0, 0), b2);
;             PG8_BAR; PG8_WAIT_L(0); PG8_MMA(0, 1, At, B1); PG8_BAR;
;             PG8_LDA(At, 0, 1); PG8_STAGE(PG8_SA(0, 0), a2);
;             PG8_BAR; PG8_WAIT_L(0); PG8_MMA(1, 0, At, B0); PG8_BAR; PG8_SCHED;
;             PG8_STAGE(PG8_SB(0, 1), b2 + hstep);
;             PG8_WAIT_V(6); PG8_BAR; PG8_MMA(1, 1, At, B1); PG8_BAR;
.LBB0_231:
	s_add_u32 s18, s16, 0xfff80080
	s_addc_u32 s19, s17, -1
	s_add_i32 s37, 0, 0x10000
	v_add_u32_e32 v150, s37, v135
	ds_read_b128 v[138:141], v150
	ds_read_b128 v[142:145], v150 offset:1024
	ds_read_b128 v[146:149], v150 offset:2048
	ds_read_b128 v[150:153], v150 offset:3072
	s_cmp_eq_u32 s36, 28
	s_cselect_b32 s21, s4, s19
	s_cselect_b32 s20, s5, s18
	s_cselect_b32 s19, s9, s35
	s_cselect_b32 s18, s11, s34
	v_lshl_add_u64 v[154:155], s[16:17], 0, v[130:131]
	s_add_i32 m0, s24, 0xc000
	ds_read_b128 v[186:189], v137
	ds_read_b128 v[190:193], v137 offset:1024
	ds_read_b128 v[194:197], v137 offset:2048
	ds_read_b128 v[198:201], v137 offset:3072
	ds_read_b128 v[202:205], v137 offset:4096
	ds_read_b128 v[206:209], v137 offset:5120
	ds_read_b128 v[210:213], v137 offset:6144
	ds_read_b128 v[214:217], v137 offset:7168
	global_load_lds_dwordx4 v[154:155], off
	v_lshl_add_u64 v[154:155], s[16:17], 0, v[132:133]
	s_add_i32 m0, s24, 0xe000
	s_nop 0
	global_load_lds_dwordx4 v[154:155], off
	s_waitcnt lgkmcnt(8)
	s_setprio 1
	s_barrier
	s_waitcnt lgkmcnt(0)
	v_mfma_f32_16x16x32_bf16 v[124:127], v[138:141], v[186:189], v[124:127]
	v_mfma_f32_16x16x32_bf16 v[120:123], v[146:149], v[186:189], v[120:123]
	v_mfma_f32_16x16x32_bf16 v[116:119], v[138:141], v[194:197], v[116:119]
	v_mfma_f32_16x16x32_bf16 v[112:115], v[146:149], v[194:197], v[112:115]
	v_mfma_f32_16x16x32_bf16 v[100:103], v[138:141], v[202:205], v[100:103]
	v_mfma_f32_16x16x32_bf16 v[96:99], v[146:149], v[202:205], v[96:99]
	v_mfma_f32_16x16x32_bf16 v[84:87], v[138:141], v[210:213], v[84:87]
	v_mfma_f32_16x16x32_bf16 v[80:83], v[146:149], v[210:213], v[80:83]
	v_mfma_f32_16x16x32_bf16 v[124:127], v[142:145], v[190:193], v[124:127]
	v_mfma_f32_16x16x32_bf16 v[120:123], v[150:153], v[190:193], v[120:123]
	v_mfma_f32_16x16x32_bf16 v[116:119], v[142:145], v[198:201], v[116:119]
	v_mfma_f32_16x16x32_bf16 v[112:115], v[150:153], v[198:201], v[112:115]
	s_add_i32 s40, 0, 0x14000
	v_add_u32_e32 v154, s40, v135
	s_add_i32 s37, s37, s23
	v_mfma_f32_16x16x32_bf16 v[100:103], v[142:145], v[206:209], v[100:103]
	v_mfma_f32_16x16x32_bf16 v[96:99], v[150:153], v[206:209], v[96:99]
	v_mfma_f32_16x16x32_bf16 v[84:87], v[142:145], v[214:217], v[84:87]
	v_mfma_f32_16x16x32_bf16 v[80:83], v[150:153], v[214:217], v[80:83]
	s_setprio 0
	s_barrier
	ds_read_b128 v[226:229], v154
	ds_read_b128 v[230:233], v154 offset:1024
	ds_read_b128 v[234:237], v154 offset:2048
	ds_read_b128 v[238:241], v154 offset:3072
	v_lshl_add_u64 v[154:155], s[18:19], 0, v[158:159]
	s_mov_b32 m0, s37
	v_lshl_add_u64 v[218:219], s[18:19], 0, v[128:129]
	global_load_lds_dwordx4 v[154:155], off
	s_add_i32 m0, s37, 0x2000
	s_nop 0
	global_load_lds_dwordx4 v[218:219], off
	s_waitcnt lgkmcnt(0)
	s_setprio 1
	s_barrier
	v_mfma_f32_16x16x32_bf16 v[108:111], v[226:229], v[186:189], v[108:111]
	v_mfma_f32_16x16x32_bf16 v[104:107], v[234:237], v[186:189], v[104:107]
	v_mfma_f32_16x16x32_bf16 v[92:95], v[226:229], v[194:197], v[92:95]
	v_mfma_f32_16x16x32_bf16 v[88:91], v[234:237], v[194:197], v[88:91]
	v_mfma_f32_16x16x32_bf16 v[76:79], v[226:229], v[202:205], v[76:79]
	v_mfma_f32_16x16x32_bf16 v[72:75], v[234:237], v[202:205], v[72:75]
	v_mfma_f32_16x16x32_bf16 v[68:71], v[226:229], v[210:213], v[68:71]
	v_mfma_f32_16x16x32_bf16 v[64:67], v[234:237], v[210:213], v[64:67]
	v_mfma_f32_16x16x32_bf16 v[108:111], v[230:233], v[190:193], v[108:111]
	v_mfma_f32_16x16x32_bf16 v[104:107], v[238:241], v[190:193], v[104:107]
	v_mfma_f32_16x16x32_bf16 v[92:95], v[230:233], v[198:201], v[92:95]
	v_mfma_f32_16x16x32_bf16 v[88:91], v[238:241], v[198:201], v[88:91]
	s_mov_b32 m0, s24
	v_lshl_add_u64 v[242:243], s[20:21], 0, v[158:159]
	v_mfma_f32_16x16x32_bf16 v[76:79], v[230:233], v[206:209], v[76:79]
	v_mfma_f32_16x16x32_bf16 v[72:75], v[238:241], v[206:209], v[72:75]
	v_mfma_f32_16x16x32_bf16 v[68:71], v[230:233], v[214:217], v[68:71]
	v_mfma_f32_16x16x32_bf16 v[64:67], v[238:241], v[214:217], v[64:67]
	s_setprio 0
	s_barrier
	ds_read_b128 v[186:189], v137 offset:16384
	ds_read_b128 v[190:193], v137 offset:17408
	ds_read_b128 v[194:197], v137 offset:18432
	ds_read_b128 v[198:201], v137 offset:19456
	ds_read_b128 v[202:205], v137 offset:20480
	ds_read_b128 v[206:209], v137 offset:21504
	ds_read_b128 v[210:213], v137 offset:22528
	ds_read_b128 v[214:217], v137 offset:23552
	global_load_lds_dwordx4 v[242:243], off
	v_lshl_add_u64 v[244:245], s[20:21], 0, v[128:129]
	s_mov_b32 m0, s25
	s_nop 0
	global_load_lds_dwordx4 v[244:245], off
	s_waitcnt lgkmcnt(0)
	s_setprio 1
	s_barrier
	v_mfma_f32_16x16x32_bf16 v[60:63], v[138:141], v[186:189], v[60:63]
	v_mfma_f32_16x16x32_bf16 v[56:59], v[146:149], v[186:189], v[56:59]
	v_mfma_f32_16x16x32_bf16 v[52:55], v[138:141], v[194:197], v[52:55]
	v_mfma_f32_16x16x32_bf16 v[48:51], v[146:149], v[194:197], v[48:51]
	v_mfma_f32_16x16x32_bf16 v[36:39], v[138:141], v[202:205], v[36:39]
	v_mfma_f32_16x16x32_bf16 v[32:35], v[146:149], v[202:205], v[32:35]
	v_mfma_f32_16x16x32_bf16 v[20:23], v[138:141], v[210:213], v[20:23]
	v_mfma_f32_16x16x32_bf16 v[16:19], v[146:149], v[210:213], v[16:19]
	v_mfma_f32_16x16x32_bf16 v[60:63], v[142:145], v[190:193], v[60:63]
	v_mfma_f32_16x16x32_bf16 v[56:59], v[150:153], v[190:193], v[56:59]
	v_mfma_f32_16x16x32_bf16 v[52:55], v[142:145], v[198:201], v[52:55]
	v_mfma_f32_16x16x32_bf16 v[48:51], v[150:153], v[198:201], v[48:51]
	s_add_u32 s38, s18, 0x80000
	s_addc_u32 s39, s19, 0
	s_add_i32 s37, s40, s23
	v_lshl_add_u64 v[138:139], s[38:39], 0, v[158:159]
	s_mov_b32 m0, s37
	v_mfma_f32_16x16x32_bf16 v[36:39], v[142:145], v[206:209], v[36:39]
	v_mfma_f32_16x16x32_bf16 v[32:35], v[150:153], v[206:209], v[32:35]
	v_mfma_f32_16x16x32_bf16 v[20:23], v[142:145], v[214:217], v[20:23]
	v_mfma_f32_16x16x32_bf16 v[16:19], v[150:153], v[214:217], v[16:19]
	s_setprio 0
	s_barrier
; #define PG8_STAGE(bufoff, gbase) do { _Pragma("unroll") for (int _i = 0; _i < 2; ++_i) \
;         __builtin_amdgcn_global_load_lds((const unsigned*)((const char*)(gbase) + voff[_i]), (LAS unsigned*)(lds + (bufoff) + ldsw + _i * 8192), 16, 0, 0); } while (0)
; #define PG8_LDA(dst, b, h) do { _Pragma("unroll") for (int m = 0; m < 4; ++m) _Pragma("unroll") for (int k = 0; k < 2; ++k) dst[m][k] = *(const LAS bf16x8*)(lds + PG8_SA(b, h) + aoff + m * 2048 + k * 1024); } while (0)
; #define PG8_LDB(dst, b, h) do { _Pragma("unroll") for (int n = 0; n < 2; ++n) _Pragma("unroll") for (int k = 0; k < 2; ++k) dst[n][k] = *(const LAS bf16x8*)(lds + PG8_SB(b, h) + boff + n * 2048 + k * 1024); } while (0)
; #define PG8_MMA(ai, bj, At, Bt) do { __builtin_amdgcn_s_setprio(1); _Pragma("unroll") for (int m = 0; m < 4; ++m) _Pragma("unroll") for (int n = 0; n < 2; ++n) _Pragma("unroll") for (int k = 0; k < 2; ++k) \
;         acc[ai][bj][m][n] = __builtin_amdgcn_mfma_f32_16x16x32_bf16(Bt[n][k], At[m][k], acc[ai][bj][m][n], 0, 0, 0); __builtin_amdgcn_s_setprio(0); } while (0)
; #define PG8_WAIT_V(n) asm volatile("s_waitcnt vmcnt(" #n ")" ::: "memory")
; #define PG8_WAIT_L(n) asm volatile("s_waitcnt lgkmcnt(" #n ")" ::: "memory")
; #define PG8_BAR __builtin_amdgcn_s_barrier()
; #define PG8_SCHED __builtin_amdgcn_sched_barrier(0)
; template <class Epi>
; DI void gemm_phase(LAS unsigned char* lds, const Gemm g, const StaticOrder& S, const Epi& E) {
;     ...
;             PG8_BAR; PG8_WAIT_L(0); PG8_MMA(1, 0, At, B0); PG8_BAR; PG8_SCHED;
;             PG8_STAGE(PG8_SB(0, 1), b2 + hstep);
;             PG8_WAIT_V(6); PG8_BAR; PG8_MMA(1, 1, At, B1); PG8_BAR;
;             PG8_LDB(B0, 1, 0); PG8_SCHED; PG8_LDA(At, 1, 0); PG8_STAGE(PG8_SA(0, 1), a2 + hstep);
;             PG8_WAIT_L(8); PG8_BAR; PG8_WAIT_L(0); PG8_MMA(0, 0, At, B0); PG8_BAR; PG8_SCHED;
;             PG8_LDB(B1, 1, 1); PG8_STAGE(PG8_SB(1, 0), b3);
;             PG8_BAR; PG8_WAIT_L(0); PG8_MMA(0, 1, At, B1); PG8_BAR;
;             PG8_LDA(At, 1, 1); PG8_STAGE(PG8_SA(1, 0), a3);
;             PG8_BAR; PG8_WAIT_L(0); PG8_MMA(1, 0, At, B0); PG8_BAR; PG8_SCHED;
	s_nop 0
	global_load_lds_dwordx4 v[138:139], off
	v_lshl_add_u64 v[138:139], s[38:39], 0, v[128:129]
	s_add_i32 m0, s37, 0x2000
	s_nop 0
	global_load_lds_dwordx4 v[138:139], off
	s_waitcnt vmcnt(6)
	s_setprio 1
	s_barrier
	v_mfma_f32_16x16x32_bf16 v[44:47], v[226:229], v[186:189], v[44:47]
	v_mfma_f32_16x16x32_bf16 v[40:43], v[234:237], v[186:189], v[40:43]
	v_mfma_f32_16x16x32_bf16 v[28:31], v[226:229], v[194:197], v[28:31]
	v_mfma_f32_16x16x32_bf16 v[24:27], v[234:237], v[194:197], v[24:27]
	v_mfma_f32_16x16x32_bf16 v[12:15], v[226:229], v[202:205], v[12:15]
	v_mfma_f32_16x16x32_bf16 v[8:11], v[234:237], v[202:205], v[8:11]
	v_mfma_f32_16x16x32_bf16 v[4:7], v[226:229], v[210:213], v[4:7]
	v_mfma_f32_16x16x32_bf16 v[0:3], v[234:237], v[210:213], v[0:3]
	v_mfma_f32_16x16x32_bf16 v[44:47], v[230:233], v[190:193], v[44:47]
	v_mfma_f32_16x16x32_bf16 v[40:43], v[238:241], v[190:193], v[40:43]
	v_mfma_f32_16x16x32_bf16 v[28:31], v[230:233], v[198:201], v[28:31]
	v_mfma_f32_16x16x32_bf16 v[24:27], v[238:241], v[198:201], v[24:27]
	s_add_i32 s37, 0, 0x18000
	v_add_u32_e32 v150, s37, v135
	v_mfma_f32_16x16x32_bf16 v[12:15], v[230:233], v[206:209], v[12:15]
	v_mfma_f32_16x16x32_bf16 v[8:11], v[238:241], v[206:209], v[8:11]
	v_mfma_f32_16x16x32_bf16 v[4:7], v[230:233], v[214:217], v[4:7]
	v_mfma_f32_16x16x32_bf16 v[0:3], v[238:241], v[214:217], v[0:3]
	s_setprio 0
	s_barrier
	ds_read_b128 v[138:141], v150
	ds_read_b128 v[142:145], v150 offset:1024
	ds_read_b128 v[146:149], v150 offset:2048
	ds_read_b128 v[150:153], v150 offset:3072
	s_add_u32 s20, s20, 0x80000
	s_addc_u32 s21, s21, 0
	s_mov_b32 m0, s26
	v_lshl_add_u64 v[226:227], s[20:21], 0, v[158:159]
	ds_read_b128 v[186:189], v137 offset:32768
	ds_read_b128 v[190:193], v137 offset:33792
	ds_read_b128 v[194:197], v137 offset:34816
	ds_read_b128 v[198:201], v137 offset:35840
	ds_read_b128 v[202:205], v137 offset:36864
	ds_read_b128 v[206:209], v137 offset:37888
	ds_read_b128 v[210:213], v137 offset:38912
	ds_read_b128 v[214:217], v137 offset:39936
	global_load_lds_dwordx4 v[226:227], off
	v_lshl_add_u64 v[226:227], s[20:21], 0, v[128:129]
	s_mov_b32 m0, s27
	s_nop 0
	global_load_lds_dwordx4 v[226:227], off
	s_waitcnt lgkmcnt(8)
	s_setprio 1
	s_barrier
	s_waitcnt lgkmcnt(0)
	v_mfma_f32_16x16x32_bf16 v[124:127], v[138:141], v[186:189], v[124:127]
	v_mfma_f32_16x16x32_bf16 v[120:123], v[146:149], v[186:189], v[120:123]
	v_mfma_f32_16x16x32_bf16 v[116:119], v[138:141], v[194:197], v[116:119]
	v_mfma_f32_16x16x32_bf16 v[112:115], v[146:149], v[194:197], v[112:115]
	v_mfma_f32_16x16x32_bf16 v[100:103], v[138:141], v[202:205], v[100:103]
	v_mfma_f32_16x16x32_bf16 v[96:99], v[146:149], v[202:205], v[96:99]
	v_mfma_f32_16x16x32_bf16 v[84:87], v[138:141], v[210:213], v[84:87]
	v_mfma_f32_16x16x32_bf16 v[80:83], v[146:149], v[210:213], v[80:83]
	v_mfma_f32_16x16x32_bf16 v[124:127], v[142:145], v[190:193], v[124:127]
	v_mfma_f32_16x16x32_bf16 v[120:123], v[150:153], v[190:193], v[120:123]
	v_mfma_f32_16x16x32_bf16 v[116:119], v[142:145], v[198:201], v[116:119]
	v_mfma_f32_16x16x32_bf16 v[112:115], v[150:153], v[198:201], v[112:115]
	s_add_i32 s20, 0, 0x1c000
	s_add_i32 s21, s37, s23
	v_add_u32_e32 v220, s20, v135
	v_lshl_add_u64 v[154:155], v[154:155], 0, s[94:95]
	s_mov_b32 m0, s21
	v_mfma_f32_16x16x32_bf16 v[100:103], v[142:145], v[206:209], v[100:103]
	v_mfma_f32_16x16x32_bf16 v[96:99], v[150:153], v[206:209], v[96:99]
	v_mfma_f32_16x16x32_bf16 v[84:87], v[142:145], v[214:217], v[84:87]
	v_mfma_f32_16x16x32_bf16 v[80:83], v[150:153], v[214:217], v[80:83]
	s_setprio 0
	s_barrier
	ds_read_b128 v[226:229], v220
	ds_read_b128 v[230:233], v220 offset:1024
	ds_read_b128 v[234:237], v220 offset:2048
	ds_read_b128 v[238:241], v220 offset:3072
	global_load_lds_dwordx4 v[154:155], off
	v_lshl_add_u64 v[154:155], v[218:219], 0, s[94:95]
	s_add_i32 m0, s21, 0x2000
	s_nop 0
	global_load_lds_dwordx4 v[154:155], off
	s_waitcnt lgkmcnt(0)
	s_setprio 1
	s_barrier
	v_mfma_f32_16x16x32_bf16 v[108:111], v[226:229], v[186:189], v[108:111]
	v_mfma_f32_16x16x32_bf16 v[104:107], v[234:237], v[186:189], v[104:107]
	v_mfma_f32_16x16x32_bf16 v[92:95], v[226:229], v[194:197], v[92:95]
	v_mfma_f32_16x16x32_bf16 v[88:91], v[234:237], v[194:197], v[88:91]
	v_mfma_f32_16x16x32_bf16 v[76:79], v[226:229], v[202:205], v[76:79]
	v_mfma_f32_16x16x32_bf16 v[72:75], v[234:237], v[202:205], v[72:75]
	v_mfma_f32_16x16x32_bf16 v[68:71], v[226:229], v[210:213], v[68:71]
	v_mfma_f32_16x16x32_bf16 v[64:67], v[234:237], v[210:213], v[64:67]
	v_mfma_f32_16x16x32_bf16 v[108:111], v[230:233], v[190:193], v[108:111]
	v_mfma_f32_16x16x32_bf16 v[104:107], v[238:241], v[190:193], v[104:107]
	v_mfma_f32_16x16x32_bf16 v[92:95], v[230:233], v[198:201], v[92:95]
	v_mfma_f32_16x16x32_bf16 v[88:91], v[238:241], v[198:201], v[88:91]
	s_mov_b32 m0, s28
	v_lshl_add_u64 v[154:155], v[242:243], 0, s[94:95]
	v_mfma_f32_16x16x32_bf16 v[76:79], v[230:233], v[206:209], v[76:79]
	v_mfma_f32_16x16x32_bf16 v[72:75], v[238:241], v[206:209], v[72:75]
	v_mfma_f32_16x16x32_bf16 v[68:71], v[230:233], v[214:217], v[68:71]
	v_mfma_f32_16x16x32_bf16 v[64:67], v[238:241], v[214:217], v[64:67]
	s_setprio 0
	s_barrier
	ds_read_b128 v[186:189], v137 offset:49152
	ds_read_b128 v[190:193], v137 offset:50176
	ds_read_b128 v[194:197], v137 offset:51200
	ds_read_b128 v[198:201], v137 offset:52224
	ds_read_b128 v[202:205], v137 offset:53248
	ds_read_b128 v[206:209], v137 offset:54272
	ds_read_b128 v[210:213], v137 offset:55296
	ds_read_b128 v[214:217], v137 offset:56320
	global_load_lds_dwordx4 v[154:155], off
	v_lshl_add_u64 v[154:155], v[244:245], 0, s[94:95]
	s_mov_b32 m0, s29
	s_nop 0
	global_load_lds_dwordx4 v[154:155], off
	s_waitcnt lgkmcnt(0)
	s_setprio 1
	s_barrier
; #define PG8_STAGE(bufoff, gbase) do { _Pragma("unroll") for (int _i = 0; _i < 2; ++_i) \
;         __builtin_amdgcn_global_load_lds((const unsigned*)((const char*)(gbase) + voff[_i]), (LAS unsigned*)(lds + (bufoff) + ldsw + _i * 8192), 16, 0, 0); } while (0)
; #define PG8_MMA(ai, bj, At, Bt) do { __builtin_amdgcn_s_setprio(1); _Pragma("unroll") for (int m = 0; m < 4; ++m) _Pragma("unroll") for (int n = 0; n < 2; ++n) _Pragma("unroll") for (int k = 0; k < 2; ++k) \
;         acc[ai][bj][m][n] = __builtin_amdgcn_mfma_f32_16x16x32_bf16(Bt[n][k], At[m][k], acc[ai][bj][m][n], 0, 0, 0); __builtin_amdgcn_s_setprio(0); } while (0)
; #define PG8_WAIT_V(n) asm volatile("s_waitcnt vmcnt(" #n ")" ::: "memory")
; #define PG8_WAIT_L(n) asm volatile("s_waitcnt lgkmcnt(" #n ")" ::: "memory")
; #define PG8_BAR __builtin_amdgcn_s_barrier()
; #define PG8_SCHED __builtin_amdgcn_sched_barrier(0)
; template <class Epi>
; DI void gemm_phase(LAS unsigned char* lds, const Gemm g, const StaticOrder& S, const Epi& E) {
;     ...
;             PG8_BAR; PG8_WAIT_L(0); PG8_MMA(1, 0, At, B0); PG8_BAR; PG8_SCHED;
;             PG8_STAGE(PG8_SB(1, 1), b3 + hstep);
;             PG8_WAIT_V(6); PG8_BAR; PG8_MMA(1, 1, At, B1); PG8_BAR;
;         }
	v_mfma_f32_16x16x32_bf16 v[60:63], v[138:141], v[186:189], v[60:63]
	v_mfma_f32_16x16x32_bf16 v[56:59], v[146:149], v[186:189], v[56:59]
	v_mfma_f32_16x16x32_bf16 v[52:55], v[138:141], v[194:197], v[52:55]
	v_mfma_f32_16x16x32_bf16 v[48:51], v[146:149], v[194:197], v[48:51]
	v_mfma_f32_16x16x32_bf16 v[36:39], v[138:141], v[202:205], v[36:39]
	v_mfma_f32_16x16x32_bf16 v[32:35], v[146:149], v[202:205], v[32:35]
	v_mfma_f32_16x16x32_bf16 v[20:23], v[138:141], v[210:213], v[20:23]
	v_mfma_f32_16x16x32_bf16 v[16:19], v[146:149], v[210:213], v[16:19]
	v_mfma_f32_16x16x32_bf16 v[60:63], v[142:145], v[190:193], v[60:63]
	v_mfma_f32_16x16x32_bf16 v[56:59], v[150:153], v[190:193], v[56:59]
	v_mfma_f32_16x16x32_bf16 v[52:55], v[142:145], v[198:201], v[52:55]
	v_mfma_f32_16x16x32_bf16 v[48:51], v[150:153], v[198:201], v[48:51]
	s_add_u32 s18, s18, 0x80080
	s_addc_u32 s19, s19, 0
	s_add_i32 s20, s20, s23
	v_lshl_add_u64 v[138:139], s[18:19], 0, v[158:159]
	s_mov_b32 m0, s20
	v_mfma_f32_16x16x32_bf16 v[36:39], v[142:145], v[206:209], v[36:39]
	v_mfma_f32_16x16x32_bf16 v[32:35], v[150:153], v[206:209], v[32:35]
	v_mfma_f32_16x16x32_bf16 v[20:23], v[142:145], v[214:217], v[20:23]
	v_mfma_f32_16x16x32_bf16 v[16:19], v[150:153], v[214:217], v[16:19]
	s_setprio 0
	s_barrier
	s_nop 0
	global_load_lds_dwordx4 v[138:139], off
	v_lshl_add_u64 v[138:139], s[18:19], 0, v[128:129]
	s_add_i32 m0, s20, 0x2000
	s_nop 0
	global_load_lds_dwordx4 v[138:139], off
	s_waitcnt vmcnt(6)
	s_setprio 1
	s_barrier
	v_mfma_f32_16x16x32_bf16 v[44:47], v[226:229], v[186:189], v[44:47]
	v_mfma_f32_16x16x32_bf16 v[40:43], v[234:237], v[186:189], v[40:43]
	v_mfma_f32_16x16x32_bf16 v[28:31], v[226:229], v[194:197], v[28:31]
	v_mfma_f32_16x16x32_bf16 v[24:27], v[234:237], v[194:197], v[24:27]
	v_mfma_f32_16x16x32_bf16 v[12:15], v[226:229], v[202:205], v[12:15]
	v_mfma_f32_16x16x32_bf16 v[8:11], v[234:237], v[202:205], v[8:11]
	v_mfma_f32_16x16x32_bf16 v[4:7], v[226:229], v[210:213], v[4:7]
	v_mfma_f32_16x16x32_bf16 v[0:3], v[234:237], v[210:213], v[0:3]
	v_mfma_f32_16x16x32_bf16 v[44:47], v[230:233], v[190:193], v[44:47]
	v_mfma_f32_16x16x32_bf16 v[40:43], v[238:241], v[190:193], v[40:43]
	v_mfma_f32_16x16x32_bf16 v[28:31], v[230:233], v[198:201], v[28:31]
	v_mfma_f32_16x16x32_bf16 v[24:27], v[238:241], v[198:201], v[24:27]
	s_add_i32 s36, s36, 2
	s_add_u32 s16, s16, 0x100
	s_addc_u32 s17, s17, 0
	s_add_u32 s34, s34, 0x100
	s_addc_u32 s35, s35, 0
	s_cmp_gt_u32 s36, 29
	v_mfma_f32_16x16x32_bf16 v[12:15], v[230:233], v[206:209], v[12:15]
	v_mfma_f32_16x16x32_bf16 v[8:11], v[238:241], v[206:209], v[8:11]
	v_mfma_f32_16x16x32_bf16 v[4:7], v[230:233], v[214:217], v[4:7]
	v_mfma_f32_16x16x32_bf16 v[0:3], v[238:241], v[214:217], v[0:3]
	s_setprio 0
	s_barrier
	s_cbranch_scc0 .LBB0_231
;     DI void operator()(const f32x4 (&acc)[2][2][4][2], const Unit& u, int wr, int wc, int fr, int fq) const {
;         const int row0 = u.pm * BM + wr * 64 + fr, col0 = u.pn * BM + wc * 32 + 8 * fq;
; #pragma unroll
;         for (int ai = 0; ai < 2; ++ai)
; #pragma unroll
;             for (int m = 0; m < 4; ++m) { u16* rowp = O + (size_t)(row0 + ai * HALF + m * 16) * ldc + col0;
; #pragma unroll
;                 for (int bj = 0; bj < 2; ++bj) { const f32x4 v0 = acc[ai][bj][m][0], v1 = acc[ai][bj][m][1];
;                     *(u32x4*)(rowp + bj * HALF) = (u32x4){pk(v0[0], v0[1]), pk(v0[2], v0[3]), pk(v1[0], v1[1]), pk(v1[2], v1[3])}; } }
;     }
	v_lshl_add_u32 v144, s33, 8, v134
	v_lshl_or_b32 v138, s31, 8, v136
	v_ashrrev_i32_e32 v139, 31, v138
	v_mov_b64_e32 v[140:141], s[50:51]
	s_movk_i32 s9, 0x3000
	v_cvt_pk_bf16_f32 v68, v68, v69
	v_cvt_pk_bf16_f32 v69, v70, v71
	v_cvt_pk_bf16_f32 v70, v64, v65
	v_add_u32_e32 v64, 0x80, v144
	v_mad_i64_i32 v[142:143], s[4:5], v144, s9, v[140:141]
	v_lshlrev_b64 v[138:139], 1, v[138:139]
	v_cvt_pk_bf16_f32 v108, v108, v109
	v_cvt_pk_bf16_f32 v109, v110, v111
	v_cvt_pk_bf16_f32 v110, v104, v105
	v_or_b32_e32 v104, 16, v144
	v_mad_i64_i32 v[64:65], s[4:5], v64, s9, v[140:141]
	v_cvt_pk_bf16_f32 v44, v44, v45
	v_cvt_pk_bf16_f32 v45, v46, v47
	v_cvt_pk_bf16_f32 v46, v40, v41
	v_add_u32_e32 v40, 0x90, v144
	v_lshl_add_u64 v[142:143], v[142:143], 0, v[138:139]
	v_cvt_pk_bf16_f32 v111, v106, v107
	v_mad_i64_i32 v[104:105], s[4:5], v104, s9, v[140:141]
	v_cvt_pk_bf16_f32 v92, v92, v93
	v_cvt_pk_bf16_f32 v93, v94, v95
	v_cvt_pk_bf16_f32 v94, v88, v89
	v_or_b32_e32 v88, 32, v144
	v_lshl_add_u64 v[64:65], v[64:65], 0, v[138:139]
	v_cvt_pk_bf16_f32 v47, v42, v43
	v_mad_i64_i32 v[40:41], s[4:5], v40, s9, v[140:141]
	v_cvt_pk_bf16_f32 v28, v28, v29
	v_cvt_pk_bf16_f32 v29, v30, v31
	v_cvt_pk_bf16_f32 v30, v24, v25
	v_add_u32_e32 v24, 0xa0, v144
	global_store_dwordx4 v[142:143], v[108:111], off offset:256
	v_cvt_pk_bf16_f32 v95, v90, v91
	v_mad_i64_i32 v[88:89], s[4:5], v88, s9, v[140:141]
	v_lshl_add_u64 v[108:109], v[104:105], 0, v[138:139]
	v_cvt_pk_bf16_f32 v76, v76, v77
	v_cvt_pk_bf16_f32 v77, v78, v79
	v_cvt_pk_bf16_f32 v78, v72, v73
	v_or_b32_e32 v72, 48, v144
	global_store_dwordx4 v[64:65], v[44:47], off offset:256
	v_cvt_pk_bf16_f32 v31, v26, v27
	v_mad_i64_i32 v[24:25], s[4:5], v24, s9, v[140:141]
	v_lshl_add_u64 v[44:45], v[40:41], 0, v[138:139]
	v_cvt_pk_bf16_f32 v12, v12, v13
	v_cvt_pk_bf16_f32 v13, v14, v15
	v_cvt_pk_bf16_f32 v14, v8, v9
	v_add_u32_e32 v8, 0xb0, v144
	global_store_dwordx4 v[108:109], v[92:95], off offset:256
	v_cvt_pk_bf16_f32 v79, v74, v75
	v_mad_i64_i32 v[72:73], s[4:5], v72, s9, v[140:141]
	v_lshl_add_u64 v[92:93], v[88:89], 0, v[138:139]
	global_store_dwordx4 v[44:45], v[28:31], off offset:256
	v_cvt_pk_bf16_f32 v15, v10, v11
	v_mad_i64_i32 v[8:9], s[4:5], v8, s9, v[140:141]
	v_lshl_add_u64 v[28:29], v[24:25], 0, v[138:139]
	v_cvt_pk_bf16_f32 v124, v124, v125
	v_cvt_pk_bf16_f32 v125, v126, v127
	v_cvt_pk_bf16_f32 v126, v120, v121
	v_cvt_pk_bf16_f32 v127, v122, v123
	v_cvt_pk_bf16_f32 v104, v116, v117
	v_cvt_pk_bf16_f32 v105, v118, v119
	v_cvt_pk_bf16_f32 v106, v112, v113
	v_cvt_pk_bf16_f32 v107, v114, v115
	v_cvt_pk_bf16_f32 v88, v100, v101
	v_cvt_pk_bf16_f32 v89, v102, v103
	v_cvt_pk_bf16_f32 v90, v96, v97
	v_cvt_pk_bf16_f32 v91, v98, v99
	global_store_dwordx4 v[92:93], v[76:79], off offset:256
	v_cvt_pk_bf16_f32 v74, v80, v81
	v_cvt_pk_bf16_f32 v75, v82, v83
	v_lshl_add_u64 v[76:77], v[72:73], 0, v[138:139]
	v_cvt_pk_bf16_f32 v72, v84, v85
	v_cvt_pk_bf16_f32 v73, v86, v87
	v_cvt_pk_bf16_f32 v71, v66, v67
	v_cvt_pk_bf16_f32 v60, v60, v61
	v_cvt_pk_bf16_f32 v61, v62, v63
	v_cvt_pk_bf16_f32 v62, v56, v57
	v_cvt_pk_bf16_f32 v63, v58, v59
	v_cvt_pk_bf16_f32 v40, v52, v53
	v_cvt_pk_bf16_f32 v41, v54, v55
	v_cvt_pk_bf16_f32 v42, v48, v49
	v_cvt_pk_bf16_f32 v43, v50, v51
	v_cvt_pk_bf16_f32 v24, v36, v37
	v_cvt_pk_bf16_f32 v25, v38, v39
	v_cvt_pk_bf16_f32 v26, v32, v33
	v_cvt_pk_bf16_f32 v27, v34, v35
	global_store_dwordx4 v[28:29], v[12:15], off offset:256
	v_cvt_pk_bf16_f32 v10, v16, v17
	v_cvt_pk_bf16_f32 v11, v18, v19
	v_lshl_add_u64 v[12:13], v[8:9], 0, v[138:139]
	v_cvt_pk_bf16_f32 v8, v20, v21
	v_cvt_pk_bf16_f32 v9, v22, v23
	v_cvt_pk_bf16_f32 v4, v4, v5
	v_cvt_pk_bf16_f32 v5, v6, v7
	v_cvt_pk_bf16_f32 v6, v0, v1
	v_cvt_pk_bf16_f32 v7, v2, v3
	s_and_b64 vcc, exec, s[6:7]
	s_mov_b32 s31, s8
	s_mov_b32 s33, s10
	s_mov_b64 s[18:19], s[14:15]
	s_mov_b64 s[16:17], s[12:13]
	global_store_dwordx4 v[142:143], v[124:127], off
	global_store_dwordx4 v[108:109], v[104:107], off
	global_store_dwordx4 v[92:93], v[88:91], off
	global_store_dwordx4 v[76:77], v[72:75], off
	global_store_dwordx4 v[76:77], v[68:71], off offset:256
	global_store_dwordx4 v[64:65], v[60:63], off
	global_store_dwordx4 v[44:45], v[40:43], off
	global_store_dwordx4 v[28:29], v[24:27], off
	global_store_dwordx4 v[12:13], v[8:11], off
	global_store_dwordx4 v[12:13], v[4:7], off offset:256
	s_cbranch_vccz .LBB0_228
	s_waitcnt vmcnt(0)
	s_cmpk_gt_u32 s2, 0xff
	s_cbranch_scc1 .LBB0_235
	s_barrier

; #define PG8_STAGE(bufoff, gbase) do { _Pragma("unroll") for (int _i = 0; _i < 2; ++_i) \
;         __builtin_amdgcn_global_load_lds((const unsigned*)((const char*)(gbase) + voff[_i]), (LAS unsigned*)(lds + (bufoff) + ldsw + _i * 8192), 16, 0, 0); } while (0)
; #define PG8_LDA(dst, b, h) do { _Pragma("unroll") for (int m = 0; m < 4; ++m) _Pragma("unroll") for (int k = 0; k < 2; ++k) dst[m][k] = *(const LAS bf16x8*)(lds + PG8_SA(b, h) + aoff + m * 2048 + k * 1024); } while (0)
; #define PG8_LDB(dst, b, h) do { _Pragma("unroll") for (int n = 0; n < 2; ++n) _Pragma("unroll") for (int k = 0; k < 2; ++k) dst[n][k] = *(const LAS bf16x8*)(lds + PG8_SB(b, h) + boff + n * 2048 + k * 1024); } while (0)
; #define PG8_MMA(ai, bj, At, Bt) do { __builtin_amdgcn_s_setprio(1); _Pragma("unroll") for (int m = 0; m < 4; ++m) _Pragma("unroll") for (int n = 0; n < 2; ++n) _Pragma("unroll") for (int k = 0; k < 2; ++k) \
;         acc[ai][bj][m][n] = __builtin_amdgcn_mfma_f32_16x16x32_bf16(Bt[n][k], At[m][k], acc[ai][bj][m][n], 0, 0, 0); __builtin_amdgcn_s_setprio(0); } while (0)
; #define PG8_WAIT_V(n) asm volatile("s_waitcnt vmcnt(" #n ")" ::: "memory")
; #define PG8_WAIT_L(n) asm volatile("s_waitcnt lgkmcnt(" #n ")" ::: "memory")
; #define PG8_BAR __builtin_amdgcn_s_barrier()
; #define PG8_SCHED __builtin_amdgcn_sched_barrier(0)
; template <class Epi>
; DI void gemm_phase(LAS unsigned char* lds, const Gemm g, const StaticOrder& S, const Epi& E) {
;     ...
;         for (int t = 0; t < nt; t += 2) {
;             const bool last = (t == nt - 2);
;             const char* a1 = cA + (size_t)(t + 1) * kstep;
;             const char* a2 = last ? nA : cA + (size_t)(t + 2) * kstep; const char* b2 = last ? nB : cB + (size_t)(t + 2) * kstep;
;             const char* a3 = a2 + kstep; const char* b3 = b2 + kstep;
;             PG8_LDB(B0, 0, 0); PG8_SCHED; PG8_LDA(At, 0, 0); PG8_STAGE(PG8_SA(1, 1), a1 + hstep);
;             PG8_WAIT_L(8); PG8_BAR; PG8_WAIT_L(0); PG8_MMA(0, 0, At, B0); PG8_BAR; PG8_SCHED;
;             PG8_LDB(B1, 0, 1); PG8_STAGE(PG8_SB(0, 0), b2);
;             PG8_BAR; PG8_WAIT_L(0); PG8_MMA(0, 1, At, B1); PG8_BAR;
;             PG8_LDA(At, 0, 1); PG8_STAGE(PG8_SA(0, 0), a2);
;             PG8_BAR; PG8_WAIT_L(0); PG8_MMA(1, 0, At, B0); PG8_BAR; PG8_SCHED;
;             PG8_STAGE(PG8_SB(0, 1), b2 + hstep);
;             PG8_WAIT_V(6); PG8_BAR; PG8_MMA(1, 1, At, B1); PG8_BAR;
.LBB0_320:
	s_add_u32 s26, s24, 0x100
	s_addc_u32 s27, s25, 0
	s_add_i32 s47, 0, 0x10000
	v_add_u32_e32 v140, s47, v226
	ds_read_b128 v[128:131], v140
	ds_read_b128 v[132:135], v140 offset:1024
	ds_read_b128 v[136:139], v140 offset:2048
	ds_read_b128 v[140:143], v140 offset:3072
	s_cmp_eq_u32 s46, 28
	s_cselect_b32 s31, s4, s27
	s_cselect_b32 s30, s5, s26
	s_cselect_b32 s29, s9, s45
	s_cselect_b32 s28, s11, s33
	v_lshl_add_u64 v[214:215], s[24:25], 0, v[190:191]
	s_add_i32 m0, s38, 0xc000
	ds_read_b128 v[144:147], v228
	ds_read_b128 v[148:151], v228 offset:1024
	ds_read_b128 v[152:155], v228 offset:2048
	ds_read_b128 v[194:197], v228 offset:3072
	ds_read_b128 v[198:201], v228 offset:4096
	ds_read_b128 v[202:205], v228 offset:5120
	ds_read_b128 v[206:209], v228 offset:6144
	ds_read_b128 v[210:213], v228 offset:7168
	global_load_lds_dwordx4 v[214:215], off
	v_lshl_add_u64 v[214:215], s[24:25], 0, v[192:193]
	s_add_i32 m0, s38, 0xe000
	s_nop 0
	global_load_lds_dwordx4 v[214:215], off
	s_waitcnt lgkmcnt(8)
	s_setprio 1
	s_barrier
	s_waitcnt lgkmcnt(0)
	v_mfma_f32_16x16x32_bf16 v[124:127], v[128:131], v[144:147], v[124:127]
	v_mfma_f32_16x16x32_bf16 v[120:123], v[136:139], v[144:147], v[120:123]
	v_mfma_f32_16x16x32_bf16 v[116:119], v[128:131], v[152:155], v[116:119]
	v_mfma_f32_16x16x32_bf16 v[112:115], v[136:139], v[152:155], v[112:115]
	v_mfma_f32_16x16x32_bf16 v[108:111], v[128:131], v[198:201], v[108:111]
	v_mfma_f32_16x16x32_bf16 v[104:107], v[136:139], v[198:201], v[104:107]
	v_mfma_f32_16x16x32_bf16 v[100:103], v[128:131], v[206:209], v[100:103]
	v_mfma_f32_16x16x32_bf16 v[96:99], v[136:139], v[206:209], v[96:99]
	v_mfma_f32_16x16x32_bf16 v[124:127], v[132:135], v[148:151], v[124:127]
	v_mfma_f32_16x16x32_bf16 v[120:123], v[140:143], v[148:151], v[120:123]
	v_mfma_f32_16x16x32_bf16 v[116:119], v[132:135], v[194:197], v[116:119]
	v_mfma_f32_16x16x32_bf16 v[112:115], v[140:143], v[194:197], v[112:115]
	s_add_i32 s48, 0, 0x14000
	s_add_i32 s24, s47, s37
	v_add_u32_e32 v158, s48, v226
	v_lshl_add_u64 v[218:219], s[28:29], 0, v[188:189]
	s_mov_b32 m0, s24
	v_mfma_f32_16x16x32_bf16 v[108:111], v[132:135], v[202:205], v[108:111]
	v_mfma_f32_16x16x32_bf16 v[104:107], v[140:143], v[202:205], v[104:107]
	v_mfma_f32_16x16x32_bf16 v[100:103], v[132:135], v[210:213], v[100:103]
	v_mfma_f32_16x16x32_bf16 v[96:99], v[140:143], v[210:213], v[96:99]
	s_setprio 0
	s_barrier
	ds_read_b128 v[214:217], v158
	ds_read_b128 v[230:233], v158 offset:1024
	ds_read_b128 v[234:237], v158 offset:2048
	ds_read_b128 v[238:241], v158 offset:3072
	global_load_lds_dwordx4 v[218:219], off
	v_lshl_add_u64 v[220:221], s[28:29], 0, v[186:187]
	s_add_i32 m0, s24, 0x2000
	s_nop 0
	global_load_lds_dwordx4 v[220:221], off
	s_waitcnt lgkmcnt(0)
	s_setprio 1
	s_barrier
	v_mfma_f32_16x16x32_bf16 v[60:63], v[214:217], v[144:147], v[60:63]
	v_mfma_f32_16x16x32_bf16 v[56:59], v[234:237], v[144:147], v[56:59]
	v_mfma_f32_16x16x32_bf16 v[52:55], v[214:217], v[152:155], v[52:55]
	v_mfma_f32_16x16x32_bf16 v[48:51], v[234:237], v[152:155], v[48:51]
	v_mfma_f32_16x16x32_bf16 v[44:47], v[214:217], v[198:201], v[44:47]
	v_mfma_f32_16x16x32_bf16 v[40:43], v[234:237], v[198:201], v[40:43]
	v_mfma_f32_16x16x32_bf16 v[36:39], v[214:217], v[206:209], v[36:39]
	v_mfma_f32_16x16x32_bf16 v[32:35], v[234:237], v[206:209], v[32:35]
	v_mfma_f32_16x16x32_bf16 v[60:63], v[230:233], v[148:151], v[60:63]
	v_mfma_f32_16x16x32_bf16 v[56:59], v[238:241], v[148:151], v[56:59]
	v_mfma_f32_16x16x32_bf16 v[52:55], v[230:233], v[194:197], v[52:55]
	v_mfma_f32_16x16x32_bf16 v[48:51], v[238:241], v[194:197], v[48:51]
	s_mov_b32 m0, s38
	v_lshl_add_u64 v[242:243], s[30:31], 0, v[188:189]
	v_mfma_f32_16x16x32_bf16 v[44:47], v[230:233], v[202:205], v[44:47]
	v_mfma_f32_16x16x32_bf16 v[40:43], v[238:241], v[202:205], v[40:43]
	v_mfma_f32_16x16x32_bf16 v[36:39], v[230:233], v[210:213], v[36:39]
	v_mfma_f32_16x16x32_bf16 v[32:35], v[238:241], v[210:213], v[32:35]
	s_setprio 0
	s_barrier
	ds_read_b128 v[144:147], v228 offset:16384
	ds_read_b128 v[148:151], v228 offset:17408
	ds_read_b128 v[152:155], v228 offset:18432
	ds_read_b128 v[194:197], v228 offset:19456
	ds_read_b128 v[198:201], v228 offset:20480
	ds_read_b128 v[202:205], v228 offset:21504
	ds_read_b128 v[206:209], v228 offset:22528
	ds_read_b128 v[210:213], v228 offset:23552
	global_load_lds_dwordx4 v[242:243], off
	v_lshl_add_u64 v[244:245], s[30:31], 0, v[186:187]
	s_mov_b32 m0, s39
	s_nop 0
	global_load_lds_dwordx4 v[244:245], off
	s_waitcnt lgkmcnt(0)
	s_setprio 1
	s_barrier
	v_mfma_f32_16x16x32_bf16 v[92:95], v[128:131], v[144:147], v[92:95]
	v_mfma_f32_16x16x32_bf16 v[88:91], v[136:139], v[144:147], v[88:91]
	v_mfma_f32_16x16x32_bf16 v[84:87], v[128:131], v[152:155], v[84:87]
	v_mfma_f32_16x16x32_bf16 v[80:83], v[136:139], v[152:155], v[80:83]
	v_mfma_f32_16x16x32_bf16 v[76:79], v[128:131], v[198:201], v[76:79]
	v_mfma_f32_16x16x32_bf16 v[72:75], v[136:139], v[198:201], v[72:75]
	v_mfma_f32_16x16x32_bf16 v[68:71], v[128:131], v[206:209], v[68:71]
	v_mfma_f32_16x16x32_bf16 v[64:67], v[136:139], v[206:209], v[64:67]
	v_mfma_f32_16x16x32_bf16 v[92:95], v[132:135], v[148:151], v[92:95]
	v_mfma_f32_16x16x32_bf16 v[88:91], v[140:143], v[148:151], v[88:91]
	v_mfma_f32_16x16x32_bf16 v[84:87], v[132:135], v[194:197], v[84:87]
	v_mfma_f32_16x16x32_bf16 v[80:83], v[140:143], v[194:197], v[80:83]
	s_add_u32 s24, s28, 0x80000
	s_addc_u32 s25, s29, 0
	s_add_i32 s47, s48, s37
	v_lshl_add_u64 v[128:129], s[24:25], 0, v[188:189]
	s_mov_b32 m0, s47
	v_mfma_f32_16x16x32_bf16 v[76:79], v[132:135], v[202:205], v[76:79]
	v_mfma_f32_16x16x32_bf16 v[72:75], v[140:143], v[202:205], v[72:75]
	v_mfma_f32_16x16x32_bf16 v[68:71], v[132:135], v[210:213], v[68:71]
	v_mfma_f32_16x16x32_bf16 v[64:67], v[140:143], v[210:213], v[64:67]
	s_setprio 0
	s_barrier
; #define PG8_STAGE(bufoff, gbase) do { _Pragma("unroll") for (int _i = 0; _i < 2; ++_i) \
;         __builtin_amdgcn_global_load_lds((const unsigned*)((const char*)(gbase) + voff[_i]), (LAS unsigned*)(lds + (bufoff) + ldsw + _i * 8192), 16, 0, 0); } while (0)
; #define PG8_LDA(dst, b, h) do { _Pragma("unroll") for (int m = 0; m < 4; ++m) _Pragma("unroll") for (int k = 0; k < 2; ++k) dst[m][k] = *(const LAS bf16x8*)(lds + PG8_SA(b, h) + aoff + m * 2048 + k * 1024); } while (0)
; #define PG8_LDB(dst, b, h) do { _Pragma("unroll") for (int n = 0; n < 2; ++n) _Pragma("unroll") for (int k = 0; k < 2; ++k) dst[n][k] = *(const LAS bf16x8*)(lds + PG8_SB(b, h) + boff + n * 2048 + k * 1024); } while (0)
; #define PG8_MMA(ai, bj, At, Bt) do { __builtin_amdgcn_s_setprio(1); _Pragma("unroll") for (int m = 0; m < 4; ++m) _Pragma("unroll") for (int n = 0; n < 2; ++n) _Pragma("unroll") for (int k = 0; k < 2; ++k) \
;         acc[ai][bj][m][n] = __builtin_amdgcn_mfma_f32_16x16x32_bf16(Bt[n][k], At[m][k], acc[ai][bj][m][n], 0, 0, 0); __builtin_amdgcn_s_setprio(0); } while (0)
; #define PG8_WAIT_V(n) asm volatile("s_waitcnt vmcnt(" #n ")" ::: "memory")
; #define PG8_WAIT_L(n) asm volatile("s_waitcnt lgkmcnt(" #n ")" ::: "memory")
; #define PG8_BAR __builtin_amdgcn_s_barrier()
; #define PG8_SCHED __builtin_amdgcn_sched_barrier(0)
; template <class Epi>
; DI void gemm_phase(LAS unsigned char* lds, const Gemm g, const StaticOrder& S, const Epi& E) {
;     ...
;             PG8_BAR; PG8_WAIT_L(0); PG8_MMA(1, 0, At, B0); PG8_BAR; PG8_SCHED;
;             PG8_STAGE(PG8_SB(0, 1), b2 + hstep);
;             PG8_WAIT_V(6); PG8_BAR; PG8_MMA(1, 1, At, B1); PG8_BAR;
;             PG8_LDB(B0, 1, 0); PG8_SCHED; PG8_LDA(At, 1, 0); PG8_STAGE(PG8_SA(0, 1), a2 + hstep);
;             PG8_WAIT_L(8); PG8_BAR; PG8_WAIT_L(0); PG8_MMA(0, 0, At, B0); PG8_BAR; PG8_SCHED;
;             PG8_LDB(B1, 1, 1); PG8_STAGE(PG8_SB(1, 0), b3);
;             PG8_BAR; PG8_WAIT_L(0); PG8_MMA(0, 1, At, B1); PG8_BAR;
;             PG8_LDA(At, 1, 1); PG8_STAGE(PG8_SA(1, 0), a3);
;             PG8_BAR; PG8_WAIT_L(0); PG8_MMA(1, 0, At, B0); PG8_BAR; PG8_SCHED;
	s_nop 0
	global_load_lds_dwordx4 v[128:129], off
	v_lshl_add_u64 v[128:129], s[24:25], 0, v[186:187]
	s_add_i32 m0, s47, 0x2000
	s_nop 0
	global_load_lds_dwordx4 v[128:129], off
	s_waitcnt vmcnt(6)
	s_setprio 1
	s_barrier
	v_mfma_f32_16x16x32_bf16 v[28:31], v[214:217], v[144:147], v[28:31]
	v_mfma_f32_16x16x32_bf16 v[24:27], v[234:237], v[144:147], v[24:27]
	v_mfma_f32_16x16x32_bf16 v[20:23], v[214:217], v[152:155], v[20:23]
	v_mfma_f32_16x16x32_bf16 v[16:19], v[234:237], v[152:155], v[16:19]
	v_mfma_f32_16x16x32_bf16 v[12:15], v[214:217], v[198:201], v[12:15]
	v_mfma_f32_16x16x32_bf16 v[8:11], v[234:237], v[198:201], v[8:11]
	v_mfma_f32_16x16x32_bf16 v[4:7], v[214:217], v[206:209], v[4:7]
	v_mfma_f32_16x16x32_bf16 v[0:3], v[234:237], v[206:209], v[0:3]
	v_mfma_f32_16x16x32_bf16 v[28:31], v[230:233], v[148:151], v[28:31]
	v_mfma_f32_16x16x32_bf16 v[24:27], v[238:241], v[148:151], v[24:27]
	v_mfma_f32_16x16x32_bf16 v[20:23], v[230:233], v[194:197], v[20:23]
	v_mfma_f32_16x16x32_bf16 v[16:19], v[238:241], v[194:197], v[16:19]
	s_add_i32 s47, 0, 0x18000
	v_add_u32_e32 v140, s47, v226
	v_mfma_f32_16x16x32_bf16 v[12:15], v[230:233], v[202:205], v[12:15]
	v_mfma_f32_16x16x32_bf16 v[8:11], v[238:241], v[202:205], v[8:11]
	v_mfma_f32_16x16x32_bf16 v[4:7], v[230:233], v[210:213], v[4:7]
	v_mfma_f32_16x16x32_bf16 v[0:3], v[238:241], v[210:213], v[0:3]
	s_setprio 0
	s_barrier
	ds_read_b128 v[128:131], v140
	ds_read_b128 v[132:135], v140 offset:1024
	ds_read_b128 v[136:139], v140 offset:2048
	ds_read_b128 v[140:143], v140 offset:3072
	s_add_u32 s24, s30, 0x80000
	s_addc_u32 s25, s31, 0
	s_mov_b32 m0, s40
	v_lshl_add_u64 v[214:215], s[24:25], 0, v[188:189]
	ds_read_b128 v[144:147], v228 offset:32768
	ds_read_b128 v[148:151], v228 offset:33792
	ds_read_b128 v[152:155], v228 offset:34816
	ds_read_b128 v[194:197], v228 offset:35840
	ds_read_b128 v[198:201], v228 offset:36864
	ds_read_b128 v[202:205], v228 offset:37888
	ds_read_b128 v[206:209], v228 offset:38912
	ds_read_b128 v[210:213], v228 offset:39936
	global_load_lds_dwordx4 v[214:215], off
	v_lshl_add_u64 v[214:215], s[24:25], 0, v[186:187]
	s_mov_b32 m0, s41
	s_nop 0
	global_load_lds_dwordx4 v[214:215], off
	s_waitcnt lgkmcnt(8)
	s_setprio 1
	s_barrier
	s_waitcnt lgkmcnt(0)
	v_mfma_f32_16x16x32_bf16 v[124:127], v[128:131], v[144:147], v[124:127]
	v_mfma_f32_16x16x32_bf16 v[120:123], v[136:139], v[144:147], v[120:123]
	v_mfma_f32_16x16x32_bf16 v[116:119], v[128:131], v[152:155], v[116:119]
	v_mfma_f32_16x16x32_bf16 v[112:115], v[136:139], v[152:155], v[112:115]
	v_mfma_f32_16x16x32_bf16 v[108:111], v[128:131], v[198:201], v[108:111]
	v_mfma_f32_16x16x32_bf16 v[104:107], v[136:139], v[198:201], v[104:107]
	v_mfma_f32_16x16x32_bf16 v[100:103], v[128:131], v[206:209], v[100:103]
	v_mfma_f32_16x16x32_bf16 v[96:99], v[136:139], v[206:209], v[96:99]
	v_mfma_f32_16x16x32_bf16 v[124:127], v[132:135], v[148:151], v[124:127]
	v_mfma_f32_16x16x32_bf16 v[120:123], v[140:143], v[148:151], v[120:123]
	v_mfma_f32_16x16x32_bf16 v[116:119], v[132:135], v[194:197], v[116:119]
	v_mfma_f32_16x16x32_bf16 v[112:115], v[140:143], v[194:197], v[112:115]
	s_add_i32 s30, 0, 0x1c000
	s_add_i32 s24, s47, s37
	v_add_u32_e32 v158, s30, v226
	v_lshl_add_u64 v[218:219], v[218:219], 0, s[94:95]
	s_mov_b32 m0, s24
	v_mfma_f32_16x16x32_bf16 v[108:111], v[132:135], v[202:205], v[108:111]
	v_mfma_f32_16x16x32_bf16 v[104:107], v[140:143], v[202:205], v[104:107]
	v_mfma_f32_16x16x32_bf16 v[100:103], v[132:135], v[210:213], v[100:103]
	v_mfma_f32_16x16x32_bf16 v[96:99], v[140:143], v[210:213], v[96:99]
	s_setprio 0
	s_barrier
	ds_read_b128 v[214:217], v158
	ds_read_b128 v[230:233], v158 offset:1024
	ds_read_b128 v[234:237], v158 offset:2048
	ds_read_b128 v[238:241], v158 offset:3072
	global_load_lds_dwordx4 v[218:219], off
	v_lshl_add_u64 v[218:219], v[220:221], 0, s[94:95]
	s_add_i32 m0, s24, 0x2000
	s_nop 0
	global_load_lds_dwordx4 v[218:219], off
	s_waitcnt lgkmcnt(0)
	s_setprio 1
	s_barrier
	v_mfma_f32_16x16x32_bf16 v[60:63], v[214:217], v[144:147], v[60:63]
	v_mfma_f32_16x16x32_bf16 v[56:59], v[234:237], v[144:147], v[56:59]
	v_mfma_f32_16x16x32_bf16 v[52:55], v[214:217], v[152:155], v[52:55]
	v_mfma_f32_16x16x32_bf16 v[48:51], v[234:237], v[152:155], v[48:51]
	v_mfma_f32_16x16x32_bf16 v[44:47], v[214:217], v[198:201], v[44:47]
	v_mfma_f32_16x16x32_bf16 v[40:43], v[234:237], v[198:201], v[40:43]
	v_mfma_f32_16x16x32_bf16 v[36:39], v[214:217], v[206:209], v[36:39]
	v_mfma_f32_16x16x32_bf16 v[32:35], v[234:237], v[206:209], v[32:35]
	v_mfma_f32_16x16x32_bf16 v[60:63], v[230:233], v[148:151], v[60:63]
	v_mfma_f32_16x16x32_bf16 v[56:59], v[238:241], v[148:151], v[56:59]
	v_mfma_f32_16x16x32_bf16 v[52:55], v[230:233], v[194:197], v[52:55]
	v_mfma_f32_16x16x32_bf16 v[48:51], v[238:241], v[194:197], v[48:51]
	s_mov_b32 m0, s42
	v_lshl_add_u64 v[218:219], v[242:243], 0, s[94:95]
	v_mfma_f32_16x16x32_bf16 v[44:47], v[230:233], v[202:205], v[44:47]
	v_mfma_f32_16x16x32_bf16 v[40:43], v[238:241], v[202:205], v[40:43]
	v_mfma_f32_16x16x32_bf16 v[36:39], v[230:233], v[210:213], v[36:39]
	v_mfma_f32_16x16x32_bf16 v[32:35], v[238:241], v[210:213], v[32:35]
	s_setprio 0
	s_barrier
	ds_read_b128 v[144:147], v228 offset:49152
	ds_read_b128 v[148:151], v228 offset:50176
	ds_read_b128 v[152:155], v228 offset:51200
	ds_read_b128 v[194:197], v228 offset:52224
	ds_read_b128 v[198:201], v228 offset:53248
	ds_read_b128 v[202:205], v228 offset:54272
	ds_read_b128 v[206:209], v228 offset:55296
	ds_read_b128 v[210:213], v228 offset:56320
	global_load_lds_dwordx4 v[218:219], off
	v_lshl_add_u64 v[218:219], v[244:245], 0, s[94:95]
	s_mov_b32 m0, s43
	s_nop 0
	global_load_lds_dwordx4 v[218:219], off
	s_waitcnt lgkmcnt(0)
	s_setprio 1
	s_barrier
; #define PG8_STAGE(bufoff, gbase) do { _Pragma("unroll") for (int _i = 0; _i < 2; ++_i) \
;         __builtin_amdgcn_global_load_lds((const unsigned*)((const char*)(gbase) + voff[_i]), (LAS unsigned*)(lds + (bufoff) + ldsw + _i * 8192), 16, 0, 0); } while (0)
; #define PG8_MMA(ai, bj, At, Bt) do { __builtin_amdgcn_s_setprio(1); _Pragma("unroll") for (int m = 0; m < 4; ++m) _Pragma("unroll") for (int n = 0; n < 2; ++n) _Pragma("unroll") for (int k = 0; k < 2; ++k) \
;         acc[ai][bj][m][n] = __builtin_amdgcn_mfma_f32_16x16x32_bf16(Bt[n][k], At[m][k], acc[ai][bj][m][n], 0, 0, 0); __builtin_amdgcn_s_setprio(0); } while (0)
; #define PG8_WAIT_V(n) asm volatile("s_waitcnt vmcnt(" #n ")" ::: "memory")
; #define PG8_WAIT_L(n) asm volatile("s_waitcnt lgkmcnt(" #n ")" ::: "memory")
; #define PG8_BAR __builtin_amdgcn_s_barrier()
; #define PG8_SCHED __builtin_amdgcn_sched_barrier(0)
; template <class Epi>
; DI void gemm_phase(LAS unsigned char* lds, const Gemm g, const StaticOrder& S, const Epi& E) {
;     ...
;             PG8_BAR; PG8_WAIT_L(0); PG8_MMA(1, 0, At, B0); PG8_BAR; PG8_SCHED;
;             PG8_STAGE(PG8_SB(1, 1), b3 + hstep);
;             PG8_WAIT_V(6); PG8_BAR; PG8_MMA(1, 1, At, B1); PG8_BAR;
;         }
;     template <bool LN> DI void run(const f32x4 (&acc)[2][2][4][2], const Unit& u, int wr, int wc, int fr, int fq) const {
;         const unsigned row0 = u.pm * BM + wr * 64 + fr, col0 = u.pn * BM + wc * 32 + 4 * fq;
;         f32x4 gv[2], bv[2];
;         load_gb<LN, 0>(col0, gv, bv);
;         batch<LN, 0, 0, 4>(acc, row0, col0, gv, bv);
;         batch<LN, 0, 4, 8>(acc, row0, col0, gv, bv);
;         batch<LN, 0, 8, 12>(acc, row0, col0, gv, bv);
	v_mfma_f32_16x16x32_bf16 v[92:95], v[128:131], v[144:147], v[92:95]
	v_mfma_f32_16x16x32_bf16 v[88:91], v[136:139], v[144:147], v[88:91]
	v_mfma_f32_16x16x32_bf16 v[84:87], v[128:131], v[152:155], v[84:87]
	v_mfma_f32_16x16x32_bf16 v[80:83], v[136:139], v[152:155], v[80:83]
	v_mfma_f32_16x16x32_bf16 v[76:79], v[128:131], v[198:201], v[76:79]
	v_mfma_f32_16x16x32_bf16 v[72:75], v[136:139], v[198:201], v[72:75]
	v_mfma_f32_16x16x32_bf16 v[68:71], v[128:131], v[206:209], v[68:71]
	v_mfma_f32_16x16x32_bf16 v[64:67], v[136:139], v[206:209], v[64:67]
	v_mfma_f32_16x16x32_bf16 v[92:95], v[132:135], v[148:151], v[92:95]
	v_mfma_f32_16x16x32_bf16 v[88:91], v[140:143], v[148:151], v[88:91]
	v_mfma_f32_16x16x32_bf16 v[84:87], v[132:135], v[194:197], v[84:87]
	v_mfma_f32_16x16x32_bf16 v[80:83], v[140:143], v[194:197], v[80:83]
	s_add_u32 s24, s28, 0x80080
	s_addc_u32 s25, s29, 0
	s_add_i32 s28, s30, s37
	v_lshl_add_u64 v[128:129], s[24:25], 0, v[188:189]
	s_mov_b32 m0, s28
	v_mfma_f32_16x16x32_bf16 v[76:79], v[132:135], v[202:205], v[76:79]
	v_mfma_f32_16x16x32_bf16 v[72:75], v[140:143], v[202:205], v[72:75]
	v_mfma_f32_16x16x32_bf16 v[68:71], v[132:135], v[210:213], v[68:71]
	v_mfma_f32_16x16x32_bf16 v[64:67], v[140:143], v[210:213], v[64:67]
	s_setprio 0
	s_barrier
	s_nop 0
	global_load_lds_dwordx4 v[128:129], off
	v_lshl_add_u64 v[128:129], s[24:25], 0, v[186:187]
	s_add_i32 m0, s28, 0x2000
	s_nop 0
	global_load_lds_dwordx4 v[128:129], off
	s_waitcnt vmcnt(6)
	s_setprio 1
	s_barrier
	v_mfma_f32_16x16x32_bf16 v[28:31], v[214:217], v[144:147], v[28:31]
	v_mfma_f32_16x16x32_bf16 v[24:27], v[234:237], v[144:147], v[24:27]
	v_mfma_f32_16x16x32_bf16 v[20:23], v[214:217], v[152:155], v[20:23]
	v_mfma_f32_16x16x32_bf16 v[16:19], v[234:237], v[152:155], v[16:19]
	v_mfma_f32_16x16x32_bf16 v[12:15], v[214:217], v[198:201], v[12:15]
	v_mfma_f32_16x16x32_bf16 v[8:11], v[234:237], v[198:201], v[8:11]
	v_mfma_f32_16x16x32_bf16 v[4:7], v[214:217], v[206:209], v[4:7]
	v_mfma_f32_16x16x32_bf16 v[0:3], v[234:237], v[206:209], v[0:3]
	v_mfma_f32_16x16x32_bf16 v[28:31], v[230:233], v[148:151], v[28:31]
	v_mfma_f32_16x16x32_bf16 v[24:27], v[238:241], v[148:151], v[24:27]
	v_mfma_f32_16x16x32_bf16 v[20:23], v[230:233], v[194:197], v[20:23]
	v_mfma_f32_16x16x32_bf16 v[16:19], v[238:241], v[194:197], v[16:19]
	s_add_i32 s46, s46, 2
	s_add_u32 s33, s33, 0x100
	s_addc_u32 s45, s45, 0
	s_cmp_gt_u32 s46, 29
	s_mov_b64 s[24:25], s[26:27]
	v_mfma_f32_16x16x32_bf16 v[12:15], v[230:233], v[202:205], v[12:15]
	v_mfma_f32_16x16x32_bf16 v[8:11], v[238:241], v[202:205], v[8:11]
	v_mfma_f32_16x16x32_bf16 v[4:7], v[230:233], v[210:213], v[4:7]
	v_mfma_f32_16x16x32_bf16 v[0:3], v[238:241], v[210:213], v[0:3]
	s_setprio 0
	s_barrier
	s_cbranch_scc0 .LBB0_320
	v_lshl_add_u32 v206, s3, 8, v225
	v_lshl_or_b32 v158, s2, 8, v227
	v_lshlrev_b32_e32 v232, 11, v206
	s_andn2_b64 vcc, exec, s[14:15]
	v_or_b32_e32 v231, 16, v158
	v_add_u32_e32 v194, v232, v158
	v_or_b32_e32 v230, 0x80, v158
	v_or_b32_e32 v229, 0x90, v158
	s_cbranch_vccnz .LBB0_323
	v_lshlrev_b64 v[132:133], 2, v[158:159]
	v_lshl_add_u64 v[140:141], s[16:17], 0, v[132:133]
	global_load_dwordx4 v[128:131], v[140:141], off
	v_lshl_add_u64 v[142:143], s[18:19], 0, v[132:133]
	v_readlane_b32 s2, v253, 8
	v_mov_b32_e32 v195, v159
	v_lshlrev_b32_e32 v136, 1, v206
	v_mov_b32_e32 v137, v159
	v_readlane_b32 s3, v253, 9
	v_lshlrev_b64 v[212:213], 2, v[194:195]
	v_add_u32_e32 v146, v232, v231
	v_lshl_add_u64 v[144:145], v[136:137], 2, s[2:3]
	v_lshl_add_u64 v[136:137], s[88:89], 0, v[212:213]
	v_mov_b32_e32 v147, v159
	v_lshl_add_u64 v[146:147], v[146:147], 2, s[88:89]
	v_or_b32_e32 v195, 16, v206
	v_mov_b32_e32 v201, v159
	v_mov_b32_e32 v209, v159
	v_lshl_add_u64 v[212:213], s[90:91], 0, v[212:213]
	s_waitcnt vmcnt(0)
	v_pk_mul_f32 v[152:153], v[130:131], s[78:79] op_sel_hi:[1,0]
	v_pk_mul_f32 v[154:155], v[128:129], s[78:79] op_sel_hi:[1,0]
	global_load_dwordx4 v[132:135], v[142:143], off
	global_load_dwordx4 v[128:131], v[140:141], off offset:64
	global_load_dwordx2 v[204:205], v[144:145], off
	global_load_dwordx4 v[196:199], v[146:147], off
	v_lshlrev_b32_e32 v146, 1, v195
	global_load_dwordx4 v[136:139], v[136:137], off
	v_lshlrev_b32_e32 v195, 11, v195
	v_mov_b32_e32 v147, v159
	v_add_u32_e32 v200, v195, v158
	v_lshl_add_u64 v[146:147], v[146:147], 2, s[2:3]
	v_lshl_add_u64 v[200:201], v[200:201], 2, s[88:89]
	global_load_dwordx2 v[214:215], v[146:147], off
	v_add_u32_e32 v208, v195, v231
	global_load_dwordx4 v[200:203], v[200:201], off
	v_lshl_add_u64 v[208:209], v[208:209], 2, s[88:89]
	global_load_dwordx4 v[208:211], v[208:209], off
	s_waitcnt vmcnt(0)
	v_pk_mul_f32 v[148:149], v[130:131], s[78:79] op_sel_hi:[1,0]
	v_pk_mul_f32 v[150:151], v[128:129], s[78:79] op_sel_hi:[1,0]
	global_load_dwordx4 v[128:131], v[142:143], off offset:64
	v_sub_f32_e32 v137, v137, v204
	v_sub_f32_e32 v136, v136, v204
	v_sub_f32_e32 v139, v139, v204
	v_sub_f32_e32 v138, v138, v204
	v_pk_mul_f32 v[138:139], v[204:205], v[138:139] op_sel:[1,0]
	v_pk_mul_f32 v[136:137], v[204:205], v[136:137] op_sel:[1,0]
	v_pk_fma_f32 v[138:139], v[152:153], v[138:139], v[126:127]
	v_pk_fma_f32 v[136:137], v[154:155], v[136:137], v[124:125]
	v_pk_fma_f32 v[138:139], v[134:135], s[78:79], v[138:139] op_sel_hi:[1,0,1]
	v_pk_fma_f32 v[136:137], v[132:133], s[78:79], v[136:137] op_sel_hi:[1,0,1]
	global_store_dwordx4 v[212:213], v[136:139], off
	s_nop 1
	v_sub_f32_e32 v137, v197, v204
	v_sub_f32_e32 v136, v196, v204
	v_sub_f32_e32 v139, v199, v204
	v_sub_f32_e32 v138, v198, v204
	v_pk_mul_f32 v[138:139], v[204:205], v[138:139] op_sel:[1,0]
	v_pk_mul_f32 v[136:137], v[204:205], v[136:137] op_sel:[1,0]
	v_pk_fma_f32 v[138:139], v[148:149], v[138:139], v[122:123]
	v_pk_fma_f32 v[136:137], v[150:151], v[136:137], v[120:121]
	v_or_b32_e32 v196, 16, v194
	v_mov_b32_e32 v197, v159
	v_lshl_add_u64 v[196:197], v[196:197], 2, s[90:91]
	s_waitcnt vmcnt(0)
;     template <bool LN, int BJ, int LO, int HI> DI void batch(const f32x4 (&acc)[2][2][4][2], unsigned row0, unsigned col0, const f32x4 (&gv)[2], const f32x4 (&bv)[2]) const {
;         f32x4 r[HI - LO]; float mean[(HI - LO) / 2], rstd[(HI - LO) / 2];
; #pragma unroll
;         for (int i = LO; i < HI; ++i) { const int ai = i >> 3, m = (i >> 1) & 3, n = i & 1; const unsigned row = row0 + ai * HALF + m * 16;
;             if (n == 0) { mean[(i - LO) >> 1] = 0.f; rstd[(i - LO) >> 1] = 1.f;
;                 if (LN) { const float2 st = *(const float2*)(stats + row * 2u); mean[(i - LO) >> 1] = st.x; rstd[(i - LO) >> 1] = st.y; } }
;             r[i - LO] = *(const f32x4*)(src + (row * (unsigned)DM + col0 + BJ * HALF + n * 16)); }
; #pragma unroll
;         for (int i = LO; i < HI; ++i) { const int ai = i >> 3, m = (i >> 1) & 3, n = i & 1; const unsigned row = row0 + ai * HALF + m * 16;
;             *(f32x4*)(Y + (row * (unsigned)DM + col0 + BJ * HALF + n * 16)) = acc[ai][BJ][m][n] + ((r[i - LO] - mean[(i - LO) >> 1]) * rstd[(i - LO) >> 1]) * gv[n] + bv[n]; }
;         __builtin_amdgcn_sched_barrier(0);
;     }
;     template <bool LN, int BJ> DI void load_gb(unsigned col0, f32x4 (&gv)[2], f32x4 (&bv)[2]) const {
; #pragma unroll
;         for (int n = 0; n < 2; ++n) {
;             if (LN) { gv[n] = *(const f32x4*)(gam + col0 + BJ * HALF + n * 16) * ALPHA; bv[n] = *(const f32x4*)(bet + col0 + BJ * HALF + n * 16) * ALPHA; }
;             else { gv[n] = (f32x4){ALPHA, ALPHA, ALPHA, ALPHA}; bv[n] = (f32x4){0.f, 0.f, 0.f, 0.f}; }
;         }
;     }
;     template <bool LN> DI void run(const f32x4 (&acc)[2][2][4][2], const Unit& u, int wr, int wc, int fr, int fq) const {
;         const unsigned row0 = u.pm * BM + wr * 64 + fr, col0 = u.pn * BM + wc * 32 + 4 * fq;
;         f32x4 gv[2], bv[2];
;         load_gb<LN, 0>(col0, gv, bv);
;         batch<LN, 0, 0, 4>(acc, row0, col0, gv, bv);
;         batch<LN, 0, 4, 8>(acc, row0, col0, gv, bv);
;         batch<LN, 0, 8, 12>(acc, row0, col0, gv, bv);
;         batch<LN, 0, 12, 16>(acc, row0, col0, gv, bv);
;         load_gb<LN, 1>(col0, gv, bv);
;         batch<LN, 1, 0, 8>(acc, row0, col0, gv, bv);
;         batch<LN, 1, 8, 16>(acc, row0, col0, gv, bv);
	v_pk_fma_f32 v[138:139], v[130:131], s[78:79], v[138:139] op_sel_hi:[1,0,1]
	v_pk_fma_f32 v[136:137], v[128:129], s[78:79], v[136:137] op_sel_hi:[1,0,1]
	global_store_dwordx4 v[196:197], v[136:139], off
	v_add_u32_e32 v196, 0x8000, v194
	v_mov_b32_e32 v197, v159
	v_sub_f32_e32 v137, v201, v214
	v_sub_f32_e32 v136, v200, v214
	v_sub_f32_e32 v139, v203, v214
	v_sub_f32_e32 v138, v202, v214
	v_pk_mul_f32 v[138:139], v[214:215], v[138:139] op_sel:[1,0]
	v_pk_mul_f32 v[136:137], v[214:215], v[136:137] op_sel:[1,0]
	v_pk_fma_f32 v[138:139], v[152:153], v[138:139], v[118:119]
	v_pk_fma_f32 v[136:137], v[154:155], v[136:137], v[116:117]
	v_pk_fma_f32 v[138:139], v[134:135], s[78:79], v[138:139] op_sel_hi:[1,0,1]
	v_pk_fma_f32 v[136:137], v[132:133], s[78:79], v[136:137] op_sel_hi:[1,0,1]
	v_lshl_add_u64 v[196:197], v[196:197], 2, s[90:91]
	global_store_dwordx4 v[196:197], v[136:139], off
	v_add_u32_e32 v196, 0x8010, v194
	v_mov_b32_e32 v197, v159
	v_sub_f32_e32 v137, v209, v214
	v_sub_f32_e32 v136, v208, v214
	v_sub_f32_e32 v139, v211, v214
	v_sub_f32_e32 v138, v210, v214
	v_pk_mul_f32 v[138:139], v[214:215], v[138:139] op_sel:[1,0]
	v_pk_mul_f32 v[136:137], v[214:215], v[136:137] op_sel:[1,0]
	v_pk_fma_f32 v[138:139], v[148:149], v[138:139], v[114:115]
	v_pk_fma_f32 v[136:137], v[150:151], v[136:137], v[112:113]
	v_pk_fma_f32 v[138:139], v[130:131], s[78:79], v[138:139] op_sel_hi:[1,0,1]
	v_pk_fma_f32 v[136:137], v[128:129], s[78:79], v[136:137] op_sel_hi:[1,0,1]
	v_lshl_add_u64 v[196:197], v[196:197], 2, s[90:91]
	global_store_dwordx4 v[196:197], v[136:139], off
	s_nop 1
	v_or_b32_e32 v138, 32, v206
	v_lshlrev_b32_e32 v136, 1, v138
	v_mov_b32_e32 v137, v159
	v_lshlrev_b32_e32 v236, 11, v138
	v_lshl_add_u64 v[200:201], v[136:137], 2, s[2:3]
	v_add_u32_e32 v136, v236, v158
	v_lshl_add_u64 v[136:137], v[136:137], 2, s[88:89]
	global_load_dwordx2 v[204:205], v[200:201], off
	v_add_u32_e32 v196, v236, v231
	global_load_dwordx4 v[136:139], v[136:137], off
	v_mov_b32_e32 v197, v159
	v_lshl_add_u64 v[196:197], v[196:197], 2, s[88:89]
	global_load_dwordx4 v[196:199], v[196:197], off
	v_or_b32_e32 v207, 48, v206
	v_lshlrev_b32_e32 v235, 11, v207
	v_lshlrev_b32_e32 v202, 1, v207
	v_mov_b32_e32 v203, v159
	v_add_u32_e32 v208, v235, v158
	v_mov_b32_e32 v209, v159
	v_lshl_add_u64 v[202:203], v[202:203], 2, s[2:3]
	v_lshl_add_u64 v[208:209], v[208:209], 2, s[88:89]
	global_load_dwordx2 v[216:217], v[202:203], off
	v_add_u32_e32 v212, v235, v231
	global_load_dwordx4 v[208:211], v[208:209], off
	v_mov_b32_e32 v213, v159
	v_lshl_add_u64 v[212:213], v[212:213], 2, s[88:89]
	global_load_dwordx4 v[212:215], v[212:213], off
	v_add_u32_e32 v218, 0x10000, v194
	v_mov_b32_e32 v219, v159
	v_lshl_add_u64 v[218:219], v[218:219], 2, s[90:91]
	s_waitcnt vmcnt(0)
	v_sub_f32_e32 v137, v137, v204
	v_sub_f32_e32 v136, v136, v204
	v_sub_f32_e32 v139, v139, v204
	v_sub_f32_e32 v138, v138, v204
	v_pk_mul_f32 v[138:139], v[204:205], v[138:139] op_sel:[1,0]
	v_pk_mul_f32 v[136:137], v[204:205], v[136:137] op_sel:[1,0]
	v_pk_fma_f32 v[138:139], v[152:153], v[138:139], v[110:111]
	v_pk_fma_f32 v[136:137], v[154:155], v[136:137], v[108:109]
	v_pk_fma_f32 v[138:139], v[134:135], s[78:79], v[138:139] op_sel_hi:[1,0,1]
	v_pk_fma_f32 v[136:137], v[132:133], s[78:79], v[136:137] op_sel_hi:[1,0,1]
	global_store_dwordx4 v[218:219], v[136:139], off
	s_nop 1
	v_sub_f32_e32 v137, v197, v204
	v_sub_f32_e32 v136, v196, v204
	v_sub_f32_e32 v139, v199, v204
	v_sub_f32_e32 v138, v198, v204
	v_pk_mul_f32 v[138:139], v[204:205], v[138:139] op_sel:[1,0]
	v_pk_mul_f32 v[136:137], v[204:205], v[136:137] op_sel:[1,0]
	v_pk_fma_f32 v[138:139], v[148:149], v[138:139], v[106:107]
	v_pk_fma_f32 v[136:137], v[150:151], v[136:137], v[104:105]
	v_add_u32_e32 v196, 0x10010, v194
	v_mov_b32_e32 v197, v159
	v_pk_fma_f32 v[138:139], v[130:131], s[78:79], v[138:139] op_sel_hi:[1,0,1]
	v_pk_fma_f32 v[136:137], v[128:129], s[78:79], v[136:137] op_sel_hi:[1,0,1]
	v_lshl_add_u64 v[196:197], v[196:197], 2, s[90:91]
	global_store_dwordx4 v[196:197], v[136:139], off
	v_add_u32_e32 v196, 0x18000, v194
	v_mov_b32_e32 v197, v159
	v_sub_f32_e32 v137, v209, v216
	v_sub_f32_e32 v136, v208, v216
	v_sub_f32_e32 v139, v211, v216
	v_sub_f32_e32 v138, v210, v216
	v_pk_mul_f32 v[138:139], v[216:217], v[138:139] op_sel:[1,0]
	v_pk_mul_f32 v[136:137], v[216:217], v[136:137] op_sel:[1,0]
	v_pk_fma_f32 v[138:139], v[152:153], v[138:139], v[102:103]
	v_pk_fma_f32 v[136:137], v[154:155], v[136:137], v[100:101]
	v_pk_fma_f32 v[138:139], v[134:135], s[78:79], v[138:139] op_sel_hi:[1,0,1]
	v_pk_fma_f32 v[136:137], v[132:133], s[78:79], v[136:137] op_sel_hi:[1,0,1]
	v_lshl_add_u64 v[196:197], v[196:197], 2, s[90:91]
	global_store_dwordx4 v[196:197], v[136:139], off
	v_add_u32_e32 v196, 0x18010, v194
	v_mov_b32_e32 v197, v159
	v_sub_f32_e32 v137, v213, v216
	v_sub_f32_e32 v136, v212, v216
	v_sub_f32_e32 v139, v215, v216
	v_sub_f32_e32 v138, v214, v216
	v_pk_mul_f32 v[138:139], v[216:217], v[138:139] op_sel:[1,0]
	v_pk_mul_f32 v[136:137], v[216:217], v[136:137] op_sel:[1,0]
	v_pk_fma_f32 v[138:139], v[148:149], v[138:139], v[98:99]
	v_pk_fma_f32 v[136:137], v[150:151], v[136:137], v[96:97]
	v_pk_fma_f32 v[138:139], v[130:131], s[78:79], v[138:139] op_sel_hi:[1,0,1]
	v_pk_fma_f32 v[136:137], v[128:129], s[78:79], v[136:137] op_sel_hi:[1,0,1]
	v_lshl_add_u64 v[196:197], v[196:197], 2, s[90:91]
	global_store_dwordx4 v[196:197], v[136:139], off
	s_nop 1
	v_add_u32_e32 v138, 0x80, v206
	v_lshlrev_b32_e32 v136, 1, v138
	v_mov_b32_e32 v137, v159
	v_lshlrev_b32_e32 v233, 11, v138
	v_lshl_add_u64 v[196:197], v[136:137], 2, s[2:3]
	v_add_u32_e32 v136, v233, v158
	v_lshl_add_u64 v[136:137], v[136:137], 2, s[88:89]
	global_load_dwordx2 v[204:205], v[196:197], off
	v_add_u32_e32 v198, v233, v231
	global_load_dwordx4 v[136:139], v[136:137], off
	v_mov_b32_e32 v199, v159
	v_add_u32_e32 v207, 0x90, v206
	v_lshl_add_u64 v[198:199], v[198:199], 2, s[88:89]
	v_lshlrev_b32_e32 v234, 11, v207
	global_load_dwordx4 v[208:211], v[198:199], off
	v_add_u32_e32 v212, v234, v158
	v_mov_b32_e32 v213, v159
	v_lshl_add_u64 v[212:213], v[212:213], 2, s[88:89]
	global_load_dwordx4 v[212:215], v[212:213], off
	v_lshlrev_b32_e32 v198, 1, v207
	v_mov_b32_e32 v199, v159
	v_lshl_add_u64 v[198:199], v[198:199], 2, s[2:3]
	global_load_dwordx2 v[238:239], v[198:199], off
	v_add_u32_e32 v216, v234, v231
	v_mov_b32_e32 v217, v159
	v_lshl_add_u64 v[216:217], v[216:217], 2, s[88:89]
	global_load_dwordx4 v[216:219], v[216:217], off
	v_add_u32_e32 v240, 0x40000, v194
	v_mov_b32_e32 v241, v159
	v_lshl_add_u64 v[240:241], v[240:241], 2, s[90:91]
	s_waitcnt vmcnt(0)
;     template <bool LN, int BJ, int LO, int HI> DI void batch(const f32x4 (&acc)[2][2][4][2], unsigned row0, unsigned col0, const f32x4 (&gv)[2], const f32x4 (&bv)[2]) const {
;         f32x4 r[HI - LO]; float mean[(HI - LO) / 2], rstd[(HI - LO) / 2];
; #pragma unroll
;         for (int i = LO; i < HI; ++i) { const int ai = i >> 3, m = (i >> 1) & 3, n = i & 1; const unsigned row = row0 + ai * HALF + m * 16;
;             if (n == 0) { mean[(i - LO) >> 1] = 0.f; rstd[(i - LO) >> 1] = 1.f;
;                 if (LN) { const float2 st = *(const float2*)(stats + row * 2u); mean[(i - LO) >> 1] = st.x; rstd[(i - LO) >> 1] = st.y; } }
;             r[i - LO] = *(const f32x4*)(src + (row * (unsigned)DM + col0 + BJ * HALF + n * 16)); }
; #pragma unroll
;         for (int i = LO; i < HI; ++i) { const int ai = i >> 3, m = (i >> 1) & 3, n = i & 1; const unsigned row = row0 + ai * HALF + m * 16;
;             *(f32x4*)(Y + (row * (unsigned)DM + col0 + BJ * HALF + n * 16)) = acc[ai][BJ][m][n] + ((r[i - LO] - mean[(i - LO) >> 1]) * rstd[(i - LO) >> 1]) * gv[n] + bv[n]; }
;         __builtin_amdgcn_sched_barrier(0);
;     }
;     template <bool LN, int BJ> DI void load_gb(unsigned col0, f32x4 (&gv)[2], f32x4 (&bv)[2]) const {
; #pragma unroll
;         for (int n = 0; n < 2; ++n) {
;             if (LN) { gv[n] = *(const f32x4*)(gam + col0 + BJ * HALF + n * 16) * ALPHA; bv[n] = *(const f32x4*)(bet + col0 + BJ * HALF + n * 16) * ALPHA; }
;             else { gv[n] = (f32x4){ALPHA, ALPHA, ALPHA, ALPHA}; bv[n] = (f32x4){0.f, 0.f, 0.f, 0.f}; }
;         }
;     }
	v_sub_f32_e32 v137, v137, v204
	v_sub_f32_e32 v136, v136, v204
	v_sub_f32_e32 v139, v139, v204
	v_sub_f32_e32 v138, v138, v204
	v_pk_mul_f32 v[138:139], v[204:205], v[138:139] op_sel:[1,0]
	v_pk_mul_f32 v[136:137], v[204:205], v[136:137] op_sel:[1,0]
	v_pk_fma_f32 v[138:139], v[152:153], v[138:139], v[94:95]
	v_pk_fma_f32 v[136:137], v[154:155], v[136:137], v[92:93]
	v_pk_fma_f32 v[138:139], v[134:135], s[78:79], v[138:139] op_sel_hi:[1,0,1]
	v_pk_fma_f32 v[136:137], v[132:133], s[78:79], v[136:137] op_sel_hi:[1,0,1]
	global_store_dwordx4 v[240:241], v[136:139], off
	s_nop 1
	v_sub_f32_e32 v137, v209, v204
	v_sub_f32_e32 v136, v208, v204
	v_sub_f32_e32 v139, v211, v204
	v_sub_f32_e32 v138, v210, v204
	v_pk_mul_f32 v[138:139], v[204:205], v[138:139] op_sel:[1,0]
	v_pk_mul_f32 v[136:137], v[204:205], v[136:137] op_sel:[1,0]
	v_pk_fma_f32 v[138:139], v[148:149], v[138:139], v[90:91]
	v_pk_fma_f32 v[136:137], v[150:151], v[136:137], v[88:89]
	v_add_u32_e32 v204, 0x40010, v194
	v_mov_b32_e32 v205, v159
	v_pk_fma_f32 v[138:139], v[130:131], s[78:79], v[138:139] op_sel_hi:[1,0,1]
	v_pk_fma_f32 v[136:137], v[128:129], s[78:79], v[136:137] op_sel_hi:[1,0,1]
	v_lshl_add_u64 v[204:205], v[204:205], 2, s[90:91]
	global_store_dwordx4 v[204:205], v[136:139], off
	v_add_u32_e32 v204, 0x48000, v194
	v_mov_b32_e32 v205, v159
	v_sub_f32_e32 v137, v213, v238
	v_sub_f32_e32 v136, v212, v238
	v_sub_f32_e32 v139, v215, v238
	v_sub_f32_e32 v138, v214, v238
	v_pk_mul_f32 v[138:139], v[238:239], v[138:139] op_sel:[1,0]
	v_pk_mul_f32 v[136:137], v[238:239], v[136:137] op_sel:[1,0]
	v_pk_fma_f32 v[138:139], v[152:153], v[138:139], v[86:87]
	v_pk_fma_f32 v[136:137], v[154:155], v[136:137], v[84:85]
	v_pk_fma_f32 v[138:139], v[134:135], s[78:79], v[138:139] op_sel_hi:[1,0,1]
	v_pk_fma_f32 v[136:137], v[132:133], s[78:79], v[136:137] op_sel_hi:[1,0,1]
	v_lshl_add_u64 v[204:205], v[204:205], 2, s[90:91]
	global_store_dwordx4 v[204:205], v[136:139], off
	v_add_u32_e32 v204, 0x48010, v194
	v_mov_b32_e32 v205, v159
	v_sub_f32_e32 v137, v217, v238
	v_sub_f32_e32 v136, v216, v238
	v_sub_f32_e32 v139, v219, v238
	v_sub_f32_e32 v138, v218, v238
	v_pk_mul_f32 v[138:139], v[238:239], v[138:139] op_sel:[1,0]
	v_pk_mul_f32 v[136:137], v[238:239], v[136:137] op_sel:[1,0]
	v_pk_fma_f32 v[138:139], v[148:149], v[138:139], v[82:83]
	v_pk_fma_f32 v[136:137], v[150:151], v[136:137], v[80:81]
	v_pk_fma_f32 v[138:139], v[130:131], s[78:79], v[138:139] op_sel_hi:[1,0,1]
	v_pk_fma_f32 v[136:137], v[128:129], s[78:79], v[136:137] op_sel_hi:[1,0,1]
	v_lshl_add_u64 v[204:205], v[204:205], 2, s[90:91]
	global_store_dwordx4 v[204:205], v[136:139], off
	s_nop 1
	v_add_u32_e32 v138, 0xa0, v206
	v_lshlrev_b32_e32 v136, 1, v138
	v_mov_b32_e32 v137, v159
	v_lshlrev_b32_e32 v237, 11, v138
	v_lshl_add_u64 v[204:205], v[136:137], 2, s[2:3]
	v_add_u32_e32 v136, v237, v158
	v_lshl_add_u64 v[136:137], v[136:137], 2, s[88:89]
	global_load_dwordx2 v[240:241], v[204:205], off
	v_add_u32_e32 v208, v237, v231
	global_load_dwordx4 v[136:139], v[136:137], off
	v_mov_b32_e32 v209, v159
	v_lshl_add_u64 v[208:209], v[208:209], 2, s[88:89]
	global_load_dwordx4 v[212:215], v[208:209], off
	v_add_u32_e32 v208, 0xb0, v206
	v_lshlrev_b32_e32 v206, 1, v208
	v_mov_b32_e32 v207, v159
	v_lshlrev_b32_e32 v238, 11, v208
	v_lshl_add_u64 v[210:211], v[206:207], 2, s[2:3]
	v_add_u32_e32 v206, v238, v158
	v_lshl_add_u64 v[206:207], v[206:207], 2, s[88:89]
	global_load_dwordx2 v[242:243], v[210:211], off
	v_add_u32_e32 v216, v238, v231
	global_load_dwordx4 v[206:209], v[206:207], off
	v_mov_b32_e32 v217, v159
	v_lshl_add_u64 v[216:217], v[216:217], 2, s[88:89]
	global_load_dwordx4 v[216:219], v[216:217], off
	v_add_u32_e32 v244, 0x50000, v194
	v_mov_b32_e32 v245, v159
	v_lshl_add_u64 v[244:245], v[244:245], 2, s[90:91]
	s_waitcnt vmcnt(0)
	v_sub_f32_e32 v137, v137, v240
	v_sub_f32_e32 v136, v136, v240
	v_sub_f32_e32 v139, v139, v240
	v_sub_f32_e32 v138, v138, v240
	v_pk_mul_f32 v[138:139], v[240:241], v[138:139] op_sel:[1,0]
	v_pk_mul_f32 v[136:137], v[240:241], v[136:137] op_sel:[1,0]
	v_pk_fma_f32 v[138:139], v[152:153], v[138:139], v[78:79]
	v_pk_fma_f32 v[136:137], v[154:155], v[136:137], v[76:77]
	v_pk_fma_f32 v[138:139], v[134:135], s[78:79], v[138:139] op_sel_hi:[1,0,1]
	v_pk_fma_f32 v[136:137], v[132:133], s[78:79], v[136:137] op_sel_hi:[1,0,1]
	global_store_dwordx4 v[244:245], v[136:139], off
	s_nop 1
	v_sub_f32_e32 v137, v213, v240
	v_sub_f32_e32 v136, v212, v240
	v_sub_f32_e32 v139, v215, v240
	v_sub_f32_e32 v138, v214, v240
	v_pk_mul_f32 v[138:139], v[240:241], v[138:139] op_sel:[1,0]
	v_pk_mul_f32 v[136:137], v[240:241], v[136:137] op_sel:[1,0]
	v_pk_fma_f32 v[138:139], v[148:149], v[138:139], v[74:75]
	v_pk_fma_f32 v[136:137], v[150:151], v[136:137], v[72:73]
	v_add_u32_e32 v212, 0x50010, v194
	v_mov_b32_e32 v213, v159
	v_pk_fma_f32 v[138:139], v[130:131], s[78:79], v[138:139] op_sel_hi:[1,0,1]
	v_pk_fma_f32 v[136:137], v[128:129], s[78:79], v[136:137] op_sel_hi:[1,0,1]
	v_lshl_add_u64 v[212:213], v[212:213], 2, s[90:91]
	global_store_dwordx4 v[212:213], v[136:139], off
	s_nop 1
	v_sub_f32_e32 v137, v207, v242
	v_sub_f32_e32 v136, v206, v242
	v_sub_f32_e32 v139, v209, v242
	v_sub_f32_e32 v138, v208, v242
	v_pk_mul_f32 v[136:137], v[242:243], v[136:137] op_sel:[1,0]
	v_pk_mul_f32 v[138:139], v[242:243], v[138:139] op_sel:[1,0]
	v_pk_fma_f32 v[136:137], v[154:155], v[136:137], v[68:69]
	v_pk_fma_f32 v[138:139], v[152:153], v[138:139], v[70:71]
	v_pk_fma_f32 v[132:133], v[132:133], s[78:79], v[136:137] op_sel_hi:[1,0,1]
	v_add_u32_e32 v136, 0x58000, v194
	v_mov_b32_e32 v137, v159
	v_pk_fma_f32 v[134:135], v[134:135], s[78:79], v[138:139] op_sel_hi:[1,0,1]
	v_lshl_add_u64 v[136:137], v[136:137], 2, s[90:91]
	global_store_dwordx4 v[136:137], v[132:135], off
	s_nop 1
	v_sub_f32_e32 v133, v217, v242
	v_sub_f32_e32 v132, v216, v242
	v_sub_f32_e32 v135, v219, v242
	v_sub_f32_e32 v134, v218, v242
	v_pk_mul_f32 v[132:133], v[242:243], v[132:133] op_sel:[1,0]
	v_pk_mul_f32 v[134:135], v[242:243], v[134:135] op_sel:[1,0]
	v_pk_fma_f32 v[132:133], v[150:151], v[132:133], v[64:65]
	v_pk_fma_f32 v[134:135], v[148:149], v[134:135], v[66:67]
	v_pk_fma_f32 v[128:129], v[128:129], s[78:79], v[132:133] op_sel_hi:[1,0,1]
	v_add_u32_e32 v132, 0x58010, v194
	v_mov_b32_e32 v133, v159
	v_pk_fma_f32 v[130:131], v[130:131], s[78:79], v[134:135] op_sel_hi:[1,0,1]
	v_lshl_add_u64 v[132:133], v[132:133], 2, s[90:91]
	global_store_dwordx4 v[132:133], v[128:131], off
	global_load_dwordx4 v[128:131], v[140:141], off offset:512
	v_add_u32_e32 v136, v232, v230
	v_mov_b32_e32 v137, v159
	v_lshl_add_u64 v[136:137], v[136:137], 2, s[88:89]
	s_waitcnt vmcnt(0)
;     template <bool LN, int BJ, int LO, int HI> DI void batch(const f32x4 (&acc)[2][2][4][2], unsigned row0, unsigned col0, const f32x4 (&gv)[2], const f32x4 (&bv)[2]) const {
;         f32x4 r[HI - LO]; float mean[(HI - LO) / 2], rstd[(HI - LO) / 2];
; #pragma unroll
;         for (int i = LO; i < HI; ++i) { const int ai = i >> 3, m = (i >> 1) & 3, n = i & 1; const unsigned row = row0 + ai * HALF + m * 16;
;             if (n == 0) { mean[(i - LO) >> 1] = 0.f; rstd[(i - LO) >> 1] = 1.f;
;                 if (LN) { const float2 st = *(const float2*)(stats + row * 2u); mean[(i - LO) >> 1] = st.x; rstd[(i - LO) >> 1] = st.y; } }
;             r[i - LO] = *(const f32x4*)(src + (row * (unsigned)DM + col0 + BJ * HALF + n * 16)); }
; #pragma unroll
;         for (int i = LO; i < HI; ++i) { const int ai = i >> 3, m = (i >> 1) & 3, n = i & 1; const unsigned row = row0 + ai * HALF + m * 16;
;             *(f32x4*)(Y + (row * (unsigned)DM + col0 + BJ * HALF + n * 16)) = acc[ai][BJ][m][n] + ((r[i - LO] - mean[(i - LO) >> 1]) * rstd[(i - LO) >> 1]) * gv[n] + bv[n]; }
;         __builtin_amdgcn_sched_barrier(0);
;     }
;     template <bool LN, int BJ> DI void load_gb(unsigned col0, f32x4 (&gv)[2], f32x4 (&bv)[2]) const {
; #pragma unroll
;         for (int n = 0; n < 2; ++n) {
;             if (LN) { gv[n] = *(const f32x4*)(gam + col0 + BJ * HALF + n * 16) * ALPHA; bv[n] = *(const f32x4*)(bet + col0 + BJ * HALF + n * 16) * ALPHA; }
	v_pk_mul_f32 v[212:213], v[130:131], s[78:79] op_sel_hi:[1,0]
	v_pk_mul_f32 v[214:215], v[128:129], s[78:79] op_sel_hi:[1,0]
	global_load_dwordx4 v[132:135], v[142:143], off offset:512
	global_load_dwordx4 v[128:131], v[140:141], off offset:576
	s_waitcnt vmcnt(0)
	v_pk_mul_f32 v[206:207], v[130:131], s[78:79] op_sel_hi:[1,0]
	v_pk_mul_f32 v[208:209], v[128:129], s[78:79] op_sel_hi:[1,0]
	global_load_dwordx4 v[128:131], v[142:143], off offset:576
	global_load_dwordx2 v[220:221], v[144:145], off
	global_load_dwordx4 v[240:243], v[136:137], off
	v_add_u32_e32 v136, v232, v229
	v_mov_b32_e32 v137, v159
	v_lshl_add_u64 v[136:137], v[136:137], 2, s[88:89]
	global_load_dwordx4 v[244:247], v[136:137], off
	global_load_dwordx2 v[218:219], v[146:147], off
	v_add_u32_e32 v136, v195, v230
	v_mov_b32_e32 v137, v159
	v_lshl_add_u64 v[136:137], v[136:137], 2, s[88:89]
	global_load_dwordx4 v[248:251], v[136:137], off
	v_add_u32_e32 v136, v195, v229
	v_mov_b32_e32 v137, v159
	v_lshl_add_u64 v[136:137], v[136:137], 2, s[88:89]
	global_load_dwordx4 v[152:155], v[136:137], off
	global_load_dwordx2 v[216:217], v[200:201], off
	v_add_u32_e32 v136, v236, v230
	v_mov_b32_e32 v137, v159
	v_lshl_add_u64 v[136:137], v[136:137], 2, s[88:89]
	global_load_dwordx4 v[148:151], v[136:137], off
	v_add_u32_e32 v136, v236, v229
	v_mov_b32_e32 v137, v159
	v_lshl_add_u64 v[136:137], v[136:137], 2, s[88:89]
	global_load_dwordx4 v[144:147], v[136:137], off
	global_load_dwordx2 v[200:201], v[202:203], off
	v_add_u32_e32 v136, v235, v230
	v_mov_b32_e32 v137, v159
	v_lshl_add_u64 v[136:137], v[136:137], 2, s[88:89]
	global_load_dwordx4 v[140:143], v[136:137], off
	v_add_u32_e32 v136, v235, v229
	v_mov_b32_e32 v137, v159
	v_lshl_add_u64 v[136:137], v[136:137], 2, s[88:89]
	global_load_dwordx4 v[136:139], v[136:137], off
	v_add_u32_e32 v202, 0x80, v194
	v_mov_b32_e32 v203, v159
	v_lshl_add_u64 v[202:203], v[202:203], 2, s[90:91]
	s_waitcnt vmcnt(0)
	v_sub_f32_e32 v241, v241, v220
	v_sub_f32_e32 v240, v240, v220
	v_sub_f32_e32 v243, v243, v220
	v_sub_f32_e32 v242, v242, v220
	v_pk_mul_f32 v[242:243], v[220:221], v[242:243] op_sel:[1,0]
	v_pk_mul_f32 v[240:241], v[220:221], v[240:241] op_sel:[1,0]
	v_pk_fma_f32 v[242:243], v[212:213], v[242:243], v[62:63]
	v_pk_fma_f32 v[240:241], v[214:215], v[240:241], v[60:61]
	v_pk_fma_f32 v[242:243], v[134:135], s[78:79], v[242:243] op_sel_hi:[1,0,1]
	v_pk_fma_f32 v[240:241], v[132:133], s[78:79], v[240:241] op_sel_hi:[1,0,1]
	global_store_dwordx4 v[202:203], v[240:243], off
	v_sub_f32_e32 v203, v245, v220
	v_sub_f32_e32 v202, v244, v220
	v_sub_f32_e32 v241, v247, v220
	v_sub_f32_e32 v240, v246, v220
	v_pk_mul_f32 v[202:203], v[220:221], v[202:203] op_sel:[1,0]
	v_pk_mul_f32 v[240:241], v[220:221], v[240:241] op_sel:[1,0]
	v_pk_fma_f32 v[202:203], v[208:209], v[202:203], v[56:57]
	v_pk_fma_f32 v[220:221], v[206:207], v[240:241], v[58:59]
	v_pk_fma_f32 v[240:241], v[128:129], s[78:79], v[202:203] op_sel_hi:[1,0,1]
	v_add_u32_e32 v202, 0x90, v194
	v_mov_b32_e32 v203, v159
	v_pk_fma_f32 v[242:243], v[130:131], s[78:79], v[220:221] op_sel_hi:[1,0,1]
	v_lshl_add_u64 v[202:203], v[202:203], 2, s[90:91]
	global_store_dwordx4 v[202:203], v[240:243], off
	v_sub_f32_e32 v203, v249, v218
	v_sub_f32_e32 v202, v248, v218
	v_sub_f32_e32 v221, v251, v218
	v_sub_f32_e32 v220, v250, v218
	v_pk_mul_f32 v[202:203], v[218:219], v[202:203] op_sel:[1,0]
	v_pk_mul_f32 v[220:221], v[218:219], v[220:221] op_sel:[1,0]
	v_pk_fma_f32 v[202:203], v[214:215], v[202:203], v[52:53]
	v_pk_fma_f32 v[220:221], v[212:213], v[220:221], v[54:55]
	v_pk_fma_f32 v[240:241], v[132:133], s[78:79], v[202:203] op_sel_hi:[1,0,1]
	v_add_u32_e32 v202, 0x8080, v194
	v_mov_b32_e32 v203, v159
	v_sub_f32_e32 v153, v153, v218
	v_sub_f32_e32 v152, v152, v218
	v_sub_f32_e32 v155, v155, v218
	v_sub_f32_e32 v154, v154, v218
	v_pk_fma_f32 v[242:243], v[134:135], s[78:79], v[220:221] op_sel_hi:[1,0,1]
	v_lshl_add_u64 v[202:203], v[202:203], 2, s[90:91]
	v_pk_mul_f32 v[154:155], v[218:219], v[154:155] op_sel:[1,0]
	v_pk_mul_f32 v[152:153], v[218:219], v[152:153] op_sel:[1,0]
	global_store_dwordx4 v[202:203], v[240:243], off
	v_pk_fma_f32 v[152:153], v[208:209], v[152:153], v[48:49]
	v_pk_fma_f32 v[154:155], v[206:207], v[154:155], v[50:51]
	v_add_u32_e32 v202, 0x8090, v194
	v_mov_b32_e32 v203, v159
	v_sub_f32_e32 v149, v149, v216
	v_sub_f32_e32 v148, v148, v216
	v_sub_f32_e32 v151, v151, v216
	v_sub_f32_e32 v150, v150, v216
	v_pk_fma_f32 v[154:155], v[130:131], s[78:79], v[154:155] op_sel_hi:[1,0,1]
	v_pk_fma_f32 v[152:153], v[128:129], s[78:79], v[152:153] op_sel_hi:[1,0,1]
	v_lshl_add_u64 v[202:203], v[202:203], 2, s[90:91]
	v_pk_mul_f32 v[150:151], v[216:217], v[150:151] op_sel:[1,0]
	v_pk_mul_f32 v[148:149], v[216:217], v[148:149] op_sel:[1,0]
	global_store_dwordx4 v[202:203], v[152:155], off
	v_pk_fma_f32 v[148:149], v[214:215], v[148:149], v[44:45]
	v_pk_fma_f32 v[150:151], v[212:213], v[150:151], v[46:47]
	v_add_u32_e32 v152, 0x10080, v194
	v_mov_b32_e32 v153, v159
	v_sub_f32_e32 v145, v145, v216
	v_sub_f32_e32 v144, v144, v216
	v_sub_f32_e32 v147, v147, v216
	v_sub_f32_e32 v146, v146, v216
	v_pk_fma_f32 v[150:151], v[134:135], s[78:79], v[150:151] op_sel_hi:[1,0,1]
	v_pk_fma_f32 v[148:149], v[132:133], s[78:79], v[148:149] op_sel_hi:[1,0,1]
	v_lshl_add_u64 v[152:153], v[152:153], 2, s[90:91]
	v_pk_mul_f32 v[146:147], v[216:217], v[146:147] op_sel:[1,0]
	v_pk_mul_f32 v[144:145], v[216:217], v[144:145] op_sel:[1,0]
	global_store_dwordx4 v[152:153], v[148:151], off
	v_pk_fma_f32 v[144:145], v[208:209], v[144:145], v[40:41]
	v_pk_fma_f32 v[146:147], v[206:207], v[146:147], v[42:43]
;     template <bool LN, int BJ, int LO, int HI> DI void batch(const f32x4 (&acc)[2][2][4][2], unsigned row0, unsigned col0, const f32x4 (&gv)[2], const f32x4 (&bv)[2]) const {
;         f32x4 r[HI - LO]; float mean[(HI - LO) / 2], rstd[(HI - LO) / 2];
; #pragma unroll
;         for (int i = LO; i < HI; ++i) { const int ai = i >> 3, m = (i >> 1) & 3, n = i & 1; const unsigned row = row0 + ai * HALF + m * 16;
;             if (n == 0) { mean[(i - LO) >> 1] = 0.f; rstd[(i - LO) >> 1] = 1.f;
;                 if (LN) { const float2 st = *(const float2*)(stats + row * 2u); mean[(i - LO) >> 1] = st.x; rstd[(i - LO) >> 1] = st.y; } }
;             r[i - LO] = *(const f32x4*)(src + (row * (unsigned)DM + col0 + BJ * HALF + n * 16)); }
; #pragma unroll
;         for (int i = LO; i < HI; ++i) { const int ai = i >> 3, m = (i >> 1) & 3, n = i & 1; const unsigned row = row0 + ai * HALF + m * 16;
;             *(f32x4*)(Y + (row * (unsigned)DM + col0 + BJ * HALF + n * 16)) = acc[ai][BJ][m][n] + ((r[i - LO] - mean[(i - LO) >> 1]) * rstd[(i - LO) >> 1]) * gv[n] + bv[n]; }
	v_add_u32_e32 v148, 0x10090, v194
	v_mov_b32_e32 v149, v159
	v_sub_f32_e32 v141, v141, v200
	v_sub_f32_e32 v140, v140, v200
	v_sub_f32_e32 v143, v143, v200
	v_sub_f32_e32 v142, v142, v200
	v_pk_fma_f32 v[146:147], v[130:131], s[78:79], v[146:147] op_sel_hi:[1,0,1]
	v_pk_fma_f32 v[144:145], v[128:129], s[78:79], v[144:145] op_sel_hi:[1,0,1]
	v_lshl_add_u64 v[148:149], v[148:149], 2, s[90:91]
	v_pk_mul_f32 v[142:143], v[200:201], v[142:143] op_sel:[1,0]
	v_pk_mul_f32 v[140:141], v[200:201], v[140:141] op_sel:[1,0]
	global_store_dwordx4 v[148:149], v[144:147], off
	v_pk_fma_f32 v[140:141], v[214:215], v[140:141], v[36:37]
	v_pk_fma_f32 v[142:143], v[212:213], v[142:143], v[38:39]
	v_add_u32_e32 v144, 0x18080, v194
	v_mov_b32_e32 v145, v159
	v_sub_f32_e32 v137, v137, v200
	v_sub_f32_e32 v136, v136, v200
	v_sub_f32_e32 v139, v139, v200
	v_sub_f32_e32 v138, v138, v200
	v_pk_fma_f32 v[142:143], v[134:135], s[78:79], v[142:143] op_sel_hi:[1,0,1]
	v_pk_fma_f32 v[140:141], v[132:133], s[78:79], v[140:141] op_sel_hi:[1,0,1]
	v_lshl_add_u64 v[144:145], v[144:145], 2, s[90:91]
	v_pk_mul_f32 v[138:139], v[200:201], v[138:139] op_sel:[1,0]
	v_pk_mul_f32 v[136:137], v[200:201], v[136:137] op_sel:[1,0]
	global_store_dwordx4 v[144:145], v[140:143], off
	v_pk_fma_f32 v[136:137], v[208:209], v[136:137], v[32:33]
	v_pk_fma_f32 v[138:139], v[206:207], v[138:139], v[34:35]
	v_add_u32_e32 v140, 0x18090, v194
	v_mov_b32_e32 v141, v159
	v_pk_fma_f32 v[138:139], v[130:131], s[78:79], v[138:139] op_sel_hi:[1,0,1]
	v_pk_fma_f32 v[136:137], v[128:129], s[78:79], v[136:137] op_sel_hi:[1,0,1]
	v_lshl_add_u64 v[140:141], v[140:141], 2, s[90:91]
	global_store_dwordx4 v[140:141], v[136:139], off
	s_nop 1
	v_add_u32_e32 v136, v233, v230
	v_mov_b32_e32 v137, v159
	v_lshl_add_u64 v[136:137], v[136:137], 2, s[88:89]
	global_load_dwordx2 v[220:221], v[196:197], off
	global_load_dwordx4 v[216:219], v[136:137], off
	v_add_u32_e32 v136, v233, v229
	v_mov_b32_e32 v137, v159
	v_lshl_add_u64 v[136:137], v[136:137], 2, s[88:89]
	global_load_dwordx4 v[240:243], v[136:137], off
	global_load_dwordx2 v[200:201], v[198:199], off
	v_add_u32_e32 v136, v234, v230
	v_mov_b32_e32 v137, v159
	v_lshl_add_u64 v[136:137], v[136:137], 2, s[88:89]
	global_load_dwordx4 v[244:247], v[136:137], off
	v_add_u32_e32 v136, v234, v229
	v_mov_b32_e32 v137, v159
	v_lshl_add_u64 v[136:137], v[136:137], 2, s[88:89]
	global_load_dwordx4 v[152:155], v[136:137], off
	global_load_dwordx2 v[198:199], v[204:205], off
	v_add_u32_e32 v136, v237, v230
	v_mov_b32_e32 v137, v159
	v_lshl_add_u64 v[136:137], v[136:137], 2, s[88:89]
	global_load_dwordx4 v[148:151], v[136:137], off
	v_add_u32_e32 v136, v237, v229
	v_mov_b32_e32 v137, v159
	v_lshl_add_u64 v[136:137], v[136:137], 2, s[88:89]
	global_load_dwordx4 v[144:147], v[136:137], off
	global_load_dwordx2 v[196:197], v[210:211], off
	v_add_u32_e32 v136, v238, v230
	v_mov_b32_e32 v137, v159
	v_lshl_add_u64 v[136:137], v[136:137], 2, s[88:89]
	global_load_dwordx4 v[140:143], v[136:137], off
	v_add_u32_e32 v136, v238, v229
	v_mov_b32_e32 v137, v159
	v_lshl_add_u64 v[136:137], v[136:137], 2, s[88:89]
	global_load_dwordx4 v[136:139], v[136:137], off
	v_add_u32_e32 v210, 0x40080, v194
	v_mov_b32_e32 v211, v159
	v_lshl_add_u64 v[210:211], v[210:211], 2, s[90:91]
	s_waitcnt vmcnt(0)
;     template <bool LN, int BJ, int LO, int HI> DI void batch(const f32x4 (&acc)[2][2][4][2], unsigned row0, unsigned col0, const f32x4 (&gv)[2], const f32x4 (&bv)[2]) const {
;         f32x4 r[HI - LO]; float mean[(HI - LO) / 2], rstd[(HI - LO) / 2];
; #pragma unroll
;         for (int i = LO; i < HI; ++i) { const int ai = i >> 3, m = (i >> 1) & 3, n = i & 1; const unsigned row = row0 + ai * HALF + m * 16;
;             if (n == 0) { mean[(i - LO) >> 1] = 0.f; rstd[(i - LO) >> 1] = 1.f;
;                 if (LN) { const float2 st = *(const float2*)(stats + row * 2u); mean[(i - LO) >> 1] = st.x; rstd[(i - LO) >> 1] = st.y; } }
;             r[i - LO] = *(const f32x4*)(src + (row * (unsigned)DM + col0 + BJ * HALF + n * 16)); }
; #pragma unroll
;         for (int i = LO; i < HI; ++i) { const int ai = i >> 3, m = (i >> 1) & 3, n = i & 1; const unsigned row = row0 + ai * HALF + m * 16;
;             *(f32x4*)(Y + (row * (unsigned)DM + col0 + BJ * HALF + n * 16)) = acc[ai][BJ][m][n] + ((r[i - LO] - mean[(i - LO) >> 1]) * rstd[(i - LO) >> 1]) * gv[n] + bv[n]; }
	v_sub_f32_e32 v203, v217, v220
	v_sub_f32_e32 v202, v216, v220
	v_sub_f32_e32 v205, v219, v220
	v_sub_f32_e32 v204, v218, v220
	v_pk_mul_f32 v[204:205], v[220:221], v[204:205] op_sel:[1,0]
	v_pk_mul_f32 v[202:203], v[220:221], v[202:203] op_sel:[1,0]
	v_pk_fma_f32 v[204:205], v[212:213], v[204:205], v[30:31]
	v_pk_fma_f32 v[202:203], v[214:215], v[202:203], v[28:29]
	v_pk_fma_f32 v[204:205], v[134:135], s[78:79], v[204:205] op_sel_hi:[1,0,1]
	v_pk_fma_f32 v[202:203], v[132:133], s[78:79], v[202:203] op_sel_hi:[1,0,1]
	global_store_dwordx4 v[210:211], v[202:205], off
	v_add_u32_e32 v210, 0x40090, v194
	v_mov_b32_e32 v211, v159
	v_sub_f32_e32 v203, v241, v220
	v_sub_f32_e32 v202, v240, v220
	v_sub_f32_e32 v205, v243, v220
	v_sub_f32_e32 v204, v242, v220
	v_pk_mul_f32 v[204:205], v[220:221], v[204:205] op_sel:[1,0]
	v_pk_mul_f32 v[202:203], v[220:221], v[202:203] op_sel:[1,0]
	v_pk_fma_f32 v[204:205], v[206:207], v[204:205], v[26:27]
	v_pk_fma_f32 v[202:203], v[208:209], v[202:203], v[24:25]
	v_pk_fma_f32 v[204:205], v[130:131], s[78:79], v[204:205] op_sel_hi:[1,0,1]
	v_pk_fma_f32 v[202:203], v[128:129], s[78:79], v[202:203] op_sel_hi:[1,0,1]
	v_lshl_add_u64 v[210:211], v[210:211], 2, s[90:91]
	global_store_dwordx4 v[210:211], v[202:205], off
	v_sub_f32_e32 v149, v149, v198
	v_sub_f32_e32 v148, v148, v198
	v_sub_f32_e32 v203, v245, v200
	v_sub_f32_e32 v202, v244, v200
	v_sub_f32_e32 v141, v141, v196
	v_sub_f32_e32 v140, v140, v196
	v_sub_f32_e32 v205, v247, v200
	v_sub_f32_e32 v204, v246, v200
	v_pk_mul_f32 v[202:203], v[200:201], v[202:203] op_sel:[1,0]
	v_sub_f32_e32 v151, v151, v198
	v_sub_f32_e32 v150, v150, v198
	v_pk_mul_f32 v[148:149], v[198:199], v[148:149] op_sel:[1,0]
	v_sub_f32_e32 v143, v143, v196
	v_sub_f32_e32 v142, v142, v196
	v_pk_mul_f32 v[140:141], v[196:197], v[140:141] op_sel:[1,0]
	v_pk_mul_f32 v[204:205], v[200:201], v[204:205] op_sel:[1,0]
	v_pk_fma_f32 v[202:203], v[214:215], v[202:203], v[20:21]
	v_sub_f32_e32 v153, v153, v200
	v_sub_f32_e32 v152, v152, v200
	v_sub_f32_e32 v155, v155, v200
	v_sub_f32_e32 v154, v154, v200
	v_pk_mul_f32 v[150:151], v[198:199], v[150:151] op_sel:[1,0]
	v_pk_fma_f32 v[148:149], v[214:215], v[148:149], v[12:13]
	v_pk_mul_f32 v[142:143], v[196:197], v[142:143] op_sel:[1,0]
	v_pk_fma_f32 v[140:141], v[214:215], v[140:141], v[4:5]
	v_pk_fma_f32 v[204:205], v[212:213], v[204:205], v[22:23]
	v_pk_fma_f32 v[202:203], v[132:133], s[78:79], v[202:203] op_sel_hi:[1,0,1]
	v_pk_mul_f32 v[154:155], v[200:201], v[154:155] op_sel:[1,0]
	v_pk_mul_f32 v[152:153], v[200:201], v[152:153] op_sel:[1,0]
	v_pk_fma_f32 v[150:151], v[212:213], v[150:151], v[14:15]
	v_pk_fma_f32 v[148:149], v[132:133], s[78:79], v[148:149] op_sel_hi:[1,0,1]
	v_pk_fma_f32 v[142:143], v[212:213], v[142:143], v[6:7]
	v_pk_fma_f32 v[132:133], v[132:133], s[78:79], v[140:141] op_sel_hi:[1,0,1]
	v_add_u32_e32 v140, 0x58080, v194
	v_mov_b32_e32 v141, v159
	v_pk_fma_f32 v[204:205], v[134:135], s[78:79], v[204:205] op_sel_hi:[1,0,1]
	v_pk_fma_f32 v[152:153], v[208:209], v[152:153], v[16:17]
	v_pk_fma_f32 v[154:155], v[206:207], v[154:155], v[18:19]
	v_add_u32_e32 v200, 0x48090, v194
	v_mov_b32_e32 v201, v159
	v_pk_fma_f32 v[150:151], v[134:135], s[78:79], v[150:151] op_sel_hi:[1,0,1]
	v_pk_fma_f32 v[134:135], v[134:135], s[78:79], v[142:143] op_sel_hi:[1,0,1]
	v_lshl_add_u64 v[140:141], v[140:141], 2, s[90:91]
	v_pk_fma_f32 v[154:155], v[130:131], s[78:79], v[154:155] op_sel_hi:[1,0,1]
	v_pk_fma_f32 v[152:153], v[128:129], s[78:79], v[152:153] op_sel_hi:[1,0,1]
	v_lshl_add_u64 v[200:201], v[200:201], 2, s[90:91]
	v_sub_f32_e32 v145, v145, v198
	v_sub_f32_e32 v144, v144, v198
	global_store_dwordx4 v[140:141], v[132:135], off
	global_store_dwordx4 v[200:201], v[152:155], off
	v_sub_f32_e32 v147, v147, v198
	v_sub_f32_e32 v133, v137, v196
	v_sub_f32_e32 v132, v136, v196
	v_add_u32_e32 v152, 0x50080, v194
	v_mov_b32_e32 v153, v159
	v_sub_f32_e32 v146, v146, v198
	v_pk_mul_f32 v[144:145], v[198:199], v[144:145] op_sel:[1,0]
	v_sub_f32_e32 v135, v139, v196
	v_sub_f32_e32 v134, v138, v196
	v_pk_mul_f32 v[132:133], v[196:197], v[132:133] op_sel:[1,0]
	v_lshl_add_u64 v[152:153], v[152:153], 2, s[90:91]
	v_pk_mul_f32 v[146:147], v[198:199], v[146:147] op_sel:[1,0]
	v_pk_fma_f32 v[144:145], v[208:209], v[144:145], v[8:9]
	v_pk_mul_f32 v[134:135], v[196:197], v[134:135] op_sel:[1,0]
	v_pk_fma_f32 v[132:133], v[208:209], v[132:133], v[0:1]
	v_add_u32_e32 v210, 0x48080, v194
	v_mov_b32_e32 v211, v159
	global_store_dwordx4 v[152:153], v[148:151], off
	v_pk_fma_f32 v[146:147], v[206:207], v[146:147], v[10:11]
	v_pk_fma_f32 v[144:145], v[128:129], s[78:79], v[144:145] op_sel_hi:[1,0,1]
	v_add_u32_e32 v148, 0x50090, v194
	v_mov_b32_e32 v149, v159
	v_pk_fma_f32 v[134:135], v[206:207], v[134:135], v[2:3]
	v_pk_fma_f32 v[128:129], v[128:129], s[78:79], v[132:133] op_sel_hi:[1,0,1]
	v_add_u32_e32 v132, 0x58090, v194
	v_mov_b32_e32 v133, v159
	v_lshl_add_u64 v[210:211], v[210:211], 2, s[90:91]
	v_pk_fma_f32 v[146:147], v[130:131], s[78:79], v[146:147] op_sel_hi:[1,0,1]
	v_lshl_add_u64 v[148:149], v[148:149], 2, s[90:91]
	v_pk_fma_f32 v[130:131], v[130:131], s[78:79], v[134:135] op_sel_hi:[1,0,1]
	v_lshl_add_u64 v[132:133], v[132:133], 2, s[90:91]
	global_store_dwordx4 v[210:211], v[202:205], off
	global_store_dwordx4 v[148:149], v[144:147], off
	global_store_dwordx4 v[132:133], v[128:131], off
	s_mov_b64 s[24:25], 0
	s_branch .LBB0_324
